# weight-conversion stores (prologue and GU-phase tails) write-through (sc1): converted weights are not re-read soon, keeps them out of the L2s
# baseline (speedup 1.0000x reference)
; #define LAS __attribute__((address_space(3)))
; #define LDS_WAIT() asm volatile("s_waitcnt lgkmcnt(0)" ::: "memory")
; __device__ __forceinline__ void transpose_item(const float* __restrict__ W, int ldw, int src_col0, bf16_t* WT, int K, int dst_row0, int k0, LAS float* scr, int lane) {
;     float tmp[32];
; #pragma unroll
;     for (int i = 0; i < 32; ++i) tmp[i] = __builtin_nontemporal_load(W + (size_t)(k0 + 2 * i + (lane >> 5)) * ldw + src_col0 + (lane & 31));
; #pragma unroll
;     for (int i = 0; i < 32; ++i) scr[(2 * i + (lane >> 5)) * 33 + (lane & 31)] = tmp[i];
;     LDS_WAIT();
; __device__ __forceinline__ void convert_item(ArgsP a, const Ctx& c, int it, LAS float* scr) {
;     ...
;         { const int kb = r / 64, nb = r % 64; transpose_item(a->in[16] + (size_t)l * PLE * DM, DM, 32 * nb, (bf16_t*)(wl + WL_PE), PLE, 32 * nb, 64 * kb, scr, c.lane); }
.LBB0_481:
	s_add_i32 s3, s10, 0xad00
	s_mul_hi_i32 s2, s3, 0x17ad2209
	s_lshr_b32 s4, s2, 31
	s_ashr_i32 s2, s2, 12
	s_add_i32 s2, s2, s4
	s_mul_i32 s17, s2, 0xffff5300
	s_add_i32 s17, s17, s3
	s_ashr_i32 s3, s2, 31
	s_mul_i32 s5, s2, 0xae00000
	v_readlane_b32 s6, v255, 2
	s_mul_hi_i32 s4, s2, 0xae00000
	s_add_u32 s15, s6, s5
	v_readlane_b32 s5, v255, 4
	s_addc_u32 s16, s5, s4
	s_cmpk_gt_i32 s17, 0x57ff
	s_mov_b64 s[4:5], -1
	s_cbranch_scc0 .LBB0_514
	s_cmpk_gt_u32 s17, 0x83ff
	s_cbranch_scc0 .LBB0_527
	s_cmpk_gt_u32 s17, 0x93ff
	s_cbranch_scc0 .LBB0_505
	s_cmpk_gt_u32 s17, 0x9bff
	s_cbranch_scc0 .LBB0_494
	s_cmpk_gt_u32 s17, 0xa3ff
	s_cbranch_scc0 .LBB0_491
	s_lshl_b32 s4, s10, 5
	s_and_b32 s6, s4, 0x7e0
	s_cmpk_gt_u32 s17, 0xabff
	s_mov_b64 s[4:5], -1
	v_or_b32_e32 v18, s6, v10
	v_or_b32_e32 v17, s6, v12
	v_or_b32_e32 v16, s6, v13
	v_or_b32_e32 v15, s6, v14
	s_cbranch_scc0 .LBB0_488
	s_and_b32 s4, s17, 0x7fffffc0
	s_add_i32 s60, s4, 0xffff5400
	s_load_dwordx2 s[4:5], s[0:1], 0x80
	s_lshl_b64 s[8:9], s[2:3], 21
	v_or_b32_e32 v6, s60, v3
	v_lshlrev_b32_e32 v0, 2, v2
	v_mov_b32_e32 v7, v1
	s_waitcnt lgkmcnt(0)
	s_add_u32 s4, s4, s8
	s_addc_u32 s5, s5, s9
	s_lshl_b32 s7, s6, 2
	s_add_u32 s4, s4, s7
	s_addc_u32 s5, s5, 0
	v_lshl_add_u64 v[8:9], s[4:5], 0, v[0:1]
	v_lshlrev_b64 v[20:21], 13, v[6:7]
	v_lshl_add_u64 v[20:21], v[8:9], 0, v[20:21]
	v_or_b32_e32 v0, 2, v6
	global_load_dword v19, v[20:21], off nt
	v_lshlrev_b64 v[20:21], 13, v[0:1]
	v_lshl_add_u64 v[20:21], v[8:9], 0, v[20:21]
	v_or_b32_e32 v0, 4, v6
	global_load_dword v22, v[20:21], off nt
	v_lshlrev_b64 v[20:21], 13, v[0:1]
	v_lshl_add_u64 v[20:21], v[8:9], 0, v[20:21]
	v_or_b32_e32 v0, 6, v6
	global_load_dword v23, v[20:21], off nt
	v_lshlrev_b64 v[20:21], 13, v[0:1]
	v_lshl_add_u64 v[20:21], v[8:9], 0, v[20:21]
	v_or_b32_e32 v0, 8, v6
	global_load_dword v24, v[20:21], off nt
	v_lshlrev_b64 v[20:21], 13, v[0:1]
	v_lshl_add_u64 v[20:21], v[8:9], 0, v[20:21]
	v_or_b32_e32 v0, 10, v6
	global_load_dword v25, v[20:21], off nt
	v_lshlrev_b64 v[20:21], 13, v[0:1]
	v_lshl_add_u64 v[20:21], v[8:9], 0, v[20:21]
	v_or_b32_e32 v0, 12, v6
	global_load_dword v26, v[20:21], off nt
	v_lshlrev_b64 v[20:21], 13, v[0:1]
	v_lshl_add_u64 v[20:21], v[8:9], 0, v[20:21]
	v_or_b32_e32 v0, 14, v6
	global_load_dword v27, v[20:21], off nt
	v_lshlrev_b64 v[20:21], 13, v[0:1]
	v_lshl_add_u64 v[20:21], v[8:9], 0, v[20:21]
	v_or_b32_e32 v0, 16, v6
	global_load_dword v28, v[20:21], off nt
	v_lshlrev_b64 v[20:21], 13, v[0:1]
	v_lshl_add_u64 v[20:21], v[8:9], 0, v[20:21]
	v_or_b32_e32 v0, 18, v6
	global_load_dword v29, v[20:21], off nt
	v_lshlrev_b64 v[20:21], 13, v[0:1]
	v_lshl_add_u64 v[20:21], v[8:9], 0, v[20:21]
	v_or_b32_e32 v0, 20, v6
	global_load_dword v30, v[20:21], off nt
	v_lshlrev_b64 v[20:21], 13, v[0:1]
	v_lshl_add_u64 v[20:21], v[8:9], 0, v[20:21]
	v_or_b32_e32 v0, 22, v6
	global_load_dword v31, v[20:21], off nt
	v_lshlrev_b64 v[20:21], 13, v[0:1]
	v_lshl_add_u64 v[20:21], v[8:9], 0, v[20:21]
	v_or_b32_e32 v0, 24, v6
	global_load_dword v32, v[20:21], off nt
	v_lshlrev_b64 v[20:21], 13, v[0:1]
	v_lshl_add_u64 v[20:21], v[8:9], 0, v[20:21]
	v_or_b32_e32 v0, 26, v6
	global_load_dword v33, v[20:21], off nt
	v_lshlrev_b64 v[20:21], 13, v[0:1]
	v_lshl_add_u64 v[20:21], v[8:9], 0, v[20:21]
	v_or_b32_e32 v0, 28, v6
	global_load_dword v34, v[20:21], off nt
	v_lshlrev_b64 v[20:21], 13, v[0:1]
	v_lshl_add_u64 v[20:21], v[8:9], 0, v[20:21]
	v_or_b32_e32 v0, 30, v6
	global_load_dword v35, v[20:21], off nt
	v_lshlrev_b64 v[20:21], 13, v[0:1]
	v_lshl_add_u64 v[20:21], v[8:9], 0, v[20:21]
	v_or_b32_e32 v0, 32, v6
	global_load_dword v36, v[20:21], off nt
	v_lshlrev_b64 v[20:21], 13, v[0:1]
	v_lshl_add_u64 v[20:21], v[8:9], 0, v[20:21]
	v_or_b32_e32 v0, 34, v6
	global_load_dword v37, v[20:21], off nt
	v_lshlrev_b64 v[20:21], 13, v[0:1]
	v_lshl_add_u64 v[20:21], v[8:9], 0, v[20:21]
	v_or_b32_e32 v0, 36, v6
	global_load_dword v38, v[20:21], off nt
	v_lshlrev_b64 v[20:21], 13, v[0:1]
	v_lshl_add_u64 v[20:21], v[8:9], 0, v[20:21]
	v_or_b32_e32 v0, 38, v6
	global_load_dword v39, v[20:21], off nt
	v_lshlrev_b64 v[20:21], 13, v[0:1]
	v_lshl_add_u64 v[20:21], v[8:9], 0, v[20:21]
	v_or_b32_e32 v0, 40, v6
	global_load_dword v40, v[20:21], off nt
	v_lshlrev_b64 v[20:21], 13, v[0:1]
	v_lshl_add_u64 v[20:21], v[8:9], 0, v[20:21]
	v_or_b32_e32 v0, 42, v6
	global_load_dword v41, v[20:21], off nt
	v_lshlrev_b64 v[20:21], 13, v[0:1]
	v_lshl_add_u64 v[20:21], v[8:9], 0, v[20:21]
	v_or_b32_e32 v0, 44, v6
	global_load_dword v42, v[20:21], off nt
	v_lshlrev_b64 v[20:21], 13, v[0:1]
	v_lshl_add_u64 v[20:21], v[8:9], 0, v[20:21]
	v_or_b32_e32 v0, 46, v6
	global_load_dword v43, v[20:21], off nt
	v_lshlrev_b64 v[20:21], 13, v[0:1]
	v_lshl_add_u64 v[20:21], v[8:9], 0, v[20:21]
	v_or_b32_e32 v0, 48, v6
	global_load_dword v44, v[20:21], off nt
	v_lshlrev_b64 v[20:21], 13, v[0:1]
	v_lshl_add_u64 v[20:21], v[8:9], 0, v[20:21]
	v_or_b32_e32 v0, 50, v6
	global_load_dword v45, v[20:21], off nt
	v_lshlrev_b64 v[20:21], 13, v[0:1]
	v_lshl_add_u64 v[20:21], v[8:9], 0, v[20:21]
	v_or_b32_e32 v0, 52, v6
	global_load_dword v46, v[20:21], off nt
	v_lshlrev_b64 v[20:21], 13, v[0:1]
	v_lshl_add_u64 v[20:21], v[8:9], 0, v[20:21]
	v_or_b32_e32 v0, 54, v6
	global_load_dword v47, v[20:21], off nt
	v_lshlrev_b64 v[20:21], 13, v[0:1]
	v_lshl_add_u64 v[20:21], v[8:9], 0, v[20:21]
	v_or_b32_e32 v0, 56, v6
	global_load_dword v48, v[20:21], off nt
	v_lshlrev_b64 v[20:21], 13, v[0:1]
	v_lshl_add_u64 v[20:21], v[8:9], 0, v[20:21]
	v_or_b32_e32 v0, 58, v6
	global_load_dword v49, v[20:21], off nt
	v_lshlrev_b64 v[20:21], 13, v[0:1]
	v_lshl_add_u64 v[20:21], v[8:9], 0, v[20:21]
	v_or_b32_e32 v0, 60, v6
	global_load_dword v50, v[20:21], off nt
	v_lshlrev_b64 v[20:21], 13, v[0:1]
	v_or_b32_e32 v0, 62, v6
	v_lshlrev_b64 v[6:7], 13, v[0:1]
	v_lshl_add_u64 v[20:21], v[8:9], 0, v[20:21]
	v_lshl_add_u64 v[6:7], v[8:9], 0, v[6:7]
	global_load_dword v20, v[20:21], off nt
	s_lshl_b64 s[4:5], s[60:61], 1
	global_load_dword v0, v[6:7], off nt
	v_add_u32_e32 v6, 0x400, v5
	s_waitcnt vmcnt(0)
; #define LAS __attribute__((address_space(3)))
; __device__ __forceinline__ unsigned pk_bf16(float lo, float hi) { f32x2 v = {lo, hi}; bf16x2_t b = __builtin_convertvector(v, bf16x2_t); return __builtin_bit_cast(unsigned, b); }
; #define LDS_WAIT() asm volatile("s_waitcnt lgkmcnt(0)" ::: "memory")
; __device__ __forceinline__ void transpose_item(const float* __restrict__ W, int ldw, int src_col0, bf16_t* WT, int K, int dst_row0, int k0, LAS float* scr, int lane) {
;     ...
;     LDS_WAIT();
;     const int c = lane & 7;
; #pragma unroll
;     for (int j = 0; j < 4; ++j) { const int n = (lane >> 3) + 8 * j; const LAS float* s = scr + (8 * c) * 33 + n;
;         u32x4 o; o.x = pk_bf16(s[0 * 33], s[1 * 33]); o.y = pk_bf16(s[2 * 33], s[3 * 33]); o.z = pk_bf16(s[4 * 33], s[5 * 33]); o.w = pk_bf16(s[6 * 33], s[7 * 33]);
;         *(u32x4*)(WT + (size_t)(dst_row0 + n) * K + k0 + 8 * c) = o; }
;     LDS_WAIT();
; }
; __device__ __forceinline__ void convert_item(ArgsP a, const Ctx& c, int it, LAS float* scr) {
;     ...
;         if (r < I_SQ) { const int kb = r / 64, nb = r % 64; transpose_item(a->in[17] + (size_t)l * DM * DM, DM, 32 * nb, (bf16_t*)(wl + WL_PG), DM, 32 * nb, 64 * kb, scr, c.lane); return; }
;         r -= I_SQ;
;         { const int kb = r / 64, nb = r % 64; transpose_item(a->in[16] + (size_t)l * PLE * DM, DM, 32 * nb, (bf16_t*)(wl + WL_PE), PLE, 32 * nb, 64 * kb, scr, c.lane); }
	ds_write2_b32 v5, v19, v22 offset1:66
	ds_write2_b32 v5, v23, v24 offset0:132 offset1:198
	ds_write2_b32 v6, v25, v26 offset0:8 offset1:74
	ds_write2_b32 v6, v27, v28 offset0:140 offset1:206
	v_add_u32_e32 v6, 0x800, v5
	ds_write2_b32 v6, v29, v30 offset0:16 offset1:82
	ds_write2_b32 v6, v31, v32 offset0:148 offset1:214
	v_add_u32_e32 v6, 0xc00, v5
	ds_write2_b32 v6, v33, v34 offset0:24 offset1:90
	ds_write2_b32 v6, v35, v36 offset0:156 offset1:222
	v_add_u32_e32 v6, 0x1000, v5
	ds_write2_b32 v6, v37, v38 offset0:32 offset1:98
	ds_write2_b32 v6, v39, v40 offset0:164 offset1:230
	v_add_u32_e32 v6, 0x1400, v5
	ds_write2_b32 v6, v41, v42 offset0:40 offset1:106
	ds_write2_b32 v6, v43, v44 offset0:172 offset1:238
	v_add_u32_e32 v6, 0x1800, v5
	ds_write2_b32 v6, v45, v46 offset0:48 offset1:114
	ds_write2_b32 v6, v47, v48 offset0:180 offset1:246
	v_add_u32_e32 v6, 0x1c00, v5
	ds_write2_b32 v6, v49, v50 offset0:56 offset1:122
	ds_write2_b32 v6, v20, v0 offset0:188 offset1:254
	s_waitcnt lgkmcnt(0)
	ds_read2_b32 v[22:23], v11 offset0:33 offset1:41
	ds_read2_b32 v[24:25], v11 offset1:8
	ds_read2_b32 v[26:27], v11 offset0:66 offset1:74
	ds_read2_b32 v[28:29], v11 offset0:99 offset1:107
	ds_read2_b32 v[30:31], v11 offset0:132 offset1:140
	ds_read2_b32 v[32:33], v11 offset0:165 offset1:173
	ds_read2_b32 v[34:35], v11 offset0:198 offset1:206
	ds_read2_b32 v[36:37], v11 offset0:231 offset1:239
	s_add_u32 s4, s15, s4
	s_addc_u32 s5, s16, s5
	v_lshlrev_b32_e32 v6, 1, v4
	v_mov_b32_e32 v7, v1
	v_lshl_add_u64 v[6:7], s[4:5], 0, v[6:7]
	s_mov_b64 s[4:5], 0xa400000
	v_lshl_add_u64 v[20:21], v[6:7], 0, s[4:5]
	v_lshlrev_b32_e32 v38, 9, v18
	v_mov_b32_e32 v39, v1
	s_waitcnt lgkmcnt(6)
	v_cvt_pk_bf16_f32 v6, v24, v22
	s_waitcnt lgkmcnt(4)
	v_cvt_pk_bf16_f32 v7, v26, v28
	s_waitcnt lgkmcnt(2)
	v_cvt_pk_bf16_f32 v8, v30, v32
	s_waitcnt lgkmcnt(0)
	v_cvt_pk_bf16_f32 v9, v34, v36
	v_lshl_add_u64 v[38:39], v[20:21], 0, v[38:39]
	global_store_dwordx4 v[38:39], v[6:9], off sc1
	v_lshlrev_b32_e32 v22, 9, v17
	v_lshlrev_b32_e32 v38, 9, v16
	v_cvt_pk_bf16_f32 v6, v25, v23
	v_mov_b32_e32 v23, v1
	v_cvt_pk_bf16_f32 v7, v27, v29
	v_cvt_pk_bf16_f32 v8, v31, v33
	v_cvt_pk_bf16_f32 v9, v35, v37
	v_lshl_add_u64 v[22:23], v[20:21], 0, v[22:23]
	global_store_dwordx4 v[22:23], v[6:9], off sc1
	ds_read2_b32 v[22:23], v11 offset0:49 offset1:57
	ds_read2_b32 v[24:25], v11 offset0:16 offset1:24
	ds_read2_b32 v[26:27], v11 offset0:82 offset1:90
	ds_read2_b32 v[28:29], v11 offset0:115 offset1:123
	ds_read2_b32 v[30:31], v11 offset0:148 offset1:156
	ds_read2_b32 v[32:33], v11 offset0:181 offset1:189
	ds_read2_b32 v[34:35], v11 offset0:214 offset1:222
	ds_read2_b32 v[36:37], v11 offset0:247 offset1:255
	v_mov_b32_e32 v39, v1
	s_waitcnt lgkmcnt(6)
	v_cvt_pk_bf16_f32 v6, v24, v22
	s_waitcnt lgkmcnt(4)
	v_cvt_pk_bf16_f32 v7, v26, v28
	s_waitcnt lgkmcnt(2)
	v_cvt_pk_bf16_f32 v8, v30, v32
	s_waitcnt lgkmcnt(0)
	v_cvt_pk_bf16_f32 v9, v34, v36
	v_lshl_add_u64 v[38:39], v[20:21], 0, v[38:39]
	global_store_dwordx4 v[38:39], v[6:9], off sc1
	v_lshlrev_b32_e32 v22, 9, v15
	s_mov_b64 s[4:5], 0
	v_cvt_pk_bf16_f32 v6, v25, v23
	v_mov_b32_e32 v23, v1
	v_cvt_pk_bf16_f32 v7, v27, v29
	v_cvt_pk_bf16_f32 v8, v31, v33
	v_cvt_pk_bf16_f32 v9, v35, v37
	v_lshl_add_u64 v[20:21], v[20:21], 0, v[22:23]
	global_store_dwordx4 v[20:21], v[6:9], off sc1
	s_waitcnt lgkmcnt(0)
.LBB0_488:
	s_andn2_b64 vcc, exec, s[4:5]
	s_cbranch_vccnz .LBB0_490
	s_and_b32 s4, s17, 0xffc0
	s_add_i32 s60, s4, 0xffff5c00
	s_load_dwordx2 s[4:5], s[0:1], 0x88
	s_lshl_b64 s[8:9], s[2:3], 24
	v_or_b32_e32 v6, s60, v3
	v_lshlrev_b32_e32 v0, 2, v2
	v_mov_b32_e32 v7, v1
	s_waitcnt lgkmcnt(0)
	s_add_u32 s4, s4, s8
	s_addc_u32 s5, s5, s9
	s_lshl_b32 s6, s6, 2
	s_add_u32 s4, s4, s6
	s_addc_u32 s5, s5, 0
	v_lshl_add_u64 v[8:9], s[4:5], 0, v[0:1]
	v_lshlrev_b64 v[20:21], 13, v[6:7]
	v_lshl_add_u64 v[20:21], v[8:9], 0, v[20:21]
	v_or_b32_e32 v0, 2, v6
	global_load_dword v19, v[20:21], off nt
	v_lshlrev_b64 v[20:21], 13, v[0:1]
	v_lshl_add_u64 v[20:21], v[8:9], 0, v[20:21]
	v_or_b32_e32 v0, 4, v6
	global_load_dword v22, v[20:21], off nt
	v_lshlrev_b64 v[20:21], 13, v[0:1]
	v_lshl_add_u64 v[20:21], v[8:9], 0, v[20:21]
	v_or_b32_e32 v0, 6, v6
	global_load_dword v23, v[20:21], off nt
	v_lshlrev_b64 v[20:21], 13, v[0:1]
	v_lshl_add_u64 v[20:21], v[8:9], 0, v[20:21]
	v_or_b32_e32 v0, 8, v6
	global_load_dword v24, v[20:21], off nt
	v_lshlrev_b64 v[20:21], 13, v[0:1]
	v_lshl_add_u64 v[20:21], v[8:9], 0, v[20:21]
	v_or_b32_e32 v0, 10, v6
	global_load_dword v25, v[20:21], off nt
	v_lshlrev_b64 v[20:21], 13, v[0:1]
	v_lshl_add_u64 v[20:21], v[8:9], 0, v[20:21]
	v_or_b32_e32 v0, 12, v6
	global_load_dword v26, v[20:21], off nt
	v_lshlrev_b64 v[20:21], 13, v[0:1]
	v_lshl_add_u64 v[20:21], v[8:9], 0, v[20:21]
	v_or_b32_e32 v0, 14, v6
	global_load_dword v27, v[20:21], off nt
	v_lshlrev_b64 v[20:21], 13, v[0:1]
	v_lshl_add_u64 v[20:21], v[8:9], 0, v[20:21]
	v_or_b32_e32 v0, 16, v6
	global_load_dword v28, v[20:21], off nt
	v_lshlrev_b64 v[20:21], 13, v[0:1]
	v_lshl_add_u64 v[20:21], v[8:9], 0, v[20:21]
	v_or_b32_e32 v0, 18, v6
	global_load_dword v29, v[20:21], off nt
	v_lshlrev_b64 v[20:21], 13, v[0:1]
	v_lshl_add_u64 v[20:21], v[8:9], 0, v[20:21]
	v_or_b32_e32 v0, 20, v6
	global_load_dword v30, v[20:21], off nt
	v_lshlrev_b64 v[20:21], 13, v[0:1]
	v_lshl_add_u64 v[20:21], v[8:9], 0, v[20:21]
	v_or_b32_e32 v0, 22, v6
	global_load_dword v31, v[20:21], off nt
	v_lshlrev_b64 v[20:21], 13, v[0:1]
	v_lshl_add_u64 v[20:21], v[8:9], 0, v[20:21]
	v_or_b32_e32 v0, 24, v6
	global_load_dword v32, v[20:21], off nt
	v_lshlrev_b64 v[20:21], 13, v[0:1]
	v_lshl_add_u64 v[20:21], v[8:9], 0, v[20:21]
; #define LAS __attribute__((address_space(3)))
; __device__ __forceinline__ unsigned pk_bf16(float lo, float hi) { f32x2 v = {lo, hi}; bf16x2_t b = __builtin_convertvector(v, bf16x2_t); return __builtin_bit_cast(unsigned, b); }
; #define LDS_WAIT() asm volatile("s_waitcnt lgkmcnt(0)" ::: "memory")
; __device__ __forceinline__ void transpose_item(const float* __restrict__ W, int ldw, int src_col0, bf16_t* WT, int K, int dst_row0, int k0, LAS float* scr, int lane) {
;     float tmp[32];
; #pragma unroll
;     for (int i = 0; i < 32; ++i) tmp[i] = __builtin_nontemporal_load(W + (size_t)(k0 + 2 * i + (lane >> 5)) * ldw + src_col0 + (lane & 31));
; #pragma unroll
;     for (int i = 0; i < 32; ++i) scr[(2 * i + (lane >> 5)) * 33 + (lane & 31)] = tmp[i];
;     LDS_WAIT();
;     const int c = lane & 7;
; #pragma unroll
;     for (int j = 0; j < 4; ++j) { const int n = (lane >> 3) + 8 * j; const LAS float* s = scr + (8 * c) * 33 + n;
;         u32x4 o; o.x = pk_bf16(s[0 * 33], s[1 * 33]); o.y = pk_bf16(s[2 * 33], s[3 * 33]); o.z = pk_bf16(s[4 * 33], s[5 * 33]); o.w = pk_bf16(s[6 * 33], s[7 * 33]);
;         *(u32x4*)(WT + (size_t)(dst_row0 + n) * K + k0 + 8 * c) = o; }
;     LDS_WAIT();
; }
; __device__ __forceinline__ void convert_item(ArgsP a, const Ctx& c, int it, LAS float* scr) {
;     ...
;         if (r < I_SQ) { const int kb = r / 64, nb = r % 64; transpose_item(a->in[17] + (size_t)l * DM * DM, DM, 32 * nb, (bf16_t*)(wl + WL_PG), DM, 32 * nb, 64 * kb, scr, c.lane); return; }
	v_or_b32_e32 v0, 26, v6
	global_load_dword v33, v[20:21], off nt
	v_lshlrev_b64 v[20:21], 13, v[0:1]
	v_lshl_add_u64 v[20:21], v[8:9], 0, v[20:21]
	v_or_b32_e32 v0, 28, v6
	global_load_dword v34, v[20:21], off nt
	v_lshlrev_b64 v[20:21], 13, v[0:1]
	v_lshl_add_u64 v[20:21], v[8:9], 0, v[20:21]
	v_or_b32_e32 v0, 30, v6
	global_load_dword v35, v[20:21], off nt
	v_lshlrev_b64 v[20:21], 13, v[0:1]
	v_lshl_add_u64 v[20:21], v[8:9], 0, v[20:21]
	v_or_b32_e32 v0, 32, v6
	global_load_dword v36, v[20:21], off nt
	v_lshlrev_b64 v[20:21], 13, v[0:1]
	v_lshl_add_u64 v[20:21], v[8:9], 0, v[20:21]
	v_or_b32_e32 v0, 34, v6
	global_load_dword v37, v[20:21], off nt
	v_lshlrev_b64 v[20:21], 13, v[0:1]
	v_lshl_add_u64 v[20:21], v[8:9], 0, v[20:21]
	v_or_b32_e32 v0, 36, v6
	global_load_dword v38, v[20:21], off nt
	v_lshlrev_b64 v[20:21], 13, v[0:1]
	v_lshl_add_u64 v[20:21], v[8:9], 0, v[20:21]
	v_or_b32_e32 v0, 38, v6
	global_load_dword v39, v[20:21], off nt
	v_lshlrev_b64 v[20:21], 13, v[0:1]
	v_lshl_add_u64 v[20:21], v[8:9], 0, v[20:21]
	v_or_b32_e32 v0, 40, v6
	global_load_dword v40, v[20:21], off nt
	v_lshlrev_b64 v[20:21], 13, v[0:1]
	v_lshl_add_u64 v[20:21], v[8:9], 0, v[20:21]
	v_or_b32_e32 v0, 42, v6
	global_load_dword v41, v[20:21], off nt
	v_lshlrev_b64 v[20:21], 13, v[0:1]
	v_lshl_add_u64 v[20:21], v[8:9], 0, v[20:21]
	v_or_b32_e32 v0, 44, v6
	global_load_dword v42, v[20:21], off nt
	v_lshlrev_b64 v[20:21], 13, v[0:1]
	v_lshl_add_u64 v[20:21], v[8:9], 0, v[20:21]
	v_or_b32_e32 v0, 46, v6
	global_load_dword v43, v[20:21], off nt
	v_lshlrev_b64 v[20:21], 13, v[0:1]
	v_lshl_add_u64 v[20:21], v[8:9], 0, v[20:21]
	v_or_b32_e32 v0, 48, v6
	global_load_dword v44, v[20:21], off nt
	v_lshlrev_b64 v[20:21], 13, v[0:1]
	v_lshl_add_u64 v[20:21], v[8:9], 0, v[20:21]
	v_or_b32_e32 v0, 50, v6
	global_load_dword v45, v[20:21], off nt
	v_lshlrev_b64 v[20:21], 13, v[0:1]
	v_lshl_add_u64 v[20:21], v[8:9], 0, v[20:21]
	v_or_b32_e32 v0, 52, v6
	global_load_dword v46, v[20:21], off nt
	v_lshlrev_b64 v[20:21], 13, v[0:1]
	v_lshl_add_u64 v[20:21], v[8:9], 0, v[20:21]
	v_or_b32_e32 v0, 54, v6
	global_load_dword v47, v[20:21], off nt
	v_lshlrev_b64 v[20:21], 13, v[0:1]
	v_lshl_add_u64 v[20:21], v[8:9], 0, v[20:21]
	v_or_b32_e32 v0, 56, v6
	global_load_dword v48, v[20:21], off nt
	v_lshlrev_b64 v[20:21], 13, v[0:1]
	v_lshl_add_u64 v[20:21], v[8:9], 0, v[20:21]
	v_or_b32_e32 v0, 58, v6
	global_load_dword v49, v[20:21], off nt
	v_lshlrev_b64 v[20:21], 13, v[0:1]
	v_lshl_add_u64 v[20:21], v[8:9], 0, v[20:21]
	v_or_b32_e32 v0, 60, v6
	global_load_dword v50, v[20:21], off nt
	v_lshlrev_b64 v[20:21], 13, v[0:1]
	v_or_b32_e32 v0, 62, v6
	v_lshlrev_b64 v[6:7], 13, v[0:1]
	v_lshl_add_u64 v[20:21], v[8:9], 0, v[20:21]
	v_lshl_add_u64 v[6:7], v[8:9], 0, v[6:7]
	global_load_dword v20, v[20:21], off nt
	s_lshl_b64 s[4:5], s[60:61], 1
	global_load_dword v0, v[6:7], off nt
	v_add_u32_e32 v6, 0x400, v5
	s_waitcnt vmcnt(0)
	ds_write2_b32 v5, v19, v22 offset1:66
	ds_write2_b32 v5, v23, v24 offset0:132 offset1:198
	ds_write2_b32 v6, v25, v26 offset0:8 offset1:74
	ds_write2_b32 v6, v27, v28 offset0:140 offset1:206
	v_add_u32_e32 v6, 0x800, v5
	ds_write2_b32 v6, v29, v30 offset0:16 offset1:82
	ds_write2_b32 v6, v31, v32 offset0:148 offset1:214
	v_add_u32_e32 v6, 0xc00, v5
	ds_write2_b32 v6, v33, v34 offset0:24 offset1:90
	ds_write2_b32 v6, v35, v36 offset0:156 offset1:222
	v_add_u32_e32 v6, 0x1000, v5
	ds_write2_b32 v6, v37, v38 offset0:32 offset1:98
	ds_write2_b32 v6, v39, v40 offset0:164 offset1:230
	v_add_u32_e32 v6, 0x1400, v5
	ds_write2_b32 v6, v41, v42 offset0:40 offset1:106
	ds_write2_b32 v6, v43, v44 offset0:172 offset1:238
	v_add_u32_e32 v6, 0x1800, v5
	ds_write2_b32 v6, v45, v46 offset0:48 offset1:114
	ds_write2_b32 v6, v47, v48 offset0:180 offset1:246
	v_add_u32_e32 v6, 0x1c00, v5
	ds_write2_b32 v6, v49, v50 offset0:56 offset1:122
	ds_write2_b32 v6, v20, v0 offset0:188 offset1:254
	s_waitcnt lgkmcnt(0)
	ds_read2_b32 v[22:23], v11 offset0:33 offset1:41
	ds_read2_b32 v[24:25], v11 offset1:8
	ds_read2_b32 v[26:27], v11 offset0:66 offset1:74
	ds_read2_b32 v[28:29], v11 offset0:99 offset1:107
	ds_read2_b32 v[30:31], v11 offset0:132 offset1:140
	ds_read2_b32 v[32:33], v11 offset0:165 offset1:173
	ds_read2_b32 v[34:35], v11 offset0:198 offset1:206
	ds_read2_b32 v[36:37], v11 offset0:231 offset1:239
	s_add_u32 s4, s15, s4
	s_addc_u32 s5, s16, s5
	v_lshlrev_b32_e32 v0, 1, v4
	v_lshl_add_u64 v[6:7], s[4:5], 0, v[0:1]
	s_mov_b64 s[4:5], 0xa500000
	v_lshl_add_u64 v[20:21], v[6:7], 0, s[4:5]
	v_lshlrev_b32_e32 v0, 12, v18
	s_waitcnt lgkmcnt(6)
	v_cvt_pk_bf16_f32 v6, v24, v22
	s_waitcnt lgkmcnt(4)
	v_cvt_pk_bf16_f32 v7, v26, v28
	s_waitcnt lgkmcnt(2)
	v_cvt_pk_bf16_f32 v8, v30, v32
	s_waitcnt lgkmcnt(0)
	v_cvt_pk_bf16_f32 v9, v34, v36
	v_lshl_add_u64 v[18:19], v[20:21], 0, v[0:1]
	v_lshlrev_b32_e32 v0, 12, v17
	global_store_dwordx4 v[18:19], v[6:9], off sc1
	v_lshl_add_u64 v[18:19], v[20:21], 0, v[0:1]
	v_lshlrev_b32_e32 v0, 12, v16
	v_cvt_pk_bf16_f32 v6, v25, v23
	v_cvt_pk_bf16_f32 v7, v27, v29
	v_cvt_pk_bf16_f32 v8, v31, v33
	v_cvt_pk_bf16_f32 v9, v35, v37
	global_store_dwordx4 v[18:19], v[6:9], off sc1
	ds_read2_b32 v[18:19], v11 offset0:49 offset1:57
	ds_read2_b32 v[22:23], v11 offset0:16 offset1:24
	ds_read2_b32 v[24:25], v11 offset0:82 offset1:90
	ds_read2_b32 v[26:27], v11 offset0:115 offset1:123
	ds_read2_b32 v[28:29], v11 offset0:148 offset1:156
	ds_read2_b32 v[30:31], v11 offset0:181 offset1:189
	ds_read2_b32 v[32:33], v11 offset0:214 offset1:222
	ds_read2_b32 v[34:35], v11 offset0:247 offset1:255
	v_lshl_add_u64 v[16:17], v[20:21], 0, v[0:1]
	s_waitcnt lgkmcnt(6)
	v_cvt_pk_bf16_f32 v6, v22, v18
	s_waitcnt lgkmcnt(4)
	v_cvt_pk_bf16_f32 v7, v24, v26
	s_waitcnt lgkmcnt(2)
	v_cvt_pk_bf16_f32 v8, v28, v30
	s_waitcnt lgkmcnt(0)
	v_cvt_pk_bf16_f32 v9, v32, v34
	v_lshlrev_b32_e32 v0, 12, v15
	global_store_dwordx4 v[16:17], v[6:9], off sc1
	v_lshl_add_u64 v[16:17], v[20:21], 0, v[0:1]
	s_nop 0
	v_cvt_pk_bf16_f32 v6, v23, v19
	v_cvt_pk_bf16_f32 v7, v25, v27
	v_cvt_pk_bf16_f32 v8, v29, v31
	v_cvt_pk_bf16_f32 v9, v33, v35
	global_store_dwordx4 v[16:17], v[6:9], off sc1
	s_waitcnt lgkmcnt(0)

; #define LAS __attribute__((address_space(3)))
; __device__ __forceinline__ void transpose_item(const float* __restrict__ W, int ldw, int src_col0, bf16_t* WT, int K, int dst_row0, int k0, LAS float* scr, int lane) {
;     float tmp[32];
; #pragma unroll
;     for (int i = 0; i < 32; ++i) tmp[i] = __builtin_nontemporal_load(W + (size_t)(k0 + 2 * i + (lane >> 5)) * ldw + src_col0 + (lane & 31));
; __device__ __forceinline__ void convert_item(ArgsP a, const Ctx& c, int it, LAS float* scr) {
;     ...
;         if (r < I_SQ) { const int kb = r / 64, nb = r % 64; transpose_item(a->in[4] + (size_t)l * DM * DM, DM, 32 * nb, (bf16_t*)(wl + WL_OUT), DM, 32 * nb, 64 * kb, scr, c.lane); return; }
.LBB0_491:
	s_andn2_b64 vcc, exec, s[4:5]
	s_cbranch_vccnz .LBB0_493
	s_and_b32 s4, s17, 0xffc0
	s_add_i32 s60, s4, 0xffff6400
	s_load_dwordx2 s[4:5], s[0:1], 0x20
	s_lshl_b64 s[6:7], s[2:3], 24
	v_or_b32_e32 v6, s60, v3
	v_lshlrev_b32_e32 v0, 2, v2
	v_mov_b32_e32 v7, v1
	s_waitcnt lgkmcnt(0)
	s_add_u32 s4, s4, s6
	s_addc_u32 s5, s5, s7
	s_lshl_b32 s3, s10, 5
	s_and_b32 s3, s3, 0x7e0
	s_lshl_b32 s6, s3, 2
	s_add_u32 s4, s4, s6
	s_addc_u32 s5, s5, 0
	v_lshl_add_u64 v[8:9], s[4:5], 0, v[0:1]
	v_lshlrev_b64 v[16:17], 13, v[6:7]
	v_lshl_add_u64 v[16:17], v[8:9], 0, v[16:17]
	v_or_b32_e32 v0, 2, v6
	global_load_dword v15, v[16:17], off nt
	v_lshlrev_b64 v[16:17], 13, v[0:1]
	v_lshl_add_u64 v[16:17], v[8:9], 0, v[16:17]
	v_or_b32_e32 v0, 4, v6
	global_load_dword v18, v[16:17], off nt
	v_lshlrev_b64 v[16:17], 13, v[0:1]
	v_lshl_add_u64 v[16:17], v[8:9], 0, v[16:17]
	v_or_b32_e32 v0, 6, v6
	global_load_dword v19, v[16:17], off nt
	v_lshlrev_b64 v[16:17], 13, v[0:1]
	v_lshl_add_u64 v[16:17], v[8:9], 0, v[16:17]
	v_or_b32_e32 v0, 8, v6
	global_load_dword v20, v[16:17], off nt
	v_lshlrev_b64 v[16:17], 13, v[0:1]
	v_lshl_add_u64 v[16:17], v[8:9], 0, v[16:17]
	v_or_b32_e32 v0, 10, v6
	global_load_dword v21, v[16:17], off nt
	v_lshlrev_b64 v[16:17], 13, v[0:1]
	v_lshl_add_u64 v[16:17], v[8:9], 0, v[16:17]
	v_or_b32_e32 v0, 12, v6
	global_load_dword v22, v[16:17], off nt
	v_lshlrev_b64 v[16:17], 13, v[0:1]
	v_lshl_add_u64 v[16:17], v[8:9], 0, v[16:17]
	v_or_b32_e32 v0, 14, v6
	global_load_dword v23, v[16:17], off nt
	v_lshlrev_b64 v[16:17], 13, v[0:1]
	v_lshl_add_u64 v[16:17], v[8:9], 0, v[16:17]
	v_or_b32_e32 v0, 16, v6
	global_load_dword v24, v[16:17], off nt
	v_lshlrev_b64 v[16:17], 13, v[0:1]
	v_lshl_add_u64 v[16:17], v[8:9], 0, v[16:17]
	v_or_b32_e32 v0, 18, v6
	global_load_dword v25, v[16:17], off nt
	v_lshlrev_b64 v[16:17], 13, v[0:1]
	v_lshl_add_u64 v[16:17], v[8:9], 0, v[16:17]
	v_or_b32_e32 v0, 20, v6
	global_load_dword v26, v[16:17], off nt
	v_lshlrev_b64 v[16:17], 13, v[0:1]
	v_lshl_add_u64 v[16:17], v[8:9], 0, v[16:17]
	v_or_b32_e32 v0, 22, v6
	global_load_dword v27, v[16:17], off nt
	v_lshlrev_b64 v[16:17], 13, v[0:1]
	v_lshl_add_u64 v[16:17], v[8:9], 0, v[16:17]
	v_or_b32_e32 v0, 24, v6
	global_load_dword v28, v[16:17], off nt
	v_lshlrev_b64 v[16:17], 13, v[0:1]
	v_lshl_add_u64 v[16:17], v[8:9], 0, v[16:17]
	v_or_b32_e32 v0, 26, v6
	global_load_dword v29, v[16:17], off nt
	v_lshlrev_b64 v[16:17], 13, v[0:1]
	v_lshl_add_u64 v[16:17], v[8:9], 0, v[16:17]
	v_or_b32_e32 v0, 28, v6
	global_load_dword v30, v[16:17], off nt
	v_lshlrev_b64 v[16:17], 13, v[0:1]
	v_lshl_add_u64 v[16:17], v[8:9], 0, v[16:17]
	v_or_b32_e32 v0, 30, v6
	global_load_dword v31, v[16:17], off nt
	v_lshlrev_b64 v[16:17], 13, v[0:1]
	v_lshl_add_u64 v[16:17], v[8:9], 0, v[16:17]
	v_or_b32_e32 v0, 32, v6
	global_load_dword v32, v[16:17], off nt
	v_lshlrev_b64 v[16:17], 13, v[0:1]
	v_lshl_add_u64 v[16:17], v[8:9], 0, v[16:17]
	v_or_b32_e32 v0, 34, v6
	global_load_dword v33, v[16:17], off nt
	v_lshlrev_b64 v[16:17], 13, v[0:1]
	v_lshl_add_u64 v[16:17], v[8:9], 0, v[16:17]
	v_or_b32_e32 v0, 36, v6
	global_load_dword v34, v[16:17], off nt
	v_lshlrev_b64 v[16:17], 13, v[0:1]
	v_lshl_add_u64 v[16:17], v[8:9], 0, v[16:17]
	v_or_b32_e32 v0, 38, v6
	global_load_dword v35, v[16:17], off nt
	v_lshlrev_b64 v[16:17], 13, v[0:1]
	v_lshl_add_u64 v[16:17], v[8:9], 0, v[16:17]
	v_or_b32_e32 v0, 40, v6
	global_load_dword v36, v[16:17], off nt
	v_lshlrev_b64 v[16:17], 13, v[0:1]
	v_lshl_add_u64 v[16:17], v[8:9], 0, v[16:17]
	v_or_b32_e32 v0, 42, v6
	global_load_dword v37, v[16:17], off nt
	v_lshlrev_b64 v[16:17], 13, v[0:1]
	v_lshl_add_u64 v[16:17], v[8:9], 0, v[16:17]
	v_or_b32_e32 v0, 44, v6
	global_load_dword v38, v[16:17], off nt
	v_lshlrev_b64 v[16:17], 13, v[0:1]
	v_lshl_add_u64 v[16:17], v[8:9], 0, v[16:17]
	v_or_b32_e32 v0, 46, v6
	global_load_dword v39, v[16:17], off nt
	v_lshlrev_b64 v[16:17], 13, v[0:1]
	v_lshl_add_u64 v[16:17], v[8:9], 0, v[16:17]
	v_or_b32_e32 v0, 48, v6
	global_load_dword v40, v[16:17], off nt
	v_lshlrev_b64 v[16:17], 13, v[0:1]
	v_lshl_add_u64 v[16:17], v[8:9], 0, v[16:17]
	v_or_b32_e32 v0, 50, v6
	global_load_dword v41, v[16:17], off nt
	v_lshlrev_b64 v[16:17], 13, v[0:1]
	v_lshl_add_u64 v[16:17], v[8:9], 0, v[16:17]
	v_or_b32_e32 v0, 52, v6
	global_load_dword v42, v[16:17], off nt
	v_lshlrev_b64 v[16:17], 13, v[0:1]
	v_lshl_add_u64 v[16:17], v[8:9], 0, v[16:17]
	v_or_b32_e32 v0, 54, v6
	global_load_dword v43, v[16:17], off nt
	v_lshlrev_b64 v[16:17], 13, v[0:1]
	v_lshl_add_u64 v[16:17], v[8:9], 0, v[16:17]
	v_or_b32_e32 v0, 56, v6
	global_load_dword v44, v[16:17], off nt
	v_lshlrev_b64 v[16:17], 13, v[0:1]
	v_lshl_add_u64 v[16:17], v[8:9], 0, v[16:17]
	v_or_b32_e32 v0, 58, v6
	global_load_dword v45, v[16:17], off nt
	v_lshlrev_b64 v[16:17], 13, v[0:1]
	v_lshl_add_u64 v[16:17], v[8:9], 0, v[16:17]
	v_or_b32_e32 v0, 60, v6
	global_load_dword v46, v[16:17], off nt
	v_lshlrev_b64 v[16:17], 13, v[0:1]
	v_or_b32_e32 v0, 62, v6
	v_lshlrev_b64 v[6:7], 13, v[0:1]
	v_lshl_add_u64 v[16:17], v[8:9], 0, v[16:17]
	v_lshl_add_u64 v[6:7], v[8:9], 0, v[6:7]
	global_load_dword v16, v[16:17], off nt
	s_lshl_b64 s[4:5], s[60:61], 1
	global_load_dword v0, v[6:7], off nt
	v_add_u32_e32 v6, 0x400, v5
	s_waitcnt vmcnt(0)
; #define LAS __attribute__((address_space(3)))
; __device__ __forceinline__ unsigned pk_bf16(float lo, float hi) { f32x2 v = {lo, hi}; bf16x2_t b = __builtin_convertvector(v, bf16x2_t); return __builtin_bit_cast(unsigned, b); }
; #define LDS_WAIT() asm volatile("s_waitcnt lgkmcnt(0)" ::: "memory")
; __device__ __forceinline__ void transpose_item(const float* __restrict__ W, int ldw, int src_col0, bf16_t* WT, int K, int dst_row0, int k0, LAS float* scr, int lane) {
;     ...
; #pragma unroll
;     for (int i = 0; i < 32; ++i) scr[(2 * i + (lane >> 5)) * 33 + (lane & 31)] = tmp[i];
;     LDS_WAIT();
;     const int c = lane & 7;
; #pragma unroll
;     for (int j = 0; j < 4; ++j) { const int n = (lane >> 3) + 8 * j; const LAS float* s = scr + (8 * c) * 33 + n;
;         u32x4 o; o.x = pk_bf16(s[0 * 33], s[1 * 33]); o.y = pk_bf16(s[2 * 33], s[3 * 33]); o.z = pk_bf16(s[4 * 33], s[5 * 33]); o.w = pk_bf16(s[6 * 33], s[7 * 33]);
;         *(u32x4*)(WT + (size_t)(dst_row0 + n) * K + k0 + 8 * c) = o; }
; __device__ __forceinline__ void convert_item(ArgsP a, const Ctx& c, int it, LAS float* scr) {
;     ...
;         if (r < I_SQ) { const int kb = r / 64, nb = r % 64; transpose_item(a->in[4] + (size_t)l * DM * DM, DM, 32 * nb, (bf16_t*)(wl + WL_OUT), DM, 32 * nb, 64 * kb, scr, c.lane); return; }
	ds_write2_b32 v5, v15, v18 offset1:66
	ds_write2_b32 v5, v19, v20 offset0:132 offset1:198
	ds_write2_b32 v6, v21, v22 offset0:8 offset1:74
	ds_write2_b32 v6, v23, v24 offset0:140 offset1:206
	v_add_u32_e32 v6, 0x800, v5
	ds_write2_b32 v6, v25, v26 offset0:16 offset1:82
	ds_write2_b32 v6, v27, v28 offset0:148 offset1:214
	v_add_u32_e32 v6, 0xc00, v5
	ds_write2_b32 v6, v29, v30 offset0:24 offset1:90
	ds_write2_b32 v6, v31, v32 offset0:156 offset1:222
	v_add_u32_e32 v6, 0x1000, v5
	ds_write2_b32 v6, v33, v34 offset0:32 offset1:98
	ds_write2_b32 v6, v35, v36 offset0:164 offset1:230
	v_add_u32_e32 v6, 0x1400, v5
	ds_write2_b32 v6, v37, v38 offset0:40 offset1:106
	ds_write2_b32 v6, v39, v40 offset0:172 offset1:238
	v_add_u32_e32 v6, 0x1800, v5
	ds_write2_b32 v6, v41, v42 offset0:48 offset1:114
	ds_write2_b32 v6, v43, v44 offset0:180 offset1:246
	v_add_u32_e32 v6, 0x1c00, v5
	ds_write2_b32 v6, v45, v46 offset0:56 offset1:122
	ds_write2_b32 v6, v16, v0 offset0:188 offset1:254
	s_waitcnt lgkmcnt(0)
	s_add_u32 s4, s15, s4
	ds_read2_b32 v[18:19], v11 offset0:33 offset1:41
	ds_read2_b32 v[20:21], v11 offset1:8
	ds_read2_b32 v[22:23], v11 offset0:66 offset1:74
	ds_read2_b32 v[24:25], v11 offset0:99 offset1:107
	ds_read2_b32 v[26:27], v11 offset0:132 offset1:140
	ds_read2_b32 v[28:29], v11 offset0:165 offset1:173
	ds_read2_b32 v[30:31], v11 offset0:198 offset1:206
	ds_read2_b32 v[32:33], v11 offset0:231 offset1:239
	s_addc_u32 s5, s16, s5
	v_lshlrev_b32_e32 v0, 1, v4
	v_lshl_add_u64 v[6:7], s[4:5], 0, v[0:1]
	s_mov_b64 s[4:5], 0x5a00000
	v_or_b32_e32 v0, s3, v10
	v_lshl_add_u64 v[16:17], v[6:7], 0, s[4:5]
	v_lshlrev_b32_e32 v0, 12, v0
	v_lshl_add_u64 v[34:35], v[16:17], 0, v[0:1]
	v_or_b32_e32 v0, s3, v12
	s_waitcnt lgkmcnt(6)
	v_cvt_pk_bf16_f32 v6, v20, v18
	s_waitcnt lgkmcnt(4)
	v_cvt_pk_bf16_f32 v7, v22, v24
	s_waitcnt lgkmcnt(2)
	v_cvt_pk_bf16_f32 v8, v26, v28
	s_waitcnt lgkmcnt(0)
	v_cvt_pk_bf16_f32 v9, v30, v32
	v_lshlrev_b32_e32 v0, 12, v0
	global_store_dwordx4 v[34:35], v[6:9], off sc1
	s_nop 1
	v_cvt_pk_bf16_f32 v6, v21, v19
	v_cvt_pk_bf16_f32 v7, v23, v25
	v_cvt_pk_bf16_f32 v8, v27, v29
	v_cvt_pk_bf16_f32 v9, v31, v33
	v_lshl_add_u64 v[18:19], v[16:17], 0, v[0:1]
	global_store_dwordx4 v[18:19], v[6:9], off sc1
	ds_read2_b32 v[18:19], v11 offset0:49 offset1:57
	ds_read2_b32 v[20:21], v11 offset0:16 offset1:24
	ds_read2_b32 v[22:23], v11 offset0:82 offset1:90
	ds_read2_b32 v[24:25], v11 offset0:115 offset1:123
	ds_read2_b32 v[26:27], v11 offset0:148 offset1:156
	ds_read2_b32 v[28:29], v11 offset0:181 offset1:189
	ds_read2_b32 v[30:31], v11 offset0:214 offset1:222
	ds_read2_b32 v[32:33], v11 offset0:247 offset1:255
	v_or_b32_e32 v0, s3, v13
	v_lshlrev_b32_e32 v0, 12, v0
	v_lshl_add_u64 v[34:35], v[16:17], 0, v[0:1]
	v_or_b32_e32 v0, s3, v14
	s_waitcnt lgkmcnt(6)
	v_cvt_pk_bf16_f32 v6, v20, v18
	s_waitcnt lgkmcnt(4)
	v_cvt_pk_bf16_f32 v7, v22, v24
	s_waitcnt lgkmcnt(2)
	v_cvt_pk_bf16_f32 v8, v26, v28
	s_waitcnt lgkmcnt(0)
	v_cvt_pk_bf16_f32 v9, v30, v32
	v_lshlrev_b32_e32 v0, 12, v0
	global_store_dwordx4 v[34:35], v[6:9], off sc1
	v_lshl_add_u64 v[16:17], v[16:17], 0, v[0:1]
	s_nop 0
	v_cvt_pk_bf16_f32 v6, v21, v19
	v_cvt_pk_bf16_f32 v7, v23, v25
	v_cvt_pk_bf16_f32 v8, v27, v29
	v_cvt_pk_bf16_f32 v9, v31, v33
	global_store_dwordx4 v[16:17], v[6:9], off sc1
	s_waitcnt lgkmcnt(0)

; __device__ __forceinline__ void transpose_item(const float* __restrict__ W, int ldw, int src_col0, bf16_t* WT, int K, int dst_row0, int k0, LAS float* scr, int lane) {
;     ...
;     for (int i = 0; i < 32; ++i) tmp[i] = __builtin_nontemporal_load(W + (size_t)(k0 + 2 * i + (lane >> 5)) * ldw + src_col0 + (lane & 31));
; __device__ __forceinline__ void convert_item(ArgsP a, const Ctx& c, int it, LAS float* scr) {
;     ...
;         if (r < I_SQ) { const int kb = r / 64, nb = r % 64, row0 = 32 * nb; const int sc = row0 < 768 ? W_DV + row0 : (row0 < 1280 ? W_GV + (row0 - 768) : W_MV + (row0 - 1280));
;             transpose_item(a->in[3] + (size_t)l * DM * DIN, DIN, sc, (bf16_t*)(wl + WL_V), DM, row0, 64 * kb, scr, c.lane); return; }
.LBB0_503:
	s_load_dwordx2 s[6:7], s[0:1], 0x18
	s_and_b32 s4, s17, 0xffc0
	s_add_i32 s4, s4, 0xffff6c00
	s_mul_i32 s8, s2, 0x3020000
	s_mul_hi_i32 s5, s2, 0x3020000
	s_waitcnt lgkmcnt(0)
	s_add_u32 s8, s6, s8
	s_addc_u32 s5, s7, s5
	s_lshl_b64 s[6:7], s[60:61], 2
	s_add_u32 s6, s8, s6
	s_addc_u32 s7, s5, s7
	v_lshlrev_b32_e32 v0, 2, v2
	v_or_b32_e32 v15, s4, v3
	v_lshl_add_u64 v[6:7], s[6:7], 0, v[0:1]
	v_mad_u64_u32 v[8:9], s[6:7], v15, s75, v[6:7]
	global_load_dword v0, v[8:9], off nt
	v_or_b32_e32 v8, 2, v15
	v_mad_u64_u32 v[8:9], s[6:7], v8, s75, v[6:7]
	global_load_dword v16, v[8:9], off nt
	v_or_b32_e32 v8, 4, v15
	v_mad_u64_u32 v[8:9], s[6:7], v8, s75, v[6:7]
	global_load_dword v17, v[8:9], off nt
	v_or_b32_e32 v8, 6, v15
	v_mad_u64_u32 v[8:9], s[6:7], v8, s75, v[6:7]
	global_load_dword v18, v[8:9], off nt
	v_or_b32_e32 v8, 8, v15
	v_mad_u64_u32 v[8:9], s[6:7], v8, s75, v[6:7]
	global_load_dword v19, v[8:9], off nt
	v_or_b32_e32 v8, 10, v15
	v_mad_u64_u32 v[8:9], s[6:7], v8, s75, v[6:7]
	global_load_dword v20, v[8:9], off nt
	v_or_b32_e32 v8, 12, v15
	v_mad_u64_u32 v[8:9], s[6:7], v8, s75, v[6:7]
	global_load_dword v21, v[8:9], off nt
	v_or_b32_e32 v8, 14, v15
	v_mad_u64_u32 v[8:9], s[6:7], v8, s75, v[6:7]
	global_load_dword v22, v[8:9], off nt
	v_or_b32_e32 v8, 16, v15
	v_mad_u64_u32 v[8:9], s[6:7], v8, s75, v[6:7]
	global_load_dword v23, v[8:9], off nt
	v_or_b32_e32 v8, 18, v15
	v_mad_u64_u32 v[8:9], s[6:7], v8, s75, v[6:7]
	global_load_dword v24, v[8:9], off nt
	v_or_b32_e32 v8, 20, v15
	v_mad_u64_u32 v[8:9], s[6:7], v8, s75, v[6:7]
	global_load_dword v25, v[8:9], off nt
	v_or_b32_e32 v8, 22, v15
	v_mad_u64_u32 v[8:9], s[6:7], v8, s75, v[6:7]
	global_load_dword v26, v[8:9], off nt
	v_or_b32_e32 v8, 24, v15
	v_mad_u64_u32 v[8:9], s[6:7], v8, s75, v[6:7]
	global_load_dword v27, v[8:9], off nt
	v_or_b32_e32 v8, 26, v15
	v_mad_u64_u32 v[8:9], s[6:7], v8, s75, v[6:7]
	global_load_dword v28, v[8:9], off nt
	v_or_b32_e32 v8, 28, v15
	v_mad_u64_u32 v[8:9], s[6:7], v8, s75, v[6:7]
	global_load_dword v29, v[8:9], off nt
	v_or_b32_e32 v8, 30, v15
	v_mad_u64_u32 v[8:9], s[6:7], v8, s75, v[6:7]
	global_load_dword v30, v[8:9], off nt
	v_or_b32_e32 v8, 32, v15
	v_mad_u64_u32 v[8:9], s[6:7], v8, s75, v[6:7]
	global_load_dword v31, v[8:9], off nt
	v_or_b32_e32 v8, 34, v15
	v_mad_u64_u32 v[8:9], s[6:7], v8, s75, v[6:7]
	global_load_dword v32, v[8:9], off nt
	v_or_b32_e32 v8, 36, v15
	v_mad_u64_u32 v[8:9], s[6:7], v8, s75, v[6:7]
	global_load_dword v33, v[8:9], off nt
	v_or_b32_e32 v8, 38, v15
	v_mad_u64_u32 v[8:9], s[6:7], v8, s75, v[6:7]
	global_load_dword v34, v[8:9], off nt
	v_or_b32_e32 v8, 40, v15
	v_mad_u64_u32 v[8:9], s[6:7], v8, s75, v[6:7]
	global_load_dword v35, v[8:9], off nt
	v_or_b32_e32 v8, 42, v15
	v_mad_u64_u32 v[8:9], s[6:7], v8, s75, v[6:7]
	global_load_dword v36, v[8:9], off nt
	v_or_b32_e32 v8, 44, v15
	v_mad_u64_u32 v[8:9], s[6:7], v8, s75, v[6:7]
	global_load_dword v37, v[8:9], off nt
	v_or_b32_e32 v8, 46, v15
	v_mad_u64_u32 v[8:9], s[6:7], v8, s75, v[6:7]
	global_load_dword v38, v[8:9], off nt
	v_or_b32_e32 v8, 48, v15
	v_mad_u64_u32 v[8:9], s[6:7], v8, s75, v[6:7]
	global_load_dword v39, v[8:9], off nt
	v_or_b32_e32 v8, 50, v15
	v_mad_u64_u32 v[8:9], s[6:7], v8, s75, v[6:7]
	global_load_dword v40, v[8:9], off nt
	v_or_b32_e32 v8, 52, v15
	v_mad_u64_u32 v[8:9], s[6:7], v8, s75, v[6:7]
	global_load_dword v41, v[8:9], off nt
	v_or_b32_e32 v8, 54, v15
	v_mad_u64_u32 v[8:9], s[6:7], v8, s75, v[6:7]
	global_load_dword v42, v[8:9], off nt
	v_or_b32_e32 v8, 56, v15
	v_mad_u64_u32 v[8:9], s[6:7], v8, s75, v[6:7]
	global_load_dword v43, v[8:9], off nt
	v_or_b32_e32 v8, 58, v15
	v_mad_u64_u32 v[8:9], s[6:7], v8, s75, v[6:7]
	global_load_dword v44, v[8:9], off nt
	v_or_b32_e32 v8, 60, v15
	v_mad_u64_u32 v[8:9], s[6:7], v8, s75, v[6:7]
	global_load_dword v8, v[8:9], off nt
	v_or_b32_e32 v9, 62, v15
	v_mad_u64_u32 v[6:7], s[6:7], v9, s75, v[6:7]
	global_load_dword v6, v[6:7], off nt
	s_waitcnt vmcnt(0)
; #define LAS __attribute__((address_space(3)))
; __device__ __forceinline__ unsigned pk_bf16(float lo, float hi) { f32x2 v = {lo, hi}; bf16x2_t b = __builtin_convertvector(v, bf16x2_t); return __builtin_bit_cast(unsigned, b); }
; #define LDS_WAIT() asm volatile("s_waitcnt lgkmcnt(0)" ::: "memory")
; __device__ __forceinline__ void transpose_item(const float* __restrict__ W, int ldw, int src_col0, bf16_t* WT, int K, int dst_row0, int k0, LAS float* scr, int lane) {
;     ...
; #pragma unroll
;     for (int i = 0; i < 32; ++i) scr[(2 * i + (lane >> 5)) * 33 + (lane & 31)] = tmp[i];
;     LDS_WAIT();
;     const int c = lane & 7;
; #pragma unroll
;     for (int j = 0; j < 4; ++j) { const int n = (lane >> 3) + 8 * j; const LAS float* s = scr + (8 * c) * 33 + n;
;         u32x4 o; o.x = pk_bf16(s[0 * 33], s[1 * 33]); o.y = pk_bf16(s[2 * 33], s[3 * 33]); o.z = pk_bf16(s[4 * 33], s[5 * 33]); o.w = pk_bf16(s[6 * 33], s[7 * 33]);
;         *(u32x4*)(WT + (size_t)(dst_row0 + n) * K + k0 + 8 * c) = o; }
; __device__ __forceinline__ void convert_item(ArgsP a, const Ctx& c, int it, LAS float* scr) {
;     ...
;         if (r < I_SQ) { const int kb = r / 64, nb = r % 64, row0 = 32 * nb; const int sc = row0 < 768 ? W_DV + row0 : (row0 < 1280 ? W_GV + (row0 - 768) : W_MV + (row0 - 1280));
;             transpose_item(a->in[3] + (size_t)l * DM * DIN, DIN, sc, (bf16_t*)(wl + WL_V), DM, row0, 64 * kb, scr, c.lane); return; }
	ds_write2_b32 v5, v0, v16 offset1:66
	ds_write2_b32 v5, v17, v18 offset0:132 offset1:198
	v_add_u32_e32 v0, 0x400, v5
	ds_write2_b32 v0, v19, v20 offset0:8 offset1:74
	ds_write2_b32 v0, v21, v22 offset0:140 offset1:206
	v_add_u32_e32 v0, 0x800, v5
	ds_write2_b32 v0, v23, v24 offset0:16 offset1:82
	ds_write2_b32 v0, v25, v26 offset0:148 offset1:214
	v_add_u32_e32 v0, 0xc00, v5
	ds_write2_b32 v0, v27, v28 offset0:24 offset1:90
	ds_write2_b32 v0, v29, v30 offset0:156 offset1:222
	v_add_u32_e32 v0, 0x1000, v5
	ds_write2_b32 v0, v31, v32 offset0:32 offset1:98
	ds_write2_b32 v0, v33, v34 offset0:164 offset1:230
	v_add_u32_e32 v0, 0x1400, v5
	ds_write2_b32 v0, v35, v36 offset0:40 offset1:106
	ds_write2_b32 v0, v37, v38 offset0:172 offset1:238
	v_add_u32_e32 v0, 0x1800, v5
	ds_write2_b32 v0, v39, v40 offset0:48 offset1:114
	ds_write2_b32 v0, v41, v42 offset0:180 offset1:246
	v_add_u32_e32 v0, 0x1c00, v5
	ds_write2_b32 v0, v43, v44 offset0:56 offset1:122
	ds_write2_b32 v0, v8, v6 offset0:188 offset1:254
	s_mov_b32 s5, s61
	s_waitcnt lgkmcnt(0)
	s_lshl_b64 s[4:5], s[4:5], 1
	s_add_u32 s4, s15, s4
	ds_read2_b32 v[18:19], v11 offset0:33 offset1:41
	ds_read2_b32 v[20:21], v11 offset1:8
	ds_read2_b32 v[22:23], v11 offset0:66 offset1:74
	ds_read2_b32 v[24:25], v11 offset0:99 offset1:107
	ds_read2_b32 v[26:27], v11 offset0:132 offset1:140
	ds_read2_b32 v[28:29], v11 offset0:165 offset1:173
	ds_read2_b32 v[30:31], v11 offset0:198 offset1:206
	ds_read2_b32 v[32:33], v11 offset0:231 offset1:239
	s_addc_u32 s5, s16, s5
	v_lshlrev_b32_e32 v0, 1, v4
	v_lshl_add_u64 v[6:7], s[4:5], 0, v[0:1]
	s_mov_b64 s[4:5], 0x5200000
	v_or_b32_e32 v0, s3, v10
	v_lshl_add_u64 v[16:17], v[6:7], 0, s[4:5]
	v_lshlrev_b32_e32 v0, 12, v0
	v_lshl_add_u64 v[34:35], v[16:17], 0, v[0:1]
	v_or_b32_e32 v0, s3, v12
	s_waitcnt lgkmcnt(6)
	v_cvt_pk_bf16_f32 v6, v20, v18
	s_waitcnt lgkmcnt(4)
	v_cvt_pk_bf16_f32 v7, v22, v24
	s_waitcnt lgkmcnt(2)
	v_cvt_pk_bf16_f32 v8, v26, v28
	s_waitcnt lgkmcnt(0)
	v_cvt_pk_bf16_f32 v9, v30, v32
	v_lshlrev_b32_e32 v0, 12, v0
	global_store_dwordx4 v[34:35], v[6:9], off sc1
	s_nop 1
	v_cvt_pk_bf16_f32 v6, v21, v19
	v_cvt_pk_bf16_f32 v7, v23, v25
	v_cvt_pk_bf16_f32 v8, v27, v29
	v_cvt_pk_bf16_f32 v9, v31, v33
	v_lshl_add_u64 v[18:19], v[16:17], 0, v[0:1]
	global_store_dwordx4 v[18:19], v[6:9], off sc1
	ds_read2_b32 v[18:19], v11 offset0:49 offset1:57
	ds_read2_b32 v[20:21], v11 offset0:16 offset1:24
	ds_read2_b32 v[22:23], v11 offset0:82 offset1:90
	ds_read2_b32 v[24:25], v11 offset0:115 offset1:123
	ds_read2_b32 v[26:27], v11 offset0:148 offset1:156
	ds_read2_b32 v[28:29], v11 offset0:181 offset1:189
	ds_read2_b32 v[30:31], v11 offset0:214 offset1:222
	ds_read2_b32 v[32:33], v11 offset0:247 offset1:255
	v_or_b32_e32 v0, s3, v13
	v_lshlrev_b32_e32 v0, 12, v0
	v_lshl_add_u64 v[34:35], v[16:17], 0, v[0:1]
	v_or_b32_e32 v0, s3, v14
	s_waitcnt lgkmcnt(6)
	v_cvt_pk_bf16_f32 v6, v20, v18
	s_waitcnt lgkmcnt(4)
	v_cvt_pk_bf16_f32 v7, v22, v24
	s_waitcnt lgkmcnt(2)
	v_cvt_pk_bf16_f32 v8, v26, v28
	s_waitcnt lgkmcnt(0)
	v_cvt_pk_bf16_f32 v9, v30, v32
	v_lshlrev_b32_e32 v0, 12, v0
	global_store_dwordx4 v[34:35], v[6:9], off sc1
	v_lshl_add_u64 v[16:17], v[16:17], 0, v[0:1]
	s_nop 0
	v_cvt_pk_bf16_f32 v6, v21, v19
	v_cvt_pk_bf16_f32 v7, v23, v25
	v_cvt_pk_bf16_f32 v8, v27, v29
	v_cvt_pk_bf16_f32 v9, v31, v33
	global_store_dwordx4 v[16:17], v[6:9], off sc1
	s_waitcnt lgkmcnt(0)

; __device__ __forceinline__ void transpose_item(const float* __restrict__ W, int ldw, int src_col0, bf16_t* WT, int K, int dst_row0, int k0, LAS float* scr, int lane) {
;     ...
;     for (int i = 0; i < 32; ++i) tmp[i] = __builtin_nontemporal_load(W + (size_t)(k0 + 2 * i + (lane >> 5)) * ldw + src_col0 + (lane & 31));
; __device__ __forceinline__ int win_src_col(int gidx) {
;     const int pn = gidx >> 3, w = gidx & 7;
;     if (pn < 6) { const int g = pn / 3, tg = pn % 3, half = w >> 2, u = w & 3; return (g ? W_DK : W_DQ) + (tg * 4 + u) * 64 + half * 32; }
;     if (pn < 12) { const int pp = pn - 6, g = pp / 3, tg = pp % 3, half = w >> 2, ww = w & 3; return (g ? W_MK : W_MQ) + (tg * 2 + (ww >> 1)) * 128 + half * 64 + (ww & 1) * 32; }
;     if (pn == 12) return W_GQ + 32 * w;
;     if (pn == 13) return W_GK + 32 * w;
;     return W_GR + (pn - 14) * 256 + 32 * w;
; }
; __device__ __forceinline__ void convert_item(ArgsP a, const Ctx& c, int it, LAS float* scr) {
;     ...
;         if (r < I_IN) { const int kb = r / 128, gidx = r % 128;
;             transpose_item(a->in[3] + (size_t)l * DM * DIN, DIN, win_src_col(gidx), (bf16_t*)(wl + WL_IN), DM, 32 * gidx, 64 * kb, scr, c.lane); return; }
.LBB0_525:
	s_add_i32 s5, s17, 0xffff7c00
	s_mul_i32 s9, s2, 0x3020000
	s_mul_hi_i32 s8, s2, 0x3020000
	s_waitcnt lgkmcnt(0)
	s_add_u32 s9, s6, s9
	s_addc_u32 s7, s7, s8
	s_lshr_b32 s5, s5, 1
	s_and_b32 s6, s5, 0x7fffffc0
	s_ashr_i32 s5, s4, 31
	s_lshl_b32 s3, s3, 5
	s_lshl_b64 s[4:5], s[4:5], 2
	s_add_u32 s4, s9, s4
	s_addc_u32 s5, s7, s5
	v_lshlrev_b32_e32 v0, 2, v2
	v_or_b32_e32 v15, s6, v3
	v_lshl_add_u64 v[6:7], s[4:5], 0, v[0:1]
	v_mad_u64_u32 v[8:9], s[4:5], v15, s75, v[6:7]
	global_load_dword v0, v[8:9], off nt
	v_or_b32_e32 v8, 2, v15
	v_mad_u64_u32 v[8:9], s[4:5], v8, s75, v[6:7]
	global_load_dword v16, v[8:9], off nt
	v_or_b32_e32 v8, 4, v15
	v_mad_u64_u32 v[8:9], s[4:5], v8, s75, v[6:7]
	global_load_dword v17, v[8:9], off nt
	v_or_b32_e32 v8, 6, v15
	v_mad_u64_u32 v[8:9], s[4:5], v8, s75, v[6:7]
	global_load_dword v18, v[8:9], off nt
	v_or_b32_e32 v8, 8, v15
	v_mad_u64_u32 v[8:9], s[4:5], v8, s75, v[6:7]
	global_load_dword v19, v[8:9], off nt
	v_or_b32_e32 v8, 10, v15
	v_mad_u64_u32 v[8:9], s[4:5], v8, s75, v[6:7]
	global_load_dword v20, v[8:9], off nt
	v_or_b32_e32 v8, 12, v15
	v_mad_u64_u32 v[8:9], s[4:5], v8, s75, v[6:7]
	global_load_dword v21, v[8:9], off nt
	v_or_b32_e32 v8, 14, v15
	v_mad_u64_u32 v[8:9], s[4:5], v8, s75, v[6:7]
	global_load_dword v22, v[8:9], off nt
	v_or_b32_e32 v8, 16, v15
	v_mad_u64_u32 v[8:9], s[4:5], v8, s75, v[6:7]
	global_load_dword v23, v[8:9], off nt
	v_or_b32_e32 v8, 18, v15
	v_mad_u64_u32 v[8:9], s[4:5], v8, s75, v[6:7]
	global_load_dword v24, v[8:9], off nt
	v_or_b32_e32 v8, 20, v15
	v_mad_u64_u32 v[8:9], s[4:5], v8, s75, v[6:7]
	global_load_dword v25, v[8:9], off nt
	v_or_b32_e32 v8, 22, v15
	v_mad_u64_u32 v[8:9], s[4:5], v8, s75, v[6:7]
	global_load_dword v26, v[8:9], off nt
	v_or_b32_e32 v8, 24, v15
	v_mad_u64_u32 v[8:9], s[4:5], v8, s75, v[6:7]
	global_load_dword v27, v[8:9], off nt
	v_or_b32_e32 v8, 26, v15
	v_mad_u64_u32 v[8:9], s[4:5], v8, s75, v[6:7]
	global_load_dword v28, v[8:9], off nt
	v_or_b32_e32 v8, 28, v15
	v_mad_u64_u32 v[8:9], s[4:5], v8, s75, v[6:7]
	global_load_dword v29, v[8:9], off nt
	v_or_b32_e32 v8, 30, v15
	v_mad_u64_u32 v[8:9], s[4:5], v8, s75, v[6:7]
	global_load_dword v30, v[8:9], off nt
	v_or_b32_e32 v8, 32, v15
	v_mad_u64_u32 v[8:9], s[4:5], v8, s75, v[6:7]
	global_load_dword v31, v[8:9], off nt
	v_or_b32_e32 v8, 34, v15
	v_mad_u64_u32 v[8:9], s[4:5], v8, s75, v[6:7]
	global_load_dword v32, v[8:9], off nt
	v_or_b32_e32 v8, 36, v15
	v_mad_u64_u32 v[8:9], s[4:5], v8, s75, v[6:7]
	global_load_dword v33, v[8:9], off nt
	v_or_b32_e32 v8, 38, v15
	v_mad_u64_u32 v[8:9], s[4:5], v8, s75, v[6:7]
	global_load_dword v34, v[8:9], off nt
	v_or_b32_e32 v8, 40, v15
	v_mad_u64_u32 v[8:9], s[4:5], v8, s75, v[6:7]
	global_load_dword v35, v[8:9], off nt
	v_or_b32_e32 v8, 42, v15
	v_mad_u64_u32 v[8:9], s[4:5], v8, s75, v[6:7]
	global_load_dword v36, v[8:9], off nt
	v_or_b32_e32 v8, 44, v15
	v_mad_u64_u32 v[8:9], s[4:5], v8, s75, v[6:7]
	global_load_dword v37, v[8:9], off nt
	v_or_b32_e32 v8, 46, v15
	v_mad_u64_u32 v[8:9], s[4:5], v8, s75, v[6:7]
	global_load_dword v38, v[8:9], off nt
	v_or_b32_e32 v8, 48, v15
	v_mad_u64_u32 v[8:9], s[4:5], v8, s75, v[6:7]
	global_load_dword v39, v[8:9], off nt
	v_or_b32_e32 v8, 50, v15
	v_mad_u64_u32 v[8:9], s[4:5], v8, s75, v[6:7]
	global_load_dword v40, v[8:9], off nt
	v_or_b32_e32 v8, 52, v15
	v_mad_u64_u32 v[8:9], s[4:5], v8, s75, v[6:7]
	global_load_dword v41, v[8:9], off nt
	v_or_b32_e32 v8, 54, v15
	v_mad_u64_u32 v[8:9], s[4:5], v8, s75, v[6:7]
	global_load_dword v42, v[8:9], off nt
	v_or_b32_e32 v8, 56, v15
	v_mad_u64_u32 v[8:9], s[4:5], v8, s75, v[6:7]
	global_load_dword v43, v[8:9], off nt
	v_or_b32_e32 v8, 58, v15
	v_mad_u64_u32 v[8:9], s[4:5], v8, s75, v[6:7]
	global_load_dword v44, v[8:9], off nt
	v_or_b32_e32 v8, 60, v15
	v_mad_u64_u32 v[8:9], s[4:5], v8, s75, v[6:7]
	global_load_dword v8, v[8:9], off nt
	v_or_b32_e32 v9, 62, v15
	v_mad_u64_u32 v[6:7], s[4:5], v9, s75, v[6:7]
	global_load_dword v6, v[6:7], off nt
	s_waitcnt vmcnt(0)
; #define LAS __attribute__((address_space(3)))
; __device__ __forceinline__ unsigned pk_bf16(float lo, float hi) { f32x2 v = {lo, hi}; bf16x2_t b = __builtin_convertvector(v, bf16x2_t); return __builtin_bit_cast(unsigned, b); }
; #define LDS_WAIT() asm volatile("s_waitcnt lgkmcnt(0)" ::: "memory")
; __device__ __forceinline__ void transpose_item(const float* __restrict__ W, int ldw, int src_col0, bf16_t* WT, int K, int dst_row0, int k0, LAS float* scr, int lane) {
;     ...
; #pragma unroll
;     for (int i = 0; i < 32; ++i) scr[(2 * i + (lane >> 5)) * 33 + (lane & 31)] = tmp[i];
;     LDS_WAIT();
;     const int c = lane & 7;
; #pragma unroll
;     for (int j = 0; j < 4; ++j) { const int n = (lane >> 3) + 8 * j; const LAS float* s = scr + (8 * c) * 33 + n;
;         u32x4 o; o.x = pk_bf16(s[0 * 33], s[1 * 33]); o.y = pk_bf16(s[2 * 33], s[3 * 33]); o.z = pk_bf16(s[4 * 33], s[5 * 33]); o.w = pk_bf16(s[6 * 33], s[7 * 33]);
;         *(u32x4*)(WT + (size_t)(dst_row0 + n) * K + k0 + 8 * c) = o; }
; __device__ __forceinline__ void convert_item(ArgsP a, const Ctx& c, int it, LAS float* scr) {
;     ...
;         if (r < I_IN) { const int kb = r / 128, gidx = r % 128;
;             transpose_item(a->in[3] + (size_t)l * DM * DIN, DIN, win_src_col(gidx), (bf16_t*)(wl + WL_IN), DM, 32 * gidx, 64 * kb, scr, c.lane); return; }
	ds_write2_b32 v5, v0, v16 offset1:66
	ds_write2_b32 v5, v17, v18 offset0:132 offset1:198
	v_add_u32_e32 v0, 0x400, v5
	ds_write2_b32 v0, v19, v20 offset0:8 offset1:74
	ds_write2_b32 v0, v21, v22 offset0:140 offset1:206
	v_add_u32_e32 v0, 0x800, v5
	ds_write2_b32 v0, v23, v24 offset0:16 offset1:82
	ds_write2_b32 v0, v25, v26 offset0:148 offset1:214
	v_add_u32_e32 v0, 0xc00, v5
	ds_write2_b32 v0, v27, v28 offset0:24 offset1:90
	ds_write2_b32 v0, v29, v30 offset0:156 offset1:222
	v_add_u32_e32 v0, 0x1000, v5
	ds_write2_b32 v0, v31, v32 offset0:32 offset1:98
	ds_write2_b32 v0, v33, v34 offset0:164 offset1:230
	v_add_u32_e32 v0, 0x1400, v5
	ds_write2_b32 v0, v35, v36 offset0:40 offset1:106
	ds_write2_b32 v0, v37, v38 offset0:172 offset1:238
	v_add_u32_e32 v0, 0x1800, v5
	ds_write2_b32 v0, v39, v40 offset0:48 offset1:114
	ds_write2_b32 v0, v41, v42 offset0:180 offset1:246
	v_add_u32_e32 v0, 0x1c00, v5
	ds_write2_b32 v0, v43, v44 offset0:56 offset1:122
	ds_write2_b32 v0, v8, v6 offset0:188 offset1:254
	s_waitcnt lgkmcnt(0)
	s_lshl_b32 s4, s6, 1
	s_add_u32 s4, s15, s4
	ds_read2_b32 v[18:19], v11 offset0:33 offset1:41
	ds_read2_b32 v[20:21], v11 offset1:8
	ds_read2_b32 v[22:23], v11 offset0:66 offset1:74
	ds_read2_b32 v[24:25], v11 offset0:99 offset1:107
	ds_read2_b32 v[26:27], v11 offset0:132 offset1:140
	ds_read2_b32 v[28:29], v11 offset0:165 offset1:173
	ds_read2_b32 v[30:31], v11 offset0:198 offset1:206
	ds_read2_b32 v[32:33], v11 offset0:231 offset1:239
	s_addc_u32 s5, s16, 0
	v_lshlrev_b32_e32 v0, 1, v4
	v_lshl_add_u64 v[6:7], s[4:5], 0, v[0:1]
	s_mov_b64 s[4:5], 0x4200000
	v_or_b32_e32 v0, s3, v10
	v_lshl_add_u64 v[16:17], v[6:7], 0, s[4:5]
	v_lshlrev_b32_e32 v0, 12, v0
	v_lshl_add_u64 v[34:35], v[16:17], 0, v[0:1]
	v_or_b32_e32 v0, s3, v12
	s_waitcnt lgkmcnt(6)
	v_cvt_pk_bf16_f32 v6, v20, v18
	s_waitcnt lgkmcnt(4)
	v_cvt_pk_bf16_f32 v7, v22, v24
	s_waitcnt lgkmcnt(2)
	v_cvt_pk_bf16_f32 v8, v26, v28
	s_waitcnt lgkmcnt(0)
	v_cvt_pk_bf16_f32 v9, v30, v32
	v_lshlrev_b32_e32 v0, 12, v0
	global_store_dwordx4 v[34:35], v[6:9], off sc1
	s_nop 1
	v_cvt_pk_bf16_f32 v6, v21, v19
	v_cvt_pk_bf16_f32 v7, v23, v25
	v_cvt_pk_bf16_f32 v8, v27, v29
	v_cvt_pk_bf16_f32 v9, v31, v33
	v_lshl_add_u64 v[18:19], v[16:17], 0, v[0:1]
	global_store_dwordx4 v[18:19], v[6:9], off sc1
	ds_read2_b32 v[18:19], v11 offset0:49 offset1:57
	ds_read2_b32 v[20:21], v11 offset0:16 offset1:24
	ds_read2_b32 v[22:23], v11 offset0:82 offset1:90
	ds_read2_b32 v[24:25], v11 offset0:115 offset1:123
	ds_read2_b32 v[26:27], v11 offset0:148 offset1:156
	ds_read2_b32 v[28:29], v11 offset0:181 offset1:189
	ds_read2_b32 v[30:31], v11 offset0:214 offset1:222
	ds_read2_b32 v[32:33], v11 offset0:247 offset1:255
	v_or_b32_e32 v0, s3, v13
	v_lshlrev_b32_e32 v0, 12, v0
	v_lshl_add_u64 v[34:35], v[16:17], 0, v[0:1]
	v_or_b32_e32 v0, s3, v14
	s_waitcnt lgkmcnt(6)
	v_cvt_pk_bf16_f32 v6, v20, v18
	s_waitcnt lgkmcnt(4)
	v_cvt_pk_bf16_f32 v7, v22, v24
	s_waitcnt lgkmcnt(2)
	v_cvt_pk_bf16_f32 v8, v26, v28
	s_waitcnt lgkmcnt(0)
	v_cvt_pk_bf16_f32 v9, v30, v32
	v_lshlrev_b32_e32 v0, 12, v0
	global_store_dwordx4 v[34:35], v[6:9], off sc1
	v_lshl_add_u64 v[16:17], v[16:17], 0, v[0:1]
	s_nop 0
	v_cvt_pk_bf16_f32 v6, v21, v19
	v_cvt_pk_bf16_f32 v7, v23, v25
	v_cvt_pk_bf16_f32 v8, v27, v29
	v_cvt_pk_bf16_f32 v9, v31, v33
	global_store_dwordx4 v[16:17], v[6:9], off sc1
	s_waitcnt lgkmcnt(0)

; __device__ __forceinline__ void transpose_item(const float* __restrict__ W, int ldw, int src_col0, bf16_t* WT, int K, int dst_row0, int k0, LAS float* scr, int lane) {
;     ...
;     for (int i = 0; i < 32; ++i) tmp[i] = __builtin_nontemporal_load(W + (size_t)(k0 + 2 * i + (lane >> 5)) * ldw + src_col0 + (lane & 31));
; __device__ __forceinline__ void convert_item(ArgsP a, const Ctx& c, int it, LAS float* scr) {
;     ...
;         if (r < 2 * I_D) { const int second = r >= I_D; if (second) r -= I_D; const int kb = r / 64, nb = r % 64;
;             transpose_item(a->in[second ? 15 : 12] + (size_t)l * FF * DM, DM, 32 * nb, (bf16_t*)(wl + (second ? WL_D2 : WL_D1)), FF, 32 * nb, 64 * kb, scr, c.lane); return; }
.LBB0_527:
	s_andn2_b64 vcc, exec, s[4:5]
	s_cbranch_vccnz .LBB0_529
	s_cmpk_gt_u32 s17, 0x6dff
	s_cselect_b64 s[4:5], -1, 0
	s_and_b64 s[4:5], s[4:5], exec
	s_cselect_b32 s4, s70, 0xffffa800
	s_cselect_b32 s6, 0x8e00000, s92
	s_cselect_b32 s3, s65, 0x60
	s_add_i32 s7, s4, s17
	s_and_b32 s60, s7, 0xffffffc0
	s_add_u32 s4, s0, s3
	s_addc_u32 s5, s1, 0
	s_load_dwordx2 s[4:5], s[4:5], 0x0
	s_mul_i32 s8, s2, 0x2c00000
	s_mul_hi_i32 s3, s2, 0x2c00000
	v_or_b32_e32 v6, s60, v3
	v_lshlrev_b32_e32 v0, 2, v2
	s_waitcnt lgkmcnt(0)
	s_add_u32 s8, s4, s8
	s_addc_u32 s9, s5, s3
	s_lshl_b32 s3, s7, 5
	s_and_b32 s3, s3, 0x7e0
	s_add_u32 s4, s15, s6
	s_addc_u32 s5, s16, 0
	s_lshl_b32 s6, s3, 2
	s_add_u32 s6, s8, s6
	s_addc_u32 s7, s9, 0
	v_ashrrev_i32_e32 v7, 31, v6
	v_lshl_add_u64 v[8:9], s[6:7], 0, v[0:1]
	v_lshlrev_b64 v[16:17], 13, v[6:7]
	v_lshl_add_u64 v[16:17], v[8:9], 0, v[16:17]
	global_load_dword v0, v[16:17], off nt
	v_or_b32_e32 v16, 2, v6
	v_ashrrev_i32_e32 v17, 31, v16
	v_lshlrev_b64 v[16:17], 13, v[16:17]
	v_lshl_add_u64 v[16:17], v[8:9], 0, v[16:17]
	global_load_dword v15, v[16:17], off nt
	v_or_b32_e32 v16, 4, v6
	v_ashrrev_i32_e32 v17, 31, v16
	v_lshlrev_b64 v[16:17], 13, v[16:17]
	v_lshl_add_u64 v[16:17], v[8:9], 0, v[16:17]
	global_load_dword v18, v[16:17], off nt
	v_or_b32_e32 v16, 6, v6
	v_ashrrev_i32_e32 v17, 31, v16
	v_lshlrev_b64 v[16:17], 13, v[16:17]
	v_lshl_add_u64 v[16:17], v[8:9], 0, v[16:17]
	global_load_dword v19, v[16:17], off nt
	v_or_b32_e32 v16, 8, v6
	v_ashrrev_i32_e32 v17, 31, v16
	v_lshlrev_b64 v[16:17], 13, v[16:17]
	v_lshl_add_u64 v[16:17], v[8:9], 0, v[16:17]
	global_load_dword v20, v[16:17], off nt
	v_or_b32_e32 v16, 10, v6
	v_ashrrev_i32_e32 v17, 31, v16
	v_lshlrev_b64 v[16:17], 13, v[16:17]
	v_lshl_add_u64 v[16:17], v[8:9], 0, v[16:17]
	global_load_dword v21, v[16:17], off nt
	v_or_b32_e32 v16, 12, v6
	v_ashrrev_i32_e32 v17, 31, v16
	v_lshlrev_b64 v[16:17], 13, v[16:17]
	v_lshl_add_u64 v[16:17], v[8:9], 0, v[16:17]
	global_load_dword v22, v[16:17], off nt
	v_or_b32_e32 v16, 14, v6
	v_ashrrev_i32_e32 v17, 31, v16
	v_lshlrev_b64 v[16:17], 13, v[16:17]
	v_lshl_add_u64 v[16:17], v[8:9], 0, v[16:17]
	global_load_dword v23, v[16:17], off nt
	v_or_b32_e32 v16, 16, v6
	v_ashrrev_i32_e32 v17, 31, v16
	v_lshlrev_b64 v[16:17], 13, v[16:17]
	v_lshl_add_u64 v[16:17], v[8:9], 0, v[16:17]
	global_load_dword v24, v[16:17], off nt
	v_or_b32_e32 v16, 18, v6
	v_ashrrev_i32_e32 v17, 31, v16
	v_lshlrev_b64 v[16:17], 13, v[16:17]
	v_lshl_add_u64 v[16:17], v[8:9], 0, v[16:17]
	global_load_dword v25, v[16:17], off nt
	v_or_b32_e32 v16, 20, v6
	v_ashrrev_i32_e32 v17, 31, v16
	v_lshlrev_b64 v[16:17], 13, v[16:17]
	v_lshl_add_u64 v[16:17], v[8:9], 0, v[16:17]
	global_load_dword v26, v[16:17], off nt
	v_or_b32_e32 v16, 22, v6
	v_ashrrev_i32_e32 v17, 31, v16
	v_lshlrev_b64 v[16:17], 13, v[16:17]
	v_lshl_add_u64 v[16:17], v[8:9], 0, v[16:17]
	global_load_dword v27, v[16:17], off nt
	v_or_b32_e32 v16, 24, v6
	v_ashrrev_i32_e32 v17, 31, v16
	v_lshlrev_b64 v[16:17], 13, v[16:17]
	v_lshl_add_u64 v[16:17], v[8:9], 0, v[16:17]
	global_load_dword v28, v[16:17], off nt
	v_or_b32_e32 v16, 26, v6
	v_ashrrev_i32_e32 v17, 31, v16
	v_lshlrev_b64 v[16:17], 13, v[16:17]
	v_lshl_add_u64 v[16:17], v[8:9], 0, v[16:17]
	global_load_dword v29, v[16:17], off nt
	v_or_b32_e32 v16, 28, v6
	v_ashrrev_i32_e32 v17, 31, v16
	v_lshlrev_b64 v[16:17], 13, v[16:17]
	v_lshl_add_u64 v[16:17], v[8:9], 0, v[16:17]
	global_load_dword v30, v[16:17], off nt
	v_or_b32_e32 v16, 30, v6
	v_ashrrev_i32_e32 v17, 31, v16
	v_lshlrev_b64 v[16:17], 13, v[16:17]
	v_lshl_add_u64 v[16:17], v[8:9], 0, v[16:17]
	global_load_dword v31, v[16:17], off nt
	v_or_b32_e32 v16, 32, v6
	v_ashrrev_i32_e32 v17, 31, v16
	v_lshlrev_b64 v[16:17], 13, v[16:17]
	v_lshl_add_u64 v[16:17], v[8:9], 0, v[16:17]
	global_load_dword v32, v[16:17], off nt
	v_or_b32_e32 v16, 34, v6
	v_ashrrev_i32_e32 v17, 31, v16
	v_lshlrev_b64 v[16:17], 13, v[16:17]
	v_lshl_add_u64 v[16:17], v[8:9], 0, v[16:17]
	global_load_dword v33, v[16:17], off nt
	v_or_b32_e32 v16, 36, v6
	v_ashrrev_i32_e32 v17, 31, v16
	v_lshlrev_b64 v[16:17], 13, v[16:17]
	v_lshl_add_u64 v[16:17], v[8:9], 0, v[16:17]
	global_load_dword v34, v[16:17], off nt
	v_or_b32_e32 v16, 38, v6
	v_ashrrev_i32_e32 v17, 31, v16
	v_lshlrev_b64 v[16:17], 13, v[16:17]
	v_lshl_add_u64 v[16:17], v[8:9], 0, v[16:17]
	global_load_dword v35, v[16:17], off nt
	v_or_b32_e32 v16, 40, v6
	v_ashrrev_i32_e32 v17, 31, v16
	v_lshlrev_b64 v[16:17], 13, v[16:17]
	v_lshl_add_u64 v[16:17], v[8:9], 0, v[16:17]
	global_load_dword v36, v[16:17], off nt
	v_or_b32_e32 v16, 42, v6
	v_ashrrev_i32_e32 v17, 31, v16
	v_lshlrev_b64 v[16:17], 13, v[16:17]
	v_lshl_add_u64 v[16:17], v[8:9], 0, v[16:17]
	global_load_dword v37, v[16:17], off nt
	v_or_b32_e32 v16, 44, v6
	v_ashrrev_i32_e32 v17, 31, v16
	v_lshlrev_b64 v[16:17], 13, v[16:17]
	v_lshl_add_u64 v[16:17], v[8:9], 0, v[16:17]
	global_load_dword v38, v[16:17], off nt
	v_or_b32_e32 v16, 46, v6
	v_ashrrev_i32_e32 v17, 31, v16
	v_lshlrev_b64 v[16:17], 13, v[16:17]
	v_lshl_add_u64 v[16:17], v[8:9], 0, v[16:17]
	global_load_dword v39, v[16:17], off nt
	v_or_b32_e32 v16, 48, v6
	v_ashrrev_i32_e32 v17, 31, v16
	v_lshlrev_b64 v[16:17], 13, v[16:17]
	v_lshl_add_u64 v[16:17], v[8:9], 0, v[16:17]
	global_load_dword v40, v[16:17], off nt
	v_or_b32_e32 v16, 50, v6
	v_ashrrev_i32_e32 v17, 31, v16
	v_lshlrev_b64 v[16:17], 13, v[16:17]
	v_lshl_add_u64 v[16:17], v[8:9], 0, v[16:17]
	global_load_dword v41, v[16:17], off nt
	v_or_b32_e32 v16, 52, v6
	v_ashrrev_i32_e32 v17, 31, v16
	v_lshlrev_b64 v[16:17], 13, v[16:17]
	v_lshl_add_u64 v[16:17], v[8:9], 0, v[16:17]
	global_load_dword v42, v[16:17], off nt
	v_or_b32_e32 v16, 54, v6
	v_ashrrev_i32_e32 v17, 31, v16
	v_lshlrev_b64 v[16:17], 13, v[16:17]
	v_lshl_add_u64 v[16:17], v[8:9], 0, v[16:17]
	global_load_dword v43, v[16:17], off nt
	v_or_b32_e32 v16, 56, v6
	v_ashrrev_i32_e32 v17, 31, v16
	v_lshlrev_b64 v[16:17], 13, v[16:17]
	v_lshl_add_u64 v[16:17], v[8:9], 0, v[16:17]
	global_load_dword v44, v[16:17], off nt
	v_or_b32_e32 v16, 58, v6
	v_ashrrev_i32_e32 v17, 31, v16
	v_lshlrev_b64 v[16:17], 13, v[16:17]
	v_lshl_add_u64 v[16:17], v[8:9], 0, v[16:17]
	global_load_dword v45, v[16:17], off nt
	v_or_b32_e32 v16, 60, v6
	v_or_b32_e32 v6, 62, v6
	v_ashrrev_i32_e32 v17, 31, v16
	v_ashrrev_i32_e32 v7, 31, v6
	v_lshlrev_b64 v[16:17], 13, v[16:17]
	v_lshlrev_b64 v[6:7], 13, v[6:7]
	v_lshl_add_u64 v[16:17], v[8:9], 0, v[16:17]
	v_lshl_add_u64 v[6:7], v[8:9], 0, v[6:7]
	global_load_dword v16, v[16:17], off nt
	s_lshl_b64 s[6:7], s[60:61], 1
	global_load_dword v6, v[6:7], off nt
	s_waitcnt vmcnt(0)
; #define LAS __attribute__((address_space(3)))
; __device__ __forceinline__ unsigned pk_bf16(float lo, float hi) { f32x2 v = {lo, hi}; bf16x2_t b = __builtin_convertvector(v, bf16x2_t); return __builtin_bit_cast(unsigned, b); }
; #define LDS_WAIT() asm volatile("s_waitcnt lgkmcnt(0)" ::: "memory")
; __device__ __forceinline__ void transpose_item(const float* __restrict__ W, int ldw, int src_col0, bf16_t* WT, int K, int dst_row0, int k0, LAS float* scr, int lane) {
;     ...
; #pragma unroll
;     for (int i = 0; i < 32; ++i) scr[(2 * i + (lane >> 5)) * 33 + (lane & 31)] = tmp[i];
;     LDS_WAIT();
;     const int c = lane & 7;
; #pragma unroll
;     for (int j = 0; j < 4; ++j) { const int n = (lane >> 3) + 8 * j; const LAS float* s = scr + (8 * c) * 33 + n;
;         u32x4 o; o.x = pk_bf16(s[0 * 33], s[1 * 33]); o.y = pk_bf16(s[2 * 33], s[3 * 33]); o.z = pk_bf16(s[4 * 33], s[5 * 33]); o.w = pk_bf16(s[6 * 33], s[7 * 33]);
;         *(u32x4*)(WT + (size_t)(dst_row0 + n) * K + k0 + 8 * c) = o; }
; __device__ __forceinline__ void convert_item(ArgsP a, const Ctx& c, int it, LAS float* scr) {
;     ...
;         if (r < 2 * I_D) { const int second = r >= I_D; if (second) r -= I_D; const int kb = r / 64, nb = r % 64;
;             transpose_item(a->in[second ? 15 : 12] + (size_t)l * FF * DM, DM, 32 * nb, (bf16_t*)(wl + (second ? WL_D2 : WL_D1)), FF, 32 * nb, 64 * kb, scr, c.lane); return; }
	ds_write2_b32 v5, v0, v15 offset1:66
	ds_write2_b32 v5, v18, v19 offset0:132 offset1:198
	v_add_u32_e32 v0, 0x400, v5
	ds_write2_b32 v0, v20, v21 offset0:8 offset1:74
	ds_write2_b32 v0, v22, v23 offset0:140 offset1:206
	v_add_u32_e32 v0, 0x800, v5
	ds_write2_b32 v0, v24, v25 offset0:16 offset1:82
	ds_write2_b32 v0, v26, v27 offset0:148 offset1:214
	v_add_u32_e32 v0, 0xc00, v5
	ds_write2_b32 v0, v28, v29 offset0:24 offset1:90
	ds_write2_b32 v0, v30, v31 offset0:156 offset1:222
	v_add_u32_e32 v0, 0x1000, v5
	ds_write2_b32 v0, v32, v33 offset0:32 offset1:98
	ds_write2_b32 v0, v34, v35 offset0:164 offset1:230
	v_add_u32_e32 v0, 0x1400, v5
	ds_write2_b32 v0, v36, v37 offset0:40 offset1:106
	ds_write2_b32 v0, v38, v39 offset0:172 offset1:238
	v_add_u32_e32 v0, 0x1800, v5
	ds_write2_b32 v0, v40, v41 offset0:48 offset1:114
	ds_write2_b32 v0, v42, v43 offset0:180 offset1:246
	v_add_u32_e32 v0, 0x1c00, v5
	ds_write2_b32 v0, v44, v45 offset0:56 offset1:122
	ds_write2_b32 v0, v16, v6 offset0:188 offset1:254
	s_waitcnt lgkmcnt(0)
	s_add_u32 s4, s4, s6
	ds_read2_b32 v[18:19], v11 offset0:33 offset1:41
	ds_read2_b32 v[20:21], v11 offset1:8
	ds_read2_b32 v[22:23], v11 offset0:66 offset1:74
	ds_read2_b32 v[24:25], v11 offset0:99 offset1:107
	ds_read2_b32 v[26:27], v11 offset0:132 offset1:140
	ds_read2_b32 v[28:29], v11 offset0:165 offset1:173
	ds_read2_b32 v[30:31], v11 offset0:198 offset1:206
	ds_read2_b32 v[32:33], v11 offset0:231 offset1:239
	s_addc_u32 s5, s5, s7
	v_lshlrev_b32_e32 v0, 1, v4
	v_lshl_add_u64 v[16:17], s[4:5], 0, v[0:1]
	v_or_b32_e32 v0, s3, v10
	v_mul_u32_u24_e32 v0, 0x2c00, v0
	v_lshl_add_u64 v[34:35], v[16:17], 0, v[0:1]
	v_or_b32_e32 v0, s3, v12
	s_waitcnt lgkmcnt(6)
	v_cvt_pk_bf16_f32 v6, v20, v18
	s_waitcnt lgkmcnt(4)
	v_cvt_pk_bf16_f32 v7, v22, v24
	s_waitcnt lgkmcnt(2)
	v_cvt_pk_bf16_f32 v8, v26, v28
	s_waitcnt lgkmcnt(0)
	v_cvt_pk_bf16_f32 v9, v30, v32
	v_mul_u32_u24_e32 v0, 0x2c00, v0
	global_store_dwordx4 v[34:35], v[6:9], off sc1
	s_nop 1
	v_cvt_pk_bf16_f32 v6, v21, v19
	v_cvt_pk_bf16_f32 v7, v23, v25
	v_cvt_pk_bf16_f32 v8, v27, v29
	v_cvt_pk_bf16_f32 v9, v31, v33
	v_lshl_add_u64 v[18:19], v[16:17], 0, v[0:1]
	global_store_dwordx4 v[18:19], v[6:9], off sc1
	ds_read2_b32 v[18:19], v11 offset0:16 offset1:24
	ds_read2_b32 v[20:21], v11 offset0:49 offset1:57
	ds_read2_b32 v[22:23], v11 offset0:82 offset1:90
	ds_read2_b32 v[24:25], v11 offset0:115 offset1:123
	ds_read2_b32 v[26:27], v11 offset0:148 offset1:156
	ds_read2_b32 v[28:29], v11 offset0:181 offset1:189
	ds_read2_b32 v[30:31], v11 offset0:214 offset1:222
	ds_read2_b32 v[32:33], v11 offset0:247 offset1:255
	v_or_b32_e32 v0, s3, v13
	v_mul_u32_u24_e32 v0, 0x2c00, v0
	v_lshl_add_u64 v[34:35], v[16:17], 0, v[0:1]
	v_or_b32_e32 v0, s3, v14
	s_waitcnt lgkmcnt(6)
	v_cvt_pk_bf16_f32 v6, v18, v20
	s_waitcnt lgkmcnt(4)
	v_cvt_pk_bf16_f32 v7, v22, v24
	s_waitcnt lgkmcnt(2)
	v_cvt_pk_bf16_f32 v8, v26, v28
	s_waitcnt lgkmcnt(0)
	v_cvt_pk_bf16_f32 v9, v30, v32
	v_mul_u32_u24_e32 v0, 0x2c00, v0
	global_store_dwordx4 v[34:35], v[6:9], off sc1
	v_lshl_add_u64 v[16:17], v[16:17], 0, v[0:1]
	s_nop 0
	v_cvt_pk_bf16_f32 v6, v19, v21
	v_cvt_pk_bf16_f32 v7, v23, v25
	v_cvt_pk_bf16_f32 v8, v27, v29
	v_cvt_pk_bf16_f32 v9, v31, v33
	global_store_dwordx4 v[16:17], v[6:9], off sc1
	s_waitcnt lgkmcnt(0)

; __device__ __forceinline__ void transpose_item(const float* __restrict__ W, int ldw, int src_col0, bf16_t* WT, int K, int dst_row0, int k0, LAS float* scr, int lane) {
;     ...
;     for (int i = 0; i < 32; ++i) tmp[i] = __builtin_nontemporal_load(W + (size_t)(k0 + 2 * i + (lane >> 5)) * ldw + src_col0 + (lane & 31));
; __device__ __forceinline__ void convert_item(ArgsP a, const Ctx& c, int it, LAS float* scr) {
;     ...
;         if (r < 2 * I_GU) {
;             const int second = r >= I_GU; if (second) r -= I_GU;
;             const int kb = r / 352, gidx = r % 352, pn = gidx >> 3, w = gidx & 7;
;             const float* src = a->in[(second ? 13 : 10) + (w >> 2)] + (size_t)l * DM * FF;
;             transpose_item(src, FF, 128 * pn + 32 * (w & 3), (bf16_t*)(wl + (second ? WL_GU2 : WL_GU1)), DM, 32 * gidx, 64 * kb, scr, c.lane); return; }
.LBB0_530:
	s_add_i32 s3, s17, 0xffffd400
	s_cmpk_gt_i32 s17, 0x2bff
	s_cselect_b32 s3, s3, s17
	s_mul_hi_i32 s5, s3, 0x2e8ba2e9
	s_cselect_b32 s6, 0x6200000, 0
	s_cselect_b32 s4, 13, 10
	s_lshr_b32 s7, s5, 31
	s_ashr_i32 s5, s5, 6
	s_add_i32 s7, s5, s7
	s_mul_i32 s5, s7, 0x160
	s_sub_i32 s3, s3, s5
	s_bfe_u32 s5, s3, 0x10002
	s_add_i32 s5, s5, s4
	s_lshl_b32 s4, s5, 3
	s_load_dwordx2 s[4:5], s[0:1], s4 offset:0x0
	s_mul_hi_i32 s8, s2, 0x2c00000
	s_mul_i32 s2, s2, 0x2c00000
	v_lshlrev_b32_e32 v0, 2, v2
	s_waitcnt lgkmcnt(0)
	s_add_u32 s10, s4, s2
	s_addc_u32 s11, s5, s8
	s_lshl_b32 s2, s3, 4
	s_lshl_b32 s4, s3, 5
	s_and_b32 s2, s2, 0xffffff80
	s_and_b32 s3, s4, 0x60
	s_or_b32 s8, s2, s3
	s_add_u32 s5, s15, s6
	s_addc_u32 s6, s16, 0
	s_ashr_i32 s9, s8, 31
	s_lshl_b32 s2, s7, 6
	s_lshl_b64 s[8:9], s[8:9], 2
	s_add_u32 s8, s10, s8
	s_addc_u32 s9, s11, s9
	v_or_b32_e32 v15, s2, v3
	v_lshl_add_u64 v[6:7], s[8:9], 0, v[0:1]
	v_mad_i64_i32 v[8:9], s[8:9], v15, s46, v[6:7]
	global_load_dword v0, v[8:9], off nt
	v_or_b32_e32 v8, 2, v15
	v_mad_i64_i32 v[8:9], s[8:9], v8, s46, v[6:7]
	global_load_dword v16, v[8:9], off nt
	v_or_b32_e32 v8, 4, v15
	v_mad_i64_i32 v[8:9], s[8:9], v8, s46, v[6:7]
	global_load_dword v17, v[8:9], off nt
	v_or_b32_e32 v8, 6, v15
	v_mad_i64_i32 v[8:9], s[8:9], v8, s46, v[6:7]
	global_load_dword v18, v[8:9], off nt
	v_or_b32_e32 v8, 8, v15
	v_mad_i64_i32 v[8:9], s[8:9], v8, s46, v[6:7]
	global_load_dword v19, v[8:9], off nt
	v_or_b32_e32 v8, 10, v15
	v_mad_i64_i32 v[8:9], s[8:9], v8, s46, v[6:7]
	global_load_dword v20, v[8:9], off nt
	v_or_b32_e32 v8, 12, v15
	v_mad_i64_i32 v[8:9], s[8:9], v8, s46, v[6:7]
	global_load_dword v21, v[8:9], off nt
	v_or_b32_e32 v8, 14, v15
	v_mad_i64_i32 v[8:9], s[8:9], v8, s46, v[6:7]
	global_load_dword v22, v[8:9], off nt
	v_or_b32_e32 v8, 16, v15
	v_mad_i64_i32 v[8:9], s[8:9], v8, s46, v[6:7]
	global_load_dword v23, v[8:9], off nt
	v_or_b32_e32 v8, 18, v15
	v_mad_i64_i32 v[8:9], s[8:9], v8, s46, v[6:7]
	global_load_dword v24, v[8:9], off nt
	v_or_b32_e32 v8, 20, v15
	v_mad_i64_i32 v[8:9], s[8:9], v8, s46, v[6:7]
	global_load_dword v25, v[8:9], off nt
	v_or_b32_e32 v8, 22, v15
	v_mad_i64_i32 v[8:9], s[8:9], v8, s46, v[6:7]
	global_load_dword v26, v[8:9], off nt
	v_or_b32_e32 v8, 24, v15
	v_mad_i64_i32 v[8:9], s[8:9], v8, s46, v[6:7]
	global_load_dword v27, v[8:9], off nt
	v_or_b32_e32 v8, 26, v15
	v_mad_i64_i32 v[8:9], s[8:9], v8, s46, v[6:7]
	global_load_dword v28, v[8:9], off nt
	v_or_b32_e32 v8, 28, v15
	v_mad_i64_i32 v[8:9], s[8:9], v8, s46, v[6:7]
	global_load_dword v29, v[8:9], off nt
	v_or_b32_e32 v8, 30, v15
	v_mad_i64_i32 v[8:9], s[8:9], v8, s46, v[6:7]
	global_load_dword v30, v[8:9], off nt
	v_or_b32_e32 v8, 32, v15
	v_mad_i64_i32 v[8:9], s[8:9], v8, s46, v[6:7]
	global_load_dword v31, v[8:9], off nt
	v_or_b32_e32 v8, 34, v15
	v_mad_i64_i32 v[8:9], s[8:9], v8, s46, v[6:7]
	global_load_dword v32, v[8:9], off nt
	v_or_b32_e32 v8, 36, v15
	v_mad_i64_i32 v[8:9], s[8:9], v8, s46, v[6:7]
	global_load_dword v33, v[8:9], off nt
	v_or_b32_e32 v8, 38, v15
	v_mad_i64_i32 v[8:9], s[8:9], v8, s46, v[6:7]
	global_load_dword v34, v[8:9], off nt
	v_or_b32_e32 v8, 40, v15
	v_mad_i64_i32 v[8:9], s[8:9], v8, s46, v[6:7]
	global_load_dword v35, v[8:9], off nt
	v_or_b32_e32 v8, 42, v15
	v_mad_i64_i32 v[8:9], s[8:9], v8, s46, v[6:7]
	global_load_dword v36, v[8:9], off nt
	v_or_b32_e32 v8, 44, v15
	v_mad_i64_i32 v[8:9], s[8:9], v8, s46, v[6:7]
	global_load_dword v37, v[8:9], off nt
	v_or_b32_e32 v8, 46, v15
	v_mad_i64_i32 v[8:9], s[8:9], v8, s46, v[6:7]
	global_load_dword v38, v[8:9], off nt
	v_or_b32_e32 v8, 48, v15
	v_mad_i64_i32 v[8:9], s[8:9], v8, s46, v[6:7]
	global_load_dword v39, v[8:9], off nt
	v_or_b32_e32 v8, 50, v15
	v_mad_i64_i32 v[8:9], s[8:9], v8, s46, v[6:7]
	global_load_dword v40, v[8:9], off nt
	v_or_b32_e32 v8, 52, v15
	v_mad_i64_i32 v[8:9], s[8:9], v8, s46, v[6:7]
	global_load_dword v41, v[8:9], off nt
	v_or_b32_e32 v8, 54, v15
	v_mad_i64_i32 v[8:9], s[8:9], v8, s46, v[6:7]
	global_load_dword v42, v[8:9], off nt
	v_or_b32_e32 v8, 56, v15
	v_mad_i64_i32 v[8:9], s[8:9], v8, s46, v[6:7]
	global_load_dword v43, v[8:9], off nt
	v_or_b32_e32 v8, 58, v15
	v_mad_i64_i32 v[8:9], s[8:9], v8, s46, v[6:7]
	global_load_dword v44, v[8:9], off nt
	v_or_b32_e32 v8, 60, v15
	v_mad_i64_i32 v[8:9], s[8:9], v8, s46, v[6:7]
	global_load_dword v8, v[8:9], off nt
	v_or_b32_e32 v9, 62, v15
	v_mad_i64_i32 v[6:7], s[8:9], v9, s46, v[6:7]
	global_load_dword v6, v[6:7], off nt
	s_waitcnt vmcnt(0)
; #define LAS __attribute__((address_space(3)))
; __device__ __forceinline__ unsigned pk_bf16(float lo, float hi) { f32x2 v = {lo, hi}; bf16x2_t b = __builtin_convertvector(v, bf16x2_t); return __builtin_bit_cast(unsigned, b); }
; #define LDS_WAIT() asm volatile("s_waitcnt lgkmcnt(0)" ::: "memory")
; __device__ __forceinline__ void transpose_item(const float* __restrict__ W, int ldw, int src_col0, bf16_t* WT, int K, int dst_row0, int k0, LAS float* scr, int lane) {
;     ...
; #pragma unroll
;     for (int i = 0; i < 32; ++i) scr[(2 * i + (lane >> 5)) * 33 + (lane & 31)] = tmp[i];
;     LDS_WAIT();
;     const int c = lane & 7;
; #pragma unroll
;     for (int j = 0; j < 4; ++j) { const int n = (lane >> 3) + 8 * j; const LAS float* s = scr + (8 * c) * 33 + n;
;         u32x4 o; o.x = pk_bf16(s[0 * 33], s[1 * 33]); o.y = pk_bf16(s[2 * 33], s[3 * 33]); o.z = pk_bf16(s[4 * 33], s[5 * 33]); o.w = pk_bf16(s[6 * 33], s[7 * 33]);
;         *(u32x4*)(WT + (size_t)(dst_row0 + n) * K + k0 + 8 * c) = o; }
; __global__ void __launch_bounds__(NTHREADS, 2) fwd_megakernel(Args args) {
;     ...
;                     for (int it = (c.bid - half0) * NWAVES + c.wave; it < cnt; it += (c.G - half0) * NWAVES) convert_item(ap, c, PER_LAYER + tail_item(tk, it), scr);
	ds_write2_b32 v5, v0, v16 offset1:66
	ds_write2_b32 v5, v17, v18 offset0:132 offset1:198
	v_add_u32_e32 v0, 0x400, v5
	ds_write2_b32 v0, v19, v20 offset0:8 offset1:74
	ds_write2_b32 v0, v21, v22 offset0:140 offset1:206
	v_add_u32_e32 v0, 0x800, v5
	ds_write2_b32 v0, v23, v24 offset0:16 offset1:82
	ds_write2_b32 v0, v25, v26 offset0:148 offset1:214
	v_add_u32_e32 v0, 0xc00, v5
	ds_write2_b32 v0, v27, v28 offset0:24 offset1:90
	ds_write2_b32 v0, v29, v30 offset0:156 offset1:222
	v_add_u32_e32 v0, 0x1000, v5
	ds_write2_b32 v0, v31, v32 offset0:32 offset1:98
	ds_write2_b32 v0, v33, v34 offset0:164 offset1:230
	v_add_u32_e32 v0, 0x1400, v5
	ds_write2_b32 v0, v35, v36 offset0:40 offset1:106
	ds_write2_b32 v0, v37, v38 offset0:172 offset1:238
	v_add_u32_e32 v0, 0x1800, v5
	ds_write2_b32 v0, v39, v40 offset0:48 offset1:114
	ds_write2_b32 v0, v41, v42 offset0:180 offset1:246
	v_add_u32_e32 v0, 0x1c00, v5
	ds_write2_b32 v0, v43, v44 offset0:56 offset1:122
	ds_write2_b32 v0, v8, v6 offset0:188 offset1:254
	s_waitcnt lgkmcnt(0)
	s_ashr_i32 s3, s2, 31
	ds_read2_b32 v[18:19], v11 offset0:33 offset1:41
	ds_read2_b32 v[20:21], v11 offset1:8
	ds_read2_b32 v[22:23], v11 offset0:66 offset1:74
	ds_read2_b32 v[24:25], v11 offset0:99 offset1:107
	ds_read2_b32 v[26:27], v11 offset0:132 offset1:140
	ds_read2_b32 v[28:29], v11 offset0:165 offset1:173
	ds_read2_b32 v[30:31], v11 offset0:198 offset1:206
	ds_read2_b32 v[32:33], v11 offset0:231 offset1:239
	s_lshl_b64 s[2:3], s[2:3], 1
	s_add_u32 s2, s5, s2
	v_or_b32_e32 v34, s4, v10
	s_addc_u32 s3, s6, s3
	v_lshlrev_b32_e32 v0, 1, v4
	v_ashrrev_i32_e32 v35, 31, v34
	v_lshl_add_u64 v[16:17], s[2:3], 0, v[0:1]
	v_lshlrev_b64 v[34:35], 12, v[34:35]
	s_waitcnt lgkmcnt(6)
	v_cvt_pk_bf16_f32 v6, v20, v18
	s_waitcnt lgkmcnt(4)
	v_cvt_pk_bf16_f32 v7, v22, v24
	s_waitcnt lgkmcnt(2)
	v_cvt_pk_bf16_f32 v8, v26, v28
	s_waitcnt lgkmcnt(0)
	v_cvt_pk_bf16_f32 v9, v30, v32
	v_lshl_add_u64 v[34:35], v[16:17], 0, v[34:35]
	v_or_b32_e32 v18, s4, v12
	global_store_dwordx4 v[34:35], v[6:9], off sc1
	v_or_b32_e32 v34, s4, v13
	v_ashrrev_i32_e32 v35, 31, v34
	v_cvt_pk_bf16_f32 v6, v21, v19
	v_ashrrev_i32_e32 v19, 31, v18
	v_lshlrev_b64 v[18:19], 12, v[18:19]
	v_cvt_pk_bf16_f32 v7, v23, v25
	v_cvt_pk_bf16_f32 v8, v27, v29
	v_cvt_pk_bf16_f32 v9, v31, v33
	v_lshl_add_u64 v[18:19], v[16:17], 0, v[18:19]
	global_store_dwordx4 v[18:19], v[6:9], off sc1
	ds_read2_b32 v[18:19], v11 offset0:49 offset1:57
	ds_read2_b32 v[20:21], v11 offset0:16 offset1:24
	ds_read2_b32 v[22:23], v11 offset0:82 offset1:90
	ds_read2_b32 v[24:25], v11 offset0:115 offset1:123
	ds_read2_b32 v[26:27], v11 offset0:148 offset1:156
	ds_read2_b32 v[28:29], v11 offset0:181 offset1:189
	ds_read2_b32 v[30:31], v11 offset0:214 offset1:222
	ds_read2_b32 v[32:33], v11 offset0:247 offset1:255
	v_lshlrev_b64 v[34:35], 12, v[34:35]
	s_waitcnt lgkmcnt(6)
	v_cvt_pk_bf16_f32 v6, v20, v18
	s_waitcnt lgkmcnt(4)
	v_cvt_pk_bf16_f32 v7, v22, v24
	s_waitcnt lgkmcnt(2)
	v_cvt_pk_bf16_f32 v8, v26, v28
	s_waitcnt lgkmcnt(0)
	v_cvt_pk_bf16_f32 v9, v30, v32
	v_lshl_add_u64 v[34:35], v[16:17], 0, v[34:35]
	v_or_b32_e32 v18, s4, v14
	global_store_dwordx4 v[34:35], v[6:9], off sc1
	s_nop 1
	v_cvt_pk_bf16_f32 v6, v21, v19
	v_ashrrev_i32_e32 v19, 31, v18
	v_lshlrev_b64 v[18:19], 12, v[18:19]
	v_cvt_pk_bf16_f32 v7, v23, v25
	v_cvt_pk_bf16_f32 v8, v27, v29
	v_cvt_pk_bf16_f32 v9, v31, v33
	v_lshl_add_u64 v[16:17], v[16:17], 0, v[18:19]
	global_store_dwordx4 v[16:17], v[6:9], off sc1
	s_waitcnt lgkmcnt(0)
	s_branch .LBB0_464

; __device__ __forceinline__ void convert_item(ArgsP a, const Ctx& c, int it, LAS float* scr) {
;     ...
;         const int l = it / PER_LAYER; int r = it - l * PER_LAYER;
;         unsigned char* wl = c.ws + WS_W + (size_t)l * WL_SIZE;
;         if (r < 2 * I_GU) {
;             const int second = r >= I_GU; if (second) r -= I_GU;
;             const int kb = r / 352, gidx = r % 352, pn = gidx >> 3, w = gidx & 7;
;             const float* src = a->in[(second ? 13 : 10) + (w >> 2)] + (size_t)l * DM * FF;
;             transpose_item(src, FF, 128 * pn + 32 * (w & 3), (bf16_t*)(wl + (second ? WL_GU2 : WL_GU1)), DM, 32 * gidx, 64 * kb, scr, c.lane); return; }
;         r -= 2 * I_GU;
;         if (r < 2 * I_D) { const int second = r >= I_D; if (second) r -= I_D; const int kb = r / 64, nb = r % 64;
;             transpose_item(a->in[second ? 15 : 12] + (size_t)l * FF * DM, DM, 32 * nb, (bf16_t*)(wl + (second ? WL_D2 : WL_D1)), FF, 32 * nb, 64 * kb, scr, c.lane); return; }
;         r -= 2 * I_D;
;         if (r < I_IN) { const int kb = r / 128, gidx = r % 128;
;             transpose_item(a->in[3] + (size_t)l * DM * DIN, DIN, win_src_col(gidx), (bf16_t*)(wl + WL_IN), DM, 32 * gidx, 64 * kb, scr, c.lane); return; }
;         r -= I_IN;
;         if (r < I_SQ) { const int kb = r / 64, nb = r % 64, row0 = 32 * nb; const int sc = row0 < 768 ? W_DV + row0 : (row0 < 1280 ? W_GV + (row0 - 768) : W_MV + (row0 - 1280));
;             transpose_item(a->in[3] + (size_t)l * DM * DIN, DIN, sc, (bf16_t*)(wl + WL_V), DM, row0, 64 * kb, scr, c.lane); return; }
;         r -= I_SQ;
;         if (r < I_SQ) { const int kb = r / 64, nb = r % 64; transpose_item(a->in[4] + (size_t)l * DM * DM, DM, 32 * nb, (bf16_t*)(wl + WL_OUT), DM, 32 * nb, 64 * kb, scr, c.lane); return; }
;         r -= I_SQ;
;         if (r < I_SQ) { const int kb = r / 64, nb = r % 64; transpose_item(a->in[17] + (size_t)l * DM * DM, DM, 32 * nb, (bf16_t*)(wl + WL_PG), DM, 32 * nb, 64 * kb, scr, c.lane); return; }
;         r -= I_SQ;
;         { const int kb = r / 64, nb = r % 64; transpose_item(a->in[16] + (size_t)l * PLE * DM, DM, 32 * nb, (bf16_t*)(wl + WL_PE), PLE, 32 * nb, 64 * kb, scr, c.lane); }
.LBB0_548:
	s_mul_hi_i32 s2, s10, 0x17ad2209
	s_lshr_b32 s3, s2, 31
	s_ashr_i32 s2, s2, 12
	s_add_i32 s2, s2, s3
	s_mul_i32 s17, s2, 0xffff5300
	s_add_i32 s17, s17, s10
	s_ashr_i32 s3, s2, 31
	s_mul_i32 s5, s2, 0xae00000
	s_mul_hi_i32 s4, s2, 0xae00000
	s_add_u32 s15, s12, s5
	s_addc_u32 s16, s13, s4
	s_cmpk_gt_i32 s17, 0x57ff
	s_mov_b64 s[4:5], -1
	s_cbranch_scc0 .LBB0_581
	s_cmpk_gt_u32 s17, 0x83ff
	s_cbranch_scc0 .LBB0_594
	s_cmpk_gt_u32 s17, 0x93ff
	s_cbranch_scc0 .LBB0_572
	s_cmpk_gt_u32 s17, 0x9bff
	s_cbranch_scc0 .LBB0_561
	s_cmpk_gt_u32 s17, 0xa3ff
	s_cbranch_scc0 .LBB0_558
	s_lshl_b32 s4, s10, 5
	s_and_b32 s6, s4, 0x7e0
	s_cmpk_gt_u32 s17, 0xabff
	s_mov_b64 s[4:5], -1
	v_or_b32_e32 v15, s6, v7
	v_or_b32_e32 v14, s6, v9
	v_or_b32_e32 v13, s6, v10
	v_or_b32_e32 v12, s6, v11
	s_cbranch_scc0 .LBB0_555
	s_load_dwordx2 s[4:5], s[0:1], 0x80
	s_and_b32 s7, s17, 0x7fffffc0
	s_lshl_b64 s[8:9], s[2:3], 21
	s_add_i32 s60, s7, 0xffff5400
	v_or_b32_e32 v16, s60, v3
	s_waitcnt lgkmcnt(0)
	s_add_u32 s4, s4, s8
	s_addc_u32 s5, s5, s9
	s_lshl_b32 s7, s6, 2
	s_add_u32 s4, s4, s7
	s_addc_u32 s5, s5, 0
	v_lshlrev_b32_e32 v0, 2, v4
	v_lshl_add_u64 v[18:19], s[4:5], 0, v[0:1]
	v_or_b32_e32 v0, 2, v16
	v_lshlrev_b64 v[22:23], 13, v[0:1]
	v_or_b32_e32 v0, 4, v16
	v_lshlrev_b64 v[24:25], 13, v[0:1]
	v_or_b32_e32 v0, 6, v16
	v_lshlrev_b64 v[26:27], 13, v[0:1]
	v_or_b32_e32 v0, 8, v16
	v_lshlrev_b64 v[28:29], 13, v[0:1]
	v_or_b32_e32 v0, 10, v16
	v_mov_b32_e32 v17, v1
	v_lshlrev_b64 v[30:31], 13, v[0:1]
	v_or_b32_e32 v0, 12, v16
	v_lshlrev_b64 v[20:21], 13, v[16:17]
	v_lshlrev_b64 v[32:33], 13, v[0:1]
	v_or_b32_e32 v0, 14, v16
	v_lshl_add_u64 v[20:21], v[18:19], 0, v[20:21]
	v_lshlrev_b64 v[34:35], 13, v[0:1]
	v_or_b32_e32 v0, 16, v16
	v_lshl_add_u64 v[22:23], v[18:19], 0, v[22:23]
	v_lshl_add_u64 v[24:25], v[18:19], 0, v[24:25]
	v_lshl_add_u64 v[26:27], v[18:19], 0, v[26:27]
	v_lshl_add_u64 v[28:29], v[18:19], 0, v[28:29]
	v_lshl_add_u64 v[30:31], v[18:19], 0, v[30:31]
	v_lshl_add_u64 v[32:33], v[18:19], 0, v[32:33]
	v_lshl_add_u64 v[34:35], v[18:19], 0, v[34:35]
	global_load_dword v36, v[20:21], off nt
	global_load_dword v37, v[22:23], off nt
	global_load_dword v38, v[24:25], off nt
	global_load_dword v39, v[26:27], off nt
	global_load_dword v40, v[28:29], off nt
	global_load_dword v41, v[30:31], off nt
	global_load_dword v42, v[32:33], off nt
	global_load_dword v43, v[34:35], off nt
	v_lshlrev_b64 v[20:21], 13, v[0:1]
	v_or_b32_e32 v0, 18, v16
	v_lshlrev_b64 v[22:23], 13, v[0:1]
	v_or_b32_e32 v0, 20, v16
	v_lshlrev_b64 v[24:25], 13, v[0:1]
	v_or_b32_e32 v0, 22, v16
	v_lshlrev_b64 v[26:27], 13, v[0:1]
	v_or_b32_e32 v0, 24, v16
	v_lshlrev_b64 v[28:29], 13, v[0:1]
	v_or_b32_e32 v0, 26, v16
	v_lshlrev_b64 v[30:31], 13, v[0:1]
	v_or_b32_e32 v0, 28, v16
	v_lshlrev_b64 v[32:33], 13, v[0:1]
	v_or_b32_e32 v0, 30, v16
	v_lshl_add_u64 v[20:21], v[18:19], 0, v[20:21]
	v_lshlrev_b64 v[34:35], 13, v[0:1]
	v_or_b32_e32 v0, 32, v16
	v_lshl_add_u64 v[22:23], v[18:19], 0, v[22:23]
	v_lshl_add_u64 v[24:25], v[18:19], 0, v[24:25]
	v_lshl_add_u64 v[26:27], v[18:19], 0, v[26:27]
	v_lshl_add_u64 v[28:29], v[18:19], 0, v[28:29]
	v_lshl_add_u64 v[30:31], v[18:19], 0, v[30:31]
	v_lshl_add_u64 v[32:33], v[18:19], 0, v[32:33]
	v_lshl_add_u64 v[34:35], v[18:19], 0, v[34:35]
	global_load_dword v44, v[20:21], off nt
	global_load_dword v45, v[22:23], off nt
	global_load_dword v46, v[24:25], off nt
	global_load_dword v47, v[26:27], off nt
	global_load_dword v48, v[28:29], off nt
	global_load_dword v49, v[30:31], off nt
	global_load_dword v50, v[32:33], off nt
	global_load_dword v51, v[34:35], off nt
	v_lshlrev_b64 v[20:21], 13, v[0:1]
	v_or_b32_e32 v0, 34, v16
	v_lshlrev_b64 v[22:23], 13, v[0:1]
	v_or_b32_e32 v0, 36, v16
	v_lshlrev_b64 v[24:25], 13, v[0:1]
	v_or_b32_e32 v0, 38, v16
	v_lshlrev_b64 v[26:27], 13, v[0:1]
	v_or_b32_e32 v0, 40, v16
	v_lshlrev_b64 v[28:29], 13, v[0:1]
	v_or_b32_e32 v0, 42, v16
	v_lshlrev_b64 v[30:31], 13, v[0:1]
	v_or_b32_e32 v0, 44, v16
	v_lshlrev_b64 v[32:33], 13, v[0:1]
	v_or_b32_e32 v0, 46, v16
	v_lshlrev_b64 v[34:35], 13, v[0:1]
	v_lshl_add_u64 v[20:21], v[18:19], 0, v[20:21]
	v_lshl_add_u64 v[34:35], v[18:19], 0, v[34:35]
	v_or_b32_e32 v0, 48, v16
	v_lshl_add_u64 v[22:23], v[18:19], 0, v[22:23]
	v_lshl_add_u64 v[24:25], v[18:19], 0, v[24:25]
	v_lshl_add_u64 v[26:27], v[18:19], 0, v[26:27]
	v_lshl_add_u64 v[28:29], v[18:19], 0, v[28:29]
	v_lshl_add_u64 v[30:31], v[18:19], 0, v[30:31]
	v_lshl_add_u64 v[32:33], v[18:19], 0, v[32:33]
	global_load_dword v52, v[20:21], off nt
	global_load_dword v53, v[22:23], off nt
	global_load_dword v54, v[24:25], off nt
	global_load_dword v55, v[26:27], off nt
	global_load_dword v56, v[28:29], off nt
	global_load_dword v57, v[30:31], off nt
	global_load_dword v58, v[32:33], off nt
	s_nop 0
	global_load_dword v34, v[34:35], off nt
	v_lshlrev_b64 v[20:21], 13, v[0:1]
	v_or_b32_e32 v0, 50, v16
	v_lshlrev_b64 v[22:23], 13, v[0:1]
	v_or_b32_e32 v0, 52, v16
	v_lshlrev_b64 v[24:25], 13, v[0:1]
	v_or_b32_e32 v0, 54, v16
	v_lshlrev_b64 v[26:27], 13, v[0:1]
	v_or_b32_e32 v0, 56, v16
	v_lshlrev_b64 v[28:29], 13, v[0:1]
	v_or_b32_e32 v0, 58, v16
	v_lshlrev_b64 v[30:31], 13, v[0:1]
	v_or_b32_e32 v0, 60, v16
	v_lshlrev_b64 v[32:33], 13, v[0:1]
	v_or_b32_e32 v0, 62, v16
	v_lshlrev_b64 v[16:17], 13, v[0:1]
	v_lshl_add_u64 v[20:21], v[18:19], 0, v[20:21]
	v_lshl_add_u64 v[22:23], v[18:19], 0, v[22:23]
	v_lshl_add_u64 v[16:17], v[18:19], 0, v[16:17]
	v_lshl_add_u64 v[24:25], v[18:19], 0, v[24:25]
	v_lshl_add_u64 v[26:27], v[18:19], 0, v[26:27]
	v_lshl_add_u64 v[28:29], v[18:19], 0, v[28:29]
	v_lshl_add_u64 v[30:31], v[18:19], 0, v[30:31]
	v_lshl_add_u64 v[32:33], v[18:19], 0, v[32:33]
	global_load_dword v0, v[20:21], off nt
	global_load_dword v18, v[22:23], off nt
	global_load_dword v19, v[24:25], off nt
	s_nop 0
	global_load_dword v20, v[26:27], off nt
	global_load_dword v21, v[28:29], off nt
	global_load_dword v22, v[30:31], off nt
	global_load_dword v23, v[32:33], off nt
	s_nop 0
	global_load_dword v16, v[16:17], off nt
	v_add_u32_e32 v17, 0x400, v5
	s_waitcnt vmcnt(0)
; #define LAS __attribute__((address_space(3)))
; __device__ __forceinline__ unsigned pk_bf16(float lo, float hi) { f32x2 v = {lo, hi}; bf16x2_t b = __builtin_convertvector(v, bf16x2_t); return __builtin_bit_cast(unsigned, b); }
; #define LDS_WAIT() asm volatile("s_waitcnt lgkmcnt(0)" ::: "memory")
; __device__ __forceinline__ void transpose_item(const float* __restrict__ W, int ldw, int src_col0, bf16_t* WT, int K, int dst_row0, int k0, LAS float* scr, int lane) {
;     ...
; #pragma unroll
;     for (int i = 0; i < 32; ++i) scr[(2 * i + (lane >> 5)) * 33 + (lane & 31)] = tmp[i];
;     LDS_WAIT();
;     const int c = lane & 7;
; #pragma unroll
;     for (int j = 0; j < 4; ++j) { const int n = (lane >> 3) + 8 * j; const LAS float* s = scr + (8 * c) * 33 + n;
;         u32x4 o; o.x = pk_bf16(s[0 * 33], s[1 * 33]); o.y = pk_bf16(s[2 * 33], s[3 * 33]); o.z = pk_bf16(s[4 * 33], s[5 * 33]); o.w = pk_bf16(s[6 * 33], s[7 * 33]);
;         *(u32x4*)(WT + (size_t)(dst_row0 + n) * K + k0 + 8 * c) = o; }
; __device__ __forceinline__ void convert_item(ArgsP a, const Ctx& c, int it, LAS float* scr) {
;     ...
;         if (r < I_SQ) { const int kb = r / 64, nb = r % 64; transpose_item(a->in[17] + (size_t)l * DM * DM, DM, 32 * nb, (bf16_t*)(wl + WL_PG), DM, 32 * nb, 64 * kb, scr, c.lane); return; }
;     ...
;         { const int kb = r / 64, nb = r % 64; transpose_item(a->in[16] + (size_t)l * PLE * DM, DM, 32 * nb, (bf16_t*)(wl + WL_PE), PLE, 32 * nb, 64 * kb, scr, c.lane); }
	ds_write2_b32 v5, v36, v37 offset1:66
	ds_write2_b32 v5, v38, v39 offset0:132 offset1:198
	ds_write2_b32 v17, v40, v41 offset0:8 offset1:74
	ds_write2_b32 v17, v42, v43 offset0:140 offset1:206
	v_add_u32_e32 v17, 0x800, v5
	ds_write2_b32 v17, v44, v45 offset0:16 offset1:82
	ds_write2_b32 v17, v46, v47 offset0:148 offset1:214
	v_add_u32_e32 v17, 0xc00, v5
	ds_write2_b32 v17, v48, v49 offset0:24 offset1:90
	ds_write2_b32 v17, v50, v51 offset0:156 offset1:222
	v_add_u32_e32 v17, 0x1000, v5
	ds_write2_b32 v17, v52, v53 offset0:32 offset1:98
	ds_write2_b32 v17, v54, v55 offset0:164 offset1:230
	v_add_u32_e32 v17, 0x1400, v5
	ds_write2_b32 v17, v56, v57 offset0:40 offset1:106
	ds_write2_b32 v17, v58, v34 offset0:172 offset1:238
	v_add_u32_e32 v17, 0x1800, v5
	ds_write2_b32 v17, v0, v18 offset0:48 offset1:114
	ds_write2_b32 v17, v19, v20 offset0:180 offset1:246
	v_add_u32_e32 v0, 0x1c00, v5
	ds_write2_b32 v0, v21, v22 offset0:56 offset1:122
	ds_write2_b32 v0, v23, v16 offset0:188 offset1:254
	s_waitcnt lgkmcnt(0)
	s_lshl_b64 s[4:5], s[60:61], 1
	ds_read2_b32 v[20:21], v8 offset0:33 offset1:41
	ds_read2_b32 v[22:23], v8 offset1:8
	ds_read2_b32 v[24:25], v8 offset0:66 offset1:74
	ds_read2_b32 v[26:27], v8 offset0:99 offset1:107
	ds_read2_b32 v[28:29], v8 offset0:132 offset1:140
	ds_read2_b32 v[30:31], v8 offset0:165 offset1:173
	ds_read2_b32 v[32:33], v8 offset0:198 offset1:206
	ds_read2_b32 v[34:35], v8 offset0:231 offset1:239
	s_add_u32 s4, s15, s4
	s_addc_u32 s5, s16, s5
	v_lshlrev_b32_e32 v0, 1, v6
	v_lshl_add_u64 v[16:17], s[4:5], 0, v[0:1]
	s_mov_b64 s[4:5], 0xa400000
	v_lshl_add_u64 v[36:37], v[16:17], 0, s[4:5]
	v_lshlrev_b32_e32 v0, 9, v15
	s_waitcnt lgkmcnt(6)
	v_cvt_pk_bf16_f32 v16, v22, v20
	s_waitcnt lgkmcnt(4)
	v_cvt_pk_bf16_f32 v17, v24, v26
	s_waitcnt lgkmcnt(2)
	v_cvt_pk_bf16_f32 v18, v28, v30
	s_waitcnt lgkmcnt(0)
	v_cvt_pk_bf16_f32 v19, v32, v34
	v_lshl_add_u64 v[38:39], v[36:37], 0, v[0:1]
	global_store_dwordx4 v[38:39], v[16:19], off sc1
	v_lshlrev_b32_e32 v0, 9, v14
	s_mov_b64 s[4:5], 0
	v_cvt_pk_bf16_f32 v16, v23, v21
	v_cvt_pk_bf16_f32 v17, v25, v27
	v_cvt_pk_bf16_f32 v18, v29, v31
	v_cvt_pk_bf16_f32 v19, v33, v35
	ds_read2_b32 v[22:23], v8 offset0:49 offset1:57
	ds_read2_b32 v[24:25], v8 offset0:16 offset1:24
	ds_read2_b32 v[26:27], v8 offset0:82 offset1:90
	ds_read2_b32 v[28:29], v8 offset0:115 offset1:123
	ds_read2_b32 v[30:31], v8 offset0:148 offset1:156
	ds_read2_b32 v[32:33], v8 offset0:181 offset1:189
	ds_read2_b32 v[34:35], v8 offset0:214 offset1:222
	ds_read2_b32 v[38:39], v8 offset0:247 offset1:255
	v_lshl_add_u64 v[20:21], v[36:37], 0, v[0:1]
	v_lshlrev_b32_e32 v0, 9, v13
	global_store_dwordx4 v[20:21], v[16:19], off sc1
	v_lshl_add_u64 v[20:21], v[36:37], 0, v[0:1]
	v_lshlrev_b32_e32 v0, 9, v12
	s_waitcnt lgkmcnt(6)
	v_cvt_pk_bf16_f32 v16, v24, v22
	s_waitcnt lgkmcnt(4)
	v_cvt_pk_bf16_f32 v17, v26, v28
	s_waitcnt lgkmcnt(2)
	v_cvt_pk_bf16_f32 v18, v30, v32
	s_waitcnt lgkmcnt(0)
	v_cvt_pk_bf16_f32 v19, v34, v38
	global_store_dwordx4 v[20:21], v[16:19], off sc1
	v_lshl_add_u64 v[20:21], v[36:37], 0, v[0:1]
	s_nop 0
	v_cvt_pk_bf16_f32 v16, v25, v23
	v_cvt_pk_bf16_f32 v17, v27, v29
	v_cvt_pk_bf16_f32 v18, v31, v33
	v_cvt_pk_bf16_f32 v19, v35, v39
	global_store_dwordx4 v[20:21], v[16:19], off sc1
	s_waitcnt lgkmcnt(0)
.LBB0_555:
	s_andn2_b64 vcc, exec, s[4:5]
	s_cbranch_vccnz .LBB0_557
	s_load_dwordx2 s[4:5], s[0:1], 0x88
	s_and_b32 s7, s17, 0xffc0
	s_lshl_b64 s[8:9], s[2:3], 24
	s_add_i32 s60, s7, 0xffff5c00
	v_or_b32_e32 v16, s60, v3
	s_waitcnt lgkmcnt(0)
	s_add_u32 s4, s4, s8
	s_addc_u32 s5, s5, s9
	s_lshl_b32 s6, s6, 2
	s_add_u32 s4, s4, s6
	s_addc_u32 s5, s5, 0
	v_lshlrev_b32_e32 v0, 2, v4
	v_lshl_add_u64 v[18:19], s[4:5], 0, v[0:1]
	v_or_b32_e32 v0, 2, v16
	v_lshlrev_b64 v[22:23], 13, v[0:1]
	v_or_b32_e32 v0, 4, v16
	v_lshlrev_b64 v[24:25], 13, v[0:1]
	v_or_b32_e32 v0, 6, v16
	v_lshlrev_b64 v[26:27], 13, v[0:1]
	v_or_b32_e32 v0, 8, v16
	v_lshlrev_b64 v[28:29], 13, v[0:1]
	v_or_b32_e32 v0, 10, v16
	v_mov_b32_e32 v17, v1
	v_lshlrev_b64 v[30:31], 13, v[0:1]
	v_or_b32_e32 v0, 12, v16
	v_lshlrev_b64 v[20:21], 13, v[16:17]
	v_lshlrev_b64 v[32:33], 13, v[0:1]
	v_or_b32_e32 v0, 14, v16
	v_lshl_add_u64 v[20:21], v[18:19], 0, v[20:21]
	v_lshlrev_b64 v[34:35], 13, v[0:1]
	v_or_b32_e32 v0, 16, v16
	v_lshl_add_u64 v[22:23], v[18:19], 0, v[22:23]
	v_lshl_add_u64 v[24:25], v[18:19], 0, v[24:25]
	v_lshl_add_u64 v[26:27], v[18:19], 0, v[26:27]
	v_lshl_add_u64 v[28:29], v[18:19], 0, v[28:29]
	v_lshl_add_u64 v[30:31], v[18:19], 0, v[30:31]
	v_lshl_add_u64 v[32:33], v[18:19], 0, v[32:33]
	v_lshl_add_u64 v[34:35], v[18:19], 0, v[34:35]
	global_load_dword v36, v[20:21], off nt
	global_load_dword v37, v[22:23], off nt
	global_load_dword v38, v[24:25], off nt
	global_load_dword v39, v[26:27], off nt
	global_load_dword v40, v[28:29], off nt
	global_load_dword v41, v[30:31], off nt
	global_load_dword v42, v[32:33], off nt
	global_load_dword v43, v[34:35], off nt
	v_lshlrev_b64 v[20:21], 13, v[0:1]
	v_or_b32_e32 v0, 18, v16
	v_lshlrev_b64 v[22:23], 13, v[0:1]
	v_or_b32_e32 v0, 20, v16
	v_lshlrev_b64 v[24:25], 13, v[0:1]
	v_or_b32_e32 v0, 22, v16
	v_lshlrev_b64 v[26:27], 13, v[0:1]
	v_or_b32_e32 v0, 24, v16
	v_lshlrev_b64 v[28:29], 13, v[0:1]
	v_or_b32_e32 v0, 26, v16
	v_lshlrev_b64 v[30:31], 13, v[0:1]
	v_or_b32_e32 v0, 28, v16
	v_lshlrev_b64 v[32:33], 13, v[0:1]
	v_or_b32_e32 v0, 30, v16
	v_lshl_add_u64 v[20:21], v[18:19], 0, v[20:21]
	v_lshlrev_b64 v[34:35], 13, v[0:1]
	v_or_b32_e32 v0, 32, v16
	v_lshl_add_u64 v[22:23], v[18:19], 0, v[22:23]
	v_lshl_add_u64 v[24:25], v[18:19], 0, v[24:25]
	v_lshl_add_u64 v[26:27], v[18:19], 0, v[26:27]
; #define LAS __attribute__((address_space(3)))
; __device__ __forceinline__ unsigned pk_bf16(float lo, float hi) { f32x2 v = {lo, hi}; bf16x2_t b = __builtin_convertvector(v, bf16x2_t); return __builtin_bit_cast(unsigned, b); }
; #define LDS_WAIT() asm volatile("s_waitcnt lgkmcnt(0)" ::: "memory")
; __device__ __forceinline__ void transpose_item(const float* __restrict__ W, int ldw, int src_col0, bf16_t* WT, int K, int dst_row0, int k0, LAS float* scr, int lane) {
;     float tmp[32];
; #pragma unroll
;     for (int i = 0; i < 32; ++i) tmp[i] = __builtin_nontemporal_load(W + (size_t)(k0 + 2 * i + (lane >> 5)) * ldw + src_col0 + (lane & 31));
; #pragma unroll
;     for (int i = 0; i < 32; ++i) scr[(2 * i + (lane >> 5)) * 33 + (lane & 31)] = tmp[i];
;     LDS_WAIT();
;     const int c = lane & 7;
; #pragma unroll
;     for (int j = 0; j < 4; ++j) { const int n = (lane >> 3) + 8 * j; const LAS float* s = scr + (8 * c) * 33 + n;
;         u32x4 o; o.x = pk_bf16(s[0 * 33], s[1 * 33]); o.y = pk_bf16(s[2 * 33], s[3 * 33]); o.z = pk_bf16(s[4 * 33], s[5 * 33]); o.w = pk_bf16(s[6 * 33], s[7 * 33]);
;         *(u32x4*)(WT + (size_t)(dst_row0 + n) * K + k0 + 8 * c) = o; }
;     LDS_WAIT();
; }
; __device__ __forceinline__ void convert_item(ArgsP a, const Ctx& c, int it, LAS float* scr) {
;     ...
;         if (r < I_SQ) { const int kb = r / 64, nb = r % 64; transpose_item(a->in[17] + (size_t)l * DM * DM, DM, 32 * nb, (bf16_t*)(wl + WL_PG), DM, 32 * nb, 64 * kb, scr, c.lane); return; }
	v_lshl_add_u64 v[28:29], v[18:19], 0, v[28:29]
	v_lshl_add_u64 v[30:31], v[18:19], 0, v[30:31]
	v_lshl_add_u64 v[32:33], v[18:19], 0, v[32:33]
	v_lshl_add_u64 v[34:35], v[18:19], 0, v[34:35]
	global_load_dword v44, v[20:21], off nt
	global_load_dword v45, v[22:23], off nt
	global_load_dword v46, v[24:25], off nt
	global_load_dword v47, v[26:27], off nt
	global_load_dword v48, v[28:29], off nt
	global_load_dword v49, v[30:31], off nt
	global_load_dword v50, v[32:33], off nt
	global_load_dword v51, v[34:35], off nt
	v_lshlrev_b64 v[20:21], 13, v[0:1]
	v_or_b32_e32 v0, 34, v16
	v_lshlrev_b64 v[22:23], 13, v[0:1]
	v_or_b32_e32 v0, 36, v16
	v_lshlrev_b64 v[24:25], 13, v[0:1]
	v_or_b32_e32 v0, 38, v16
	v_lshlrev_b64 v[26:27], 13, v[0:1]
	v_or_b32_e32 v0, 40, v16
	v_lshlrev_b64 v[28:29], 13, v[0:1]
	v_or_b32_e32 v0, 42, v16
	v_lshlrev_b64 v[30:31], 13, v[0:1]
	v_or_b32_e32 v0, 44, v16
	v_lshlrev_b64 v[32:33], 13, v[0:1]
	v_or_b32_e32 v0, 46, v16
	v_lshlrev_b64 v[34:35], 13, v[0:1]
	v_lshl_add_u64 v[20:21], v[18:19], 0, v[20:21]
	v_lshl_add_u64 v[34:35], v[18:19], 0, v[34:35]
	v_or_b32_e32 v0, 48, v16
	v_lshl_add_u64 v[22:23], v[18:19], 0, v[22:23]
	v_lshl_add_u64 v[24:25], v[18:19], 0, v[24:25]
	v_lshl_add_u64 v[26:27], v[18:19], 0, v[26:27]
	v_lshl_add_u64 v[28:29], v[18:19], 0, v[28:29]
	v_lshl_add_u64 v[30:31], v[18:19], 0, v[30:31]
	v_lshl_add_u64 v[32:33], v[18:19], 0, v[32:33]
	global_load_dword v52, v[20:21], off nt
	global_load_dword v53, v[22:23], off nt
	global_load_dword v54, v[24:25], off nt
	global_load_dword v55, v[26:27], off nt
	global_load_dword v56, v[28:29], off nt
	global_load_dword v57, v[30:31], off nt
	global_load_dword v58, v[32:33], off nt
	s_nop 0
	global_load_dword v34, v[34:35], off nt
	v_lshlrev_b64 v[20:21], 13, v[0:1]
	v_or_b32_e32 v0, 50, v16
	v_lshlrev_b64 v[22:23], 13, v[0:1]
	v_or_b32_e32 v0, 52, v16
	v_lshlrev_b64 v[24:25], 13, v[0:1]
	v_or_b32_e32 v0, 54, v16
	v_lshlrev_b64 v[26:27], 13, v[0:1]
	v_or_b32_e32 v0, 56, v16
	v_lshlrev_b64 v[28:29], 13, v[0:1]
	v_or_b32_e32 v0, 58, v16
	v_lshlrev_b64 v[30:31], 13, v[0:1]
	v_or_b32_e32 v0, 60, v16
	v_lshlrev_b64 v[32:33], 13, v[0:1]
	v_or_b32_e32 v0, 62, v16
	v_lshlrev_b64 v[16:17], 13, v[0:1]
	v_lshl_add_u64 v[20:21], v[18:19], 0, v[20:21]
	v_lshl_add_u64 v[22:23], v[18:19], 0, v[22:23]
	v_lshl_add_u64 v[16:17], v[18:19], 0, v[16:17]
	v_lshl_add_u64 v[24:25], v[18:19], 0, v[24:25]
	v_lshl_add_u64 v[26:27], v[18:19], 0, v[26:27]
	v_lshl_add_u64 v[28:29], v[18:19], 0, v[28:29]
	v_lshl_add_u64 v[30:31], v[18:19], 0, v[30:31]
	v_lshl_add_u64 v[32:33], v[18:19], 0, v[32:33]
	global_load_dword v0, v[20:21], off nt
	global_load_dword v18, v[22:23], off nt
	global_load_dword v19, v[24:25], off nt
	s_nop 0
	global_load_dword v20, v[26:27], off nt
	global_load_dword v21, v[28:29], off nt
	global_load_dword v22, v[30:31], off nt
	global_load_dword v23, v[32:33], off nt
	s_nop 0
	global_load_dword v16, v[16:17], off nt
	v_add_u32_e32 v17, 0x400, v5
	s_waitcnt vmcnt(0)
	ds_write2_b32 v5, v36, v37 offset1:66
	ds_write2_b32 v5, v38, v39 offset0:132 offset1:198
	ds_write2_b32 v17, v40, v41 offset0:8 offset1:74
	ds_write2_b32 v17, v42, v43 offset0:140 offset1:206
	v_add_u32_e32 v17, 0x800, v5
	ds_write2_b32 v17, v44, v45 offset0:16 offset1:82
	ds_write2_b32 v17, v46, v47 offset0:148 offset1:214
	v_add_u32_e32 v17, 0xc00, v5
	ds_write2_b32 v17, v48, v49 offset0:24 offset1:90
	ds_write2_b32 v17, v50, v51 offset0:156 offset1:222
	v_add_u32_e32 v17, 0x1000, v5
	ds_write2_b32 v17, v52, v53 offset0:32 offset1:98
	ds_write2_b32 v17, v54, v55 offset0:164 offset1:230
	v_add_u32_e32 v17, 0x1400, v5
	ds_write2_b32 v17, v56, v57 offset0:40 offset1:106
	ds_write2_b32 v17, v58, v34 offset0:172 offset1:238
	v_add_u32_e32 v17, 0x1800, v5
	ds_write2_b32 v17, v0, v18 offset0:48 offset1:114
	ds_write2_b32 v17, v19, v20 offset0:180 offset1:246
	v_add_u32_e32 v0, 0x1c00, v5
	ds_write2_b32 v0, v21, v22 offset0:56 offset1:122
	ds_write2_b32 v0, v23, v16 offset0:188 offset1:254
	s_waitcnt lgkmcnt(0)
	s_lshl_b64 s[4:5], s[60:61], 1
	ds_read2_b32 v[20:21], v8 offset0:33 offset1:41
	ds_read2_b32 v[22:23], v8 offset1:8
	ds_read2_b32 v[24:25], v8 offset0:66 offset1:74
	ds_read2_b32 v[26:27], v8 offset0:99 offset1:107
	ds_read2_b32 v[28:29], v8 offset0:132 offset1:140
	ds_read2_b32 v[30:31], v8 offset0:165 offset1:173
	ds_read2_b32 v[32:33], v8 offset0:198 offset1:206
	ds_read2_b32 v[34:35], v8 offset0:231 offset1:239
	s_add_u32 s4, s15, s4
	s_addc_u32 s5, s16, s5
	v_lshlrev_b32_e32 v0, 1, v6
	v_lshl_add_u64 v[16:17], s[4:5], 0, v[0:1]
	s_mov_b64 s[4:5], 0xa500000
	v_lshl_add_u64 v[36:37], v[16:17], 0, s[4:5]
	v_lshlrev_b32_e32 v0, 12, v15
	s_waitcnt lgkmcnt(6)
	v_cvt_pk_bf16_f32 v16, v22, v20
	s_waitcnt lgkmcnt(4)
	v_cvt_pk_bf16_f32 v17, v24, v26
	s_waitcnt lgkmcnt(2)
	v_cvt_pk_bf16_f32 v18, v28, v30
	s_waitcnt lgkmcnt(0)
	v_cvt_pk_bf16_f32 v19, v32, v34
	v_lshl_add_u64 v[38:39], v[36:37], 0, v[0:1]
	global_store_dwordx4 v[38:39], v[16:19], off sc1
	v_lshlrev_b32_e32 v0, 12, v14
	v_lshl_add_u64 v[14:15], v[36:37], 0, v[0:1]
	v_cvt_pk_bf16_f32 v16, v23, v21
	v_cvt_pk_bf16_f32 v17, v25, v27
	v_cvt_pk_bf16_f32 v18, v29, v31
	v_cvt_pk_bf16_f32 v19, v33, v35
	ds_read2_b32 v[20:21], v8 offset0:49 offset1:57
	ds_read2_b32 v[22:23], v8 offset0:16 offset1:24
	ds_read2_b32 v[24:25], v8 offset0:82 offset1:90
	ds_read2_b32 v[26:27], v8 offset0:115 offset1:123
	ds_read2_b32 v[28:29], v8 offset0:148 offset1:156
	ds_read2_b32 v[30:31], v8 offset0:181 offset1:189
	ds_read2_b32 v[32:33], v8 offset0:214 offset1:222
	ds_read2_b32 v[34:35], v8 offset0:247 offset1:255
	v_lshlrev_b32_e32 v0, 12, v13
	global_store_dwordx4 v[14:15], v[16:19], off sc1
	s_waitcnt lgkmcnt(6)
	v_cvt_pk_bf16_f32 v14, v22, v20
	s_waitcnt lgkmcnt(4)
	v_cvt_pk_bf16_f32 v15, v24, v26
	s_waitcnt lgkmcnt(2)
	v_cvt_pk_bf16_f32 v16, v28, v30
	s_waitcnt lgkmcnt(0)
	v_cvt_pk_bf16_f32 v17, v32, v34
	v_lshl_add_u64 v[18:19], v[36:37], 0, v[0:1]
	v_lshlrev_b32_e32 v0, 12, v12
	global_store_dwordx4 v[18:19], v[14:17], off sc1
	v_lshl_add_u64 v[12:13], v[36:37], 0, v[0:1]
	s_nop 0
	v_cvt_pk_bf16_f32 v14, v23, v21
	v_cvt_pk_bf16_f32 v15, v25, v27
	v_cvt_pk_bf16_f32 v16, v29, v31
	v_cvt_pk_bf16_f32 v17, v33, v35
	global_store_dwordx4 v[12:13], v[14:17], off sc1
	s_waitcnt lgkmcnt(0)

; #define LAS __attribute__((address_space(3)))
; __device__ __forceinline__ void transpose_item(const float* __restrict__ W, int ldw, int src_col0, bf16_t* WT, int K, int dst_row0, int k0, LAS float* scr, int lane) {
;     float tmp[32];
; #pragma unroll
;     for (int i = 0; i < 32; ++i) tmp[i] = __builtin_nontemporal_load(W + (size_t)(k0 + 2 * i + (lane >> 5)) * ldw + src_col0 + (lane & 31));
; __device__ __forceinline__ void convert_item(ArgsP a, const Ctx& c, int it, LAS float* scr) {
;     ...
;         if (r < I_SQ) { const int kb = r / 64, nb = r % 64; transpose_item(a->in[4] + (size_t)l * DM * DM, DM, 32 * nb, (bf16_t*)(wl + WL_OUT), DM, 32 * nb, 64 * kb, scr, c.lane); return; }
.LBB0_558:
	s_andn2_b64 vcc, exec, s[4:5]
	s_cbranch_vccnz .LBB0_560
	s_load_dwordx2 s[4:5], s[0:1], 0x20
	s_and_b32 s8, s17, 0xffc0
	s_lshl_b64 s[6:7], s[2:3], 24
	s_add_i32 s60, s8, 0xffff6400
	v_or_b32_e32 v12, s60, v3
	s_waitcnt lgkmcnt(0)
	s_add_u32 s4, s4, s6
	s_addc_u32 s5, s5, s7
	s_lshl_b32 s3, s10, 5
	s_and_b32 s3, s3, 0x7e0
	s_lshl_b32 s6, s3, 2
	s_add_u32 s4, s4, s6
	s_addc_u32 s5, s5, 0
	v_lshlrev_b32_e32 v0, 2, v4
	v_lshl_add_u64 v[14:15], s[4:5], 0, v[0:1]
	v_or_b32_e32 v0, 2, v12
	v_lshlrev_b64 v[18:19], 13, v[0:1]
	v_or_b32_e32 v0, 4, v12
	v_lshlrev_b64 v[20:21], 13, v[0:1]
	v_or_b32_e32 v0, 6, v12
	v_lshlrev_b64 v[22:23], 13, v[0:1]
	v_or_b32_e32 v0, 8, v12
	v_lshlrev_b64 v[24:25], 13, v[0:1]
	v_or_b32_e32 v0, 10, v12
	v_mov_b32_e32 v13, v1
	v_lshlrev_b64 v[26:27], 13, v[0:1]
	v_or_b32_e32 v0, 12, v12
	v_lshlrev_b64 v[16:17], 13, v[12:13]
	v_lshlrev_b64 v[28:29], 13, v[0:1]
	v_or_b32_e32 v0, 14, v12
	v_lshl_add_u64 v[16:17], v[14:15], 0, v[16:17]
	v_lshlrev_b64 v[30:31], 13, v[0:1]
	v_or_b32_e32 v0, 16, v12
	v_lshl_add_u64 v[18:19], v[14:15], 0, v[18:19]
	v_lshl_add_u64 v[20:21], v[14:15], 0, v[20:21]
	v_lshl_add_u64 v[22:23], v[14:15], 0, v[22:23]
	v_lshl_add_u64 v[24:25], v[14:15], 0, v[24:25]
	v_lshl_add_u64 v[26:27], v[14:15], 0, v[26:27]
	v_lshl_add_u64 v[28:29], v[14:15], 0, v[28:29]
	v_lshl_add_u64 v[30:31], v[14:15], 0, v[30:31]
	global_load_dword v32, v[16:17], off nt
	global_load_dword v33, v[18:19], off nt
	global_load_dword v34, v[20:21], off nt
	global_load_dword v35, v[22:23], off nt
	global_load_dword v36, v[24:25], off nt
	global_load_dword v37, v[26:27], off nt
	global_load_dword v38, v[28:29], off nt
	global_load_dword v39, v[30:31], off nt
	v_lshlrev_b64 v[16:17], 13, v[0:1]
	v_or_b32_e32 v0, 18, v12
	v_lshlrev_b64 v[18:19], 13, v[0:1]
	v_or_b32_e32 v0, 20, v12
	v_lshlrev_b64 v[20:21], 13, v[0:1]
	v_or_b32_e32 v0, 22, v12
	v_lshlrev_b64 v[22:23], 13, v[0:1]
	v_or_b32_e32 v0, 24, v12
	v_lshlrev_b64 v[24:25], 13, v[0:1]
	v_or_b32_e32 v0, 26, v12
	v_lshlrev_b64 v[26:27], 13, v[0:1]
	v_or_b32_e32 v0, 28, v12
	v_lshlrev_b64 v[28:29], 13, v[0:1]
	v_or_b32_e32 v0, 30, v12
	v_lshl_add_u64 v[16:17], v[14:15], 0, v[16:17]
	v_lshlrev_b64 v[30:31], 13, v[0:1]
	v_or_b32_e32 v0, 32, v12
	v_lshl_add_u64 v[18:19], v[14:15], 0, v[18:19]
	v_lshl_add_u64 v[20:21], v[14:15], 0, v[20:21]
	v_lshl_add_u64 v[22:23], v[14:15], 0, v[22:23]
	v_lshl_add_u64 v[24:25], v[14:15], 0, v[24:25]
	v_lshl_add_u64 v[26:27], v[14:15], 0, v[26:27]
	v_lshl_add_u64 v[28:29], v[14:15], 0, v[28:29]
	v_lshl_add_u64 v[30:31], v[14:15], 0, v[30:31]
	global_load_dword v40, v[16:17], off nt
	global_load_dword v41, v[18:19], off nt
	global_load_dword v42, v[20:21], off nt
	global_load_dword v43, v[22:23], off nt
	global_load_dword v44, v[24:25], off nt
	global_load_dword v45, v[26:27], off nt
	global_load_dword v46, v[28:29], off nt
	global_load_dword v47, v[30:31], off nt
	v_lshlrev_b64 v[16:17], 13, v[0:1]
	v_or_b32_e32 v0, 34, v12
	v_lshlrev_b64 v[18:19], 13, v[0:1]
	v_or_b32_e32 v0, 36, v12
	v_lshlrev_b64 v[20:21], 13, v[0:1]
	v_or_b32_e32 v0, 38, v12
	v_lshlrev_b64 v[22:23], 13, v[0:1]
	v_or_b32_e32 v0, 40, v12
	v_lshlrev_b64 v[24:25], 13, v[0:1]
	v_or_b32_e32 v0, 42, v12
	v_lshlrev_b64 v[26:27], 13, v[0:1]
	v_or_b32_e32 v0, 44, v12
	v_lshlrev_b64 v[28:29], 13, v[0:1]
	v_or_b32_e32 v0, 46, v12
	v_lshlrev_b64 v[30:31], 13, v[0:1]
	v_lshl_add_u64 v[16:17], v[14:15], 0, v[16:17]
	v_lshl_add_u64 v[30:31], v[14:15], 0, v[30:31]
	v_or_b32_e32 v0, 48, v12
	v_lshl_add_u64 v[18:19], v[14:15], 0, v[18:19]
	v_lshl_add_u64 v[20:21], v[14:15], 0, v[20:21]
	v_lshl_add_u64 v[22:23], v[14:15], 0, v[22:23]
	v_lshl_add_u64 v[24:25], v[14:15], 0, v[24:25]
	v_lshl_add_u64 v[26:27], v[14:15], 0, v[26:27]
	v_lshl_add_u64 v[28:29], v[14:15], 0, v[28:29]
	global_load_dword v48, v[16:17], off nt
	global_load_dword v49, v[18:19], off nt
	global_load_dword v50, v[20:21], off nt
	global_load_dword v51, v[22:23], off nt
	global_load_dword v52, v[24:25], off nt
	global_load_dword v53, v[26:27], off nt
	global_load_dword v54, v[28:29], off nt
	s_nop 0
	global_load_dword v30, v[30:31], off nt
	v_lshlrev_b64 v[16:17], 13, v[0:1]
	v_or_b32_e32 v0, 50, v12
	v_lshlrev_b64 v[18:19], 13, v[0:1]
	v_or_b32_e32 v0, 52, v12
	v_lshlrev_b64 v[20:21], 13, v[0:1]
	v_or_b32_e32 v0, 54, v12
	v_lshlrev_b64 v[22:23], 13, v[0:1]
	v_or_b32_e32 v0, 56, v12
	v_lshlrev_b64 v[24:25], 13, v[0:1]
	v_or_b32_e32 v0, 58, v12
	v_lshlrev_b64 v[26:27], 13, v[0:1]
	v_or_b32_e32 v0, 60, v12
	v_lshlrev_b64 v[28:29], 13, v[0:1]
	v_or_b32_e32 v0, 62, v12
	v_lshlrev_b64 v[12:13], 13, v[0:1]
	v_lshl_add_u64 v[16:17], v[14:15], 0, v[16:17]
	v_lshl_add_u64 v[18:19], v[14:15], 0, v[18:19]
	v_lshl_add_u64 v[12:13], v[14:15], 0, v[12:13]
	v_lshl_add_u64 v[20:21], v[14:15], 0, v[20:21]
	v_lshl_add_u64 v[22:23], v[14:15], 0, v[22:23]
	v_lshl_add_u64 v[24:25], v[14:15], 0, v[24:25]
	v_lshl_add_u64 v[26:27], v[14:15], 0, v[26:27]
	v_lshl_add_u64 v[28:29], v[14:15], 0, v[28:29]
	global_load_dword v0, v[16:17], off nt
	global_load_dword v14, v[18:19], off nt
	global_load_dword v15, v[20:21], off nt
	s_nop 0
	global_load_dword v16, v[22:23], off nt
	global_load_dword v17, v[24:25], off nt
	global_load_dword v18, v[26:27], off nt
	global_load_dword v19, v[28:29], off nt
	s_nop 0
	global_load_dword v12, v[12:13], off nt
	v_add_u32_e32 v13, 0x400, v5
	s_waitcnt vmcnt(0)
; #define LAS __attribute__((address_space(3)))
; __device__ __forceinline__ unsigned pk_bf16(float lo, float hi) { f32x2 v = {lo, hi}; bf16x2_t b = __builtin_convertvector(v, bf16x2_t); return __builtin_bit_cast(unsigned, b); }
; #define LDS_WAIT() asm volatile("s_waitcnt lgkmcnt(0)" ::: "memory")
; __device__ __forceinline__ void transpose_item(const float* __restrict__ W, int ldw, int src_col0, bf16_t* WT, int K, int dst_row0, int k0, LAS float* scr, int lane) {
;     ...
; #pragma unroll
;     for (int i = 0; i < 32; ++i) scr[(2 * i + (lane >> 5)) * 33 + (lane & 31)] = tmp[i];
;     LDS_WAIT();
;     const int c = lane & 7;
; #pragma unroll
;     for (int j = 0; j < 4; ++j) { const int n = (lane >> 3) + 8 * j; const LAS float* s = scr + (8 * c) * 33 + n;
;         u32x4 o; o.x = pk_bf16(s[0 * 33], s[1 * 33]); o.y = pk_bf16(s[2 * 33], s[3 * 33]); o.z = pk_bf16(s[4 * 33], s[5 * 33]); o.w = pk_bf16(s[6 * 33], s[7 * 33]);
;         *(u32x4*)(WT + (size_t)(dst_row0 + n) * K + k0 + 8 * c) = o; }
; __device__ __forceinline__ void convert_item(ArgsP a, const Ctx& c, int it, LAS float* scr) {
;     ...
;         if (r < I_SQ) { const int kb = r / 64, nb = r % 64; transpose_item(a->in[4] + (size_t)l * DM * DM, DM, 32 * nb, (bf16_t*)(wl + WL_OUT), DM, 32 * nb, 64 * kb, scr, c.lane); return; }
	ds_write2_b32 v5, v32, v33 offset1:66
	ds_write2_b32 v5, v34, v35 offset0:132 offset1:198
	ds_write2_b32 v13, v36, v37 offset0:8 offset1:74
	ds_write2_b32 v13, v38, v39 offset0:140 offset1:206
	v_add_u32_e32 v13, 0x800, v5
	ds_write2_b32 v13, v40, v41 offset0:16 offset1:82
	ds_write2_b32 v13, v42, v43 offset0:148 offset1:214
	v_add_u32_e32 v13, 0xc00, v5
	ds_write2_b32 v13, v44, v45 offset0:24 offset1:90
	ds_write2_b32 v13, v46, v47 offset0:156 offset1:222
	v_add_u32_e32 v13, 0x1000, v5
	ds_write2_b32 v13, v48, v49 offset0:32 offset1:98
	ds_write2_b32 v13, v50, v51 offset0:164 offset1:230
	v_add_u32_e32 v13, 0x1400, v5
	ds_write2_b32 v13, v52, v53 offset0:40 offset1:106
	ds_write2_b32 v13, v54, v30 offset0:172 offset1:238
	v_add_u32_e32 v13, 0x1800, v5
	ds_write2_b32 v13, v0, v14 offset0:48 offset1:114
	ds_write2_b32 v13, v15, v16 offset0:180 offset1:246
	v_add_u32_e32 v0, 0x1c00, v5
	ds_write2_b32 v0, v17, v18 offset0:56 offset1:122
	ds_write2_b32 v0, v19, v12 offset0:188 offset1:254
	s_waitcnt lgkmcnt(0)
	s_lshl_b64 s[4:5], s[60:61], 1
	ds_read2_b32 v[16:17], v8 offset0:33 offset1:41
	ds_read2_b32 v[18:19], v8 offset1:8
	ds_read2_b32 v[20:21], v8 offset0:66 offset1:74
	ds_read2_b32 v[22:23], v8 offset0:99 offset1:107
	ds_read2_b32 v[24:25], v8 offset0:132 offset1:140
	ds_read2_b32 v[26:27], v8 offset0:165 offset1:173
	ds_read2_b32 v[28:29], v8 offset0:198 offset1:206
	ds_read2_b32 v[30:31], v8 offset0:231 offset1:239
	s_add_u32 s4, s15, s4
	s_addc_u32 s5, s16, s5
	v_lshlrev_b32_e32 v0, 1, v6
	v_lshl_add_u64 v[12:13], s[4:5], 0, v[0:1]
	s_mov_b64 s[4:5], 0x5a00000
	v_or_b32_e32 v0, s3, v7
	v_lshl_add_u64 v[32:33], v[12:13], 0, s[4:5]
	v_lshlrev_b32_e32 v0, 12, v0
	s_waitcnt lgkmcnt(6)
	v_cvt_pk_bf16_f32 v12, v18, v16
	s_waitcnt lgkmcnt(4)
	v_cvt_pk_bf16_f32 v13, v20, v22
	s_waitcnt lgkmcnt(2)
	v_cvt_pk_bf16_f32 v14, v24, v26
	s_waitcnt lgkmcnt(0)
	v_cvt_pk_bf16_f32 v15, v28, v30
	v_lshl_add_u64 v[34:35], v[32:33], 0, v[0:1]
	global_store_dwordx4 v[34:35], v[12:15], off sc1
	v_or_b32_e32 v0, s3, v9
	v_lshlrev_b32_e32 v0, 12, v0
	v_cvt_pk_bf16_f32 v12, v19, v17
	v_cvt_pk_bf16_f32 v13, v21, v23
	v_cvt_pk_bf16_f32 v14, v25, v27
	v_cvt_pk_bf16_f32 v15, v29, v31
	ds_read2_b32 v[18:19], v8 offset0:49 offset1:57
	ds_read2_b32 v[20:21], v8 offset0:16 offset1:24
	ds_read2_b32 v[22:23], v8 offset0:82 offset1:90
	ds_read2_b32 v[24:25], v8 offset0:115 offset1:123
	ds_read2_b32 v[26:27], v8 offset0:148 offset1:156
	ds_read2_b32 v[28:29], v8 offset0:181 offset1:189
	ds_read2_b32 v[30:31], v8 offset0:214 offset1:222
	ds_read2_b32 v[34:35], v8 offset0:247 offset1:255
	v_lshl_add_u64 v[16:17], v[32:33], 0, v[0:1]
	v_or_b32_e32 v0, s3, v10
	v_lshlrev_b32_e32 v0, 12, v0
	global_store_dwordx4 v[16:17], v[12:15], off sc1
	v_lshl_add_u64 v[16:17], v[32:33], 0, v[0:1]
	v_or_b32_e32 v0, s3, v11
	s_waitcnt lgkmcnt(6)
	v_cvt_pk_bf16_f32 v12, v20, v18
	s_waitcnt lgkmcnt(4)
	v_cvt_pk_bf16_f32 v13, v22, v24
	s_waitcnt lgkmcnt(2)
	v_cvt_pk_bf16_f32 v14, v26, v28
	s_waitcnt lgkmcnt(0)
	v_cvt_pk_bf16_f32 v15, v30, v34
	v_lshlrev_b32_e32 v0, 12, v0
	global_store_dwordx4 v[16:17], v[12:15], off sc1
	v_lshl_add_u64 v[16:17], v[32:33], 0, v[0:1]
	s_nop 0
	v_cvt_pk_bf16_f32 v12, v21, v19
	v_cvt_pk_bf16_f32 v13, v23, v25
	v_cvt_pk_bf16_f32 v14, v27, v29
	v_cvt_pk_bf16_f32 v15, v31, v35
	global_store_dwordx4 v[16:17], v[12:15], off sc1
	s_waitcnt lgkmcnt(0)

; __device__ __forceinline__ void transpose_item(const float* __restrict__ W, int ldw, int src_col0, bf16_t* WT, int K, int dst_row0, int k0, LAS float* scr, int lane) {
;     ...
;     for (int i = 0; i < 32; ++i) tmp[i] = __builtin_nontemporal_load(W + (size_t)(k0 + 2 * i + (lane >> 5)) * ldw + src_col0 + (lane & 31));
; __device__ __forceinline__ void convert_item(ArgsP a, const Ctx& c, int it, LAS float* scr) {
;     ...
;         if (r < I_SQ) { const int kb = r / 64, nb = r % 64, row0 = 32 * nb; const int sc = row0 < 768 ? W_DV + row0 : (row0 < 1280 ? W_GV + (row0 - 768) : W_MV + (row0 - 1280));
;             transpose_item(a->in[3] + (size_t)l * DM * DIN, DIN, sc, (bf16_t*)(wl + WL_V), DM, row0, 64 * kb, scr, c.lane); return; }
.LBB0_570:
	s_load_dwordx2 s[6:7], s[0:1], 0x18
	s_and_b32 s4, s17, 0xffc0
	s_mul_i32 s8, s2, 0x3020000
	s_add_i32 s4, s4, 0xffff6c00
	s_mul_hi_i32 s5, s2, 0x3020000
	s_waitcnt lgkmcnt(0)
	s_add_u32 s8, s6, s8
	s_addc_u32 s5, s7, s5
	s_lshl_b64 s[6:7], s[60:61], 2
	s_add_u32 s6, s8, s6
	v_or_b32_e32 v30, s4, v3
	s_addc_u32 s7, s5, s7
	v_lshlrev_b32_e32 v0, 2, v4
	v_lshl_add_u64 v[12:13], s[6:7], 0, v[0:1]
	v_or_b32_e32 v0, 2, v30
	v_mad_u64_u32 v[16:17], s[6:7], v0, s75, v[12:13]
	v_or_b32_e32 v0, 4, v30
	v_mad_u64_u32 v[18:19], s[6:7], v0, s75, v[12:13]
	v_or_b32_e32 v0, 6, v30
	v_mad_u64_u32 v[20:21], s[6:7], v0, s75, v[12:13]
	v_or_b32_e32 v0, 8, v30
	v_mad_u64_u32 v[22:23], s[6:7], v0, s75, v[12:13]
	v_or_b32_e32 v0, 10, v30
	v_mad_u64_u32 v[24:25], s[6:7], v0, s75, v[12:13]
	v_or_b32_e32 v0, 12, v30
	v_mad_u64_u32 v[26:27], s[6:7], v0, s75, v[12:13]
	v_or_b32_e32 v0, 14, v30
	v_mad_u64_u32 v[14:15], s[6:7], v30, s75, v[12:13]
	v_mad_u64_u32 v[28:29], s[6:7], v0, s75, v[12:13]
	global_load_dword v0, v[14:15], off nt
	global_load_dword v31, v[16:17], off nt
	global_load_dword v32, v[18:19], off nt
	global_load_dword v33, v[20:21], off nt
	global_load_dword v34, v[22:23], off nt
	global_load_dword v35, v[24:25], off nt
	global_load_dword v36, v[26:27], off nt
	global_load_dword v37, v[28:29], off nt
	v_or_b32_e32 v14, 16, v30
	v_or_b32_e32 v16, 18, v30
	v_or_b32_e32 v18, 20, v30
	v_or_b32_e32 v20, 22, v30
	v_or_b32_e32 v22, 24, v30
	v_or_b32_e32 v24, 26, v30
	v_or_b32_e32 v26, 28, v30
	v_or_b32_e32 v28, 30, v30
	v_mad_u64_u32 v[14:15], s[6:7], v14, s75, v[12:13]
	v_mad_u64_u32 v[16:17], s[6:7], v16, s75, v[12:13]
	v_mad_u64_u32 v[18:19], s[6:7], v18, s75, v[12:13]
	v_mad_u64_u32 v[20:21], s[6:7], v20, s75, v[12:13]
	v_mad_u64_u32 v[22:23], s[6:7], v22, s75, v[12:13]
	v_mad_u64_u32 v[24:25], s[6:7], v24, s75, v[12:13]
	v_mad_u64_u32 v[26:27], s[6:7], v26, s75, v[12:13]
	v_mad_u64_u32 v[28:29], s[6:7], v28, s75, v[12:13]
	global_load_dword v38, v[14:15], off nt
	global_load_dword v39, v[16:17], off nt
	global_load_dword v40, v[18:19], off nt
	global_load_dword v41, v[20:21], off nt
	global_load_dword v42, v[22:23], off nt
	global_load_dword v43, v[24:25], off nt
	global_load_dword v44, v[26:27], off nt
	global_load_dword v45, v[28:29], off nt
	v_or_b32_e32 v14, 32, v30
	v_or_b32_e32 v16, 34, v30
	v_or_b32_e32 v18, 36, v30
	v_or_b32_e32 v20, 38, v30
	v_or_b32_e32 v22, 40, v30
	v_or_b32_e32 v24, 42, v30
	v_or_b32_e32 v26, 44, v30
	v_or_b32_e32 v28, 46, v30
	v_mad_u64_u32 v[14:15], s[6:7], v14, s75, v[12:13]
	v_mad_u64_u32 v[16:17], s[6:7], v16, s75, v[12:13]
	v_mad_u64_u32 v[18:19], s[6:7], v18, s75, v[12:13]
	v_mad_u64_u32 v[20:21], s[6:7], v20, s75, v[12:13]
	v_mad_u64_u32 v[22:23], s[6:7], v22, s75, v[12:13]
	v_mad_u64_u32 v[24:25], s[6:7], v24, s75, v[12:13]
	v_mad_u64_u32 v[26:27], s[6:7], v26, s75, v[12:13]
	v_mad_u64_u32 v[28:29], s[6:7], v28, s75, v[12:13]
	global_load_dword v46, v[14:15], off nt
	global_load_dword v47, v[16:17], off nt
	global_load_dword v48, v[18:19], off nt
	global_load_dword v49, v[20:21], off nt
	global_load_dword v50, v[22:23], off nt
	global_load_dword v51, v[24:25], off nt
	global_load_dword v52, v[26:27], off nt
	s_nop 0
	global_load_dword v28, v[28:29], off nt
	v_or_b32_e32 v14, 48, v30
	v_or_b32_e32 v16, 50, v30
	v_or_b32_e32 v18, 52, v30
	v_or_b32_e32 v20, 54, v30
	v_or_b32_e32 v22, 56, v30
	v_or_b32_e32 v24, 58, v30
	v_or_b32_e32 v26, 60, v30
	v_or_b32_e32 v29, 62, v30
	v_mad_u64_u32 v[14:15], s[6:7], v14, s75, v[12:13]
	v_mad_u64_u32 v[16:17], s[6:7], v16, s75, v[12:13]
	v_mad_u64_u32 v[18:19], s[6:7], v18, s75, v[12:13]
	v_mad_u64_u32 v[20:21], s[6:7], v20, s75, v[12:13]
	v_mad_u64_u32 v[22:23], s[6:7], v22, s75, v[12:13]
	v_mad_u64_u32 v[24:25], s[6:7], v24, s75, v[12:13]
	v_mad_u64_u32 v[26:27], s[6:7], v26, s75, v[12:13]
	v_mad_u64_u32 v[12:13], s[6:7], v29, s75, v[12:13]
	global_load_dword v14, v[14:15], off nt
	s_nop 0
	global_load_dword v15, v[16:17], off nt
	s_nop 0
	global_load_dword v16, v[18:19], off nt
	global_load_dword v17, v[20:21], off nt
	s_nop 0
	global_load_dword v18, v[22:23], off nt
	global_load_dword v19, v[24:25], off nt
	global_load_dword v20, v[26:27], off nt
	s_nop 0
	global_load_dword v12, v[12:13], off nt
	s_waitcnt vmcnt(0)
; #define LAS __attribute__((address_space(3)))
; __device__ __forceinline__ unsigned pk_bf16(float lo, float hi) { f32x2 v = {lo, hi}; bf16x2_t b = __builtin_convertvector(v, bf16x2_t); return __builtin_bit_cast(unsigned, b); }
; #define LDS_WAIT() asm volatile("s_waitcnt lgkmcnt(0)" ::: "memory")
; __device__ __forceinline__ void transpose_item(const float* __restrict__ W, int ldw, int src_col0, bf16_t* WT, int K, int dst_row0, int k0, LAS float* scr, int lane) {
;     ...
; #pragma unroll
;     for (int i = 0; i < 32; ++i) scr[(2 * i + (lane >> 5)) * 33 + (lane & 31)] = tmp[i];
;     LDS_WAIT();
;     const int c = lane & 7;
; #pragma unroll
;     for (int j = 0; j < 4; ++j) { const int n = (lane >> 3) + 8 * j; const LAS float* s = scr + (8 * c) * 33 + n;
;         u32x4 o; o.x = pk_bf16(s[0 * 33], s[1 * 33]); o.y = pk_bf16(s[2 * 33], s[3 * 33]); o.z = pk_bf16(s[4 * 33], s[5 * 33]); o.w = pk_bf16(s[6 * 33], s[7 * 33]);
;         *(u32x4*)(WT + (size_t)(dst_row0 + n) * K + k0 + 8 * c) = o; }
; __device__ __forceinline__ void convert_item(ArgsP a, const Ctx& c, int it, LAS float* scr) {
;     ...
;         if (r < I_SQ) { const int kb = r / 64, nb = r % 64, row0 = 32 * nb; const int sc = row0 < 768 ? W_DV + row0 : (row0 < 1280 ? W_GV + (row0 - 768) : W_MV + (row0 - 1280));
;             transpose_item(a->in[3] + (size_t)l * DM * DIN, DIN, sc, (bf16_t*)(wl + WL_V), DM, row0, 64 * kb, scr, c.lane); return; }
	ds_write2_b32 v5, v0, v31 offset1:66
	ds_write2_b32 v5, v32, v33 offset0:132 offset1:198
	v_add_u32_e32 v0, 0x400, v5
	ds_write2_b32 v0, v34, v35 offset0:8 offset1:74
	ds_write2_b32 v0, v36, v37 offset0:140 offset1:206
	v_add_u32_e32 v0, 0x800, v5
	ds_write2_b32 v0, v38, v39 offset0:16 offset1:82
	ds_write2_b32 v0, v40, v41 offset0:148 offset1:214
	v_add_u32_e32 v0, 0xc00, v5
	ds_write2_b32 v0, v42, v43 offset0:24 offset1:90
	ds_write2_b32 v0, v44, v45 offset0:156 offset1:222
	v_add_u32_e32 v0, 0x1000, v5
	ds_write2_b32 v0, v46, v47 offset0:32 offset1:98
	ds_write2_b32 v0, v48, v49 offset0:164 offset1:230
	v_add_u32_e32 v0, 0x1400, v5
	ds_write2_b32 v0, v50, v51 offset0:40 offset1:106
	ds_write2_b32 v0, v52, v28 offset0:172 offset1:238
	v_add_u32_e32 v0, 0x1800, v5
	ds_write2_b32 v0, v14, v15 offset0:48 offset1:114
	ds_write2_b32 v0, v16, v17 offset0:180 offset1:246
	v_add_u32_e32 v0, 0x1c00, v5
	ds_write2_b32 v0, v18, v19 offset0:56 offset1:122
	ds_write2_b32 v0, v20, v12 offset0:188 offset1:254
	s_waitcnt lgkmcnt(0)
	s_mov_b32 s5, s61
	s_lshl_b64 s[4:5], s[4:5], 1
	ds_read2_b32 v[16:17], v8 offset0:33 offset1:41
	ds_read2_b32 v[18:19], v8 offset1:8
	ds_read2_b32 v[20:21], v8 offset0:66 offset1:74
	ds_read2_b32 v[22:23], v8 offset0:99 offset1:107
	ds_read2_b32 v[24:25], v8 offset0:132 offset1:140
	ds_read2_b32 v[26:27], v8 offset0:165 offset1:173
	ds_read2_b32 v[28:29], v8 offset0:198 offset1:206
	ds_read2_b32 v[30:31], v8 offset0:231 offset1:239
	s_add_u32 s4, s15, s4
	s_addc_u32 s5, s16, s5
	v_lshlrev_b32_e32 v0, 1, v6
	v_lshl_add_u64 v[12:13], s[4:5], 0, v[0:1]
	s_mov_b64 s[4:5], 0x5200000
	v_or_b32_e32 v0, s3, v7
	v_lshl_add_u64 v[32:33], v[12:13], 0, s[4:5]
	v_lshlrev_b32_e32 v0, 12, v0
	s_waitcnt lgkmcnt(6)
	v_cvt_pk_bf16_f32 v12, v18, v16
	s_waitcnt lgkmcnt(4)
	v_cvt_pk_bf16_f32 v13, v20, v22
	s_waitcnt lgkmcnt(2)
	v_cvt_pk_bf16_f32 v14, v24, v26
	s_waitcnt lgkmcnt(0)
	v_cvt_pk_bf16_f32 v15, v28, v30
	v_lshl_add_u64 v[34:35], v[32:33], 0, v[0:1]
	global_store_dwordx4 v[34:35], v[12:15], off sc1
	v_or_b32_e32 v0, s3, v9
	v_lshlrev_b32_e32 v0, 12, v0
	v_cvt_pk_bf16_f32 v12, v19, v17
	v_cvt_pk_bf16_f32 v13, v21, v23
	v_cvt_pk_bf16_f32 v14, v25, v27
	v_cvt_pk_bf16_f32 v15, v29, v31
	ds_read2_b32 v[18:19], v8 offset0:49 offset1:57
	ds_read2_b32 v[20:21], v8 offset0:16 offset1:24
	ds_read2_b32 v[22:23], v8 offset0:82 offset1:90
	ds_read2_b32 v[24:25], v8 offset0:115 offset1:123
	ds_read2_b32 v[26:27], v8 offset0:148 offset1:156
	ds_read2_b32 v[28:29], v8 offset0:181 offset1:189
	ds_read2_b32 v[30:31], v8 offset0:214 offset1:222
	ds_read2_b32 v[34:35], v8 offset0:247 offset1:255
	v_lshl_add_u64 v[16:17], v[32:33], 0, v[0:1]
	v_or_b32_e32 v0, s3, v10
	v_lshlrev_b32_e32 v0, 12, v0
	global_store_dwordx4 v[16:17], v[12:15], off sc1
	v_lshl_add_u64 v[16:17], v[32:33], 0, v[0:1]
	v_or_b32_e32 v0, s3, v11
	s_waitcnt lgkmcnt(6)
	v_cvt_pk_bf16_f32 v12, v20, v18
	s_waitcnt lgkmcnt(4)
	v_cvt_pk_bf16_f32 v13, v22, v24
	s_waitcnt lgkmcnt(2)
	v_cvt_pk_bf16_f32 v14, v26, v28
	s_waitcnt lgkmcnt(0)
	v_cvt_pk_bf16_f32 v15, v30, v34
	v_lshlrev_b32_e32 v0, 12, v0
	global_store_dwordx4 v[16:17], v[12:15], off sc1
	v_lshl_add_u64 v[16:17], v[32:33], 0, v[0:1]
	s_nop 0
	v_cvt_pk_bf16_f32 v12, v21, v19
	v_cvt_pk_bf16_f32 v13, v23, v25
	v_cvt_pk_bf16_f32 v14, v27, v29
	v_cvt_pk_bf16_f32 v15, v31, v35
	global_store_dwordx4 v[16:17], v[12:15], off sc1
	s_waitcnt lgkmcnt(0)

; __device__ __forceinline__ void transpose_item(const float* __restrict__ W, int ldw, int src_col0, bf16_t* WT, int K, int dst_row0, int k0, LAS float* scr, int lane) {
;     ...
;     for (int i = 0; i < 32; ++i) tmp[i] = __builtin_nontemporal_load(W + (size_t)(k0 + 2 * i + (lane >> 5)) * ldw + src_col0 + (lane & 31));
; __device__ __forceinline__ int win_src_col(int gidx) {
;     const int pn = gidx >> 3, w = gidx & 7;
;     if (pn < 6) { const int g = pn / 3, tg = pn % 3, half = w >> 2, u = w & 3; return (g ? W_DK : W_DQ) + (tg * 4 + u) * 64 + half * 32; }
;     if (pn < 12) { const int pp = pn - 6, g = pp / 3, tg = pp % 3, half = w >> 2, ww = w & 3; return (g ? W_MK : W_MQ) + (tg * 2 + (ww >> 1)) * 128 + half * 64 + (ww & 1) * 32; }
;     if (pn == 12) return W_GQ + 32 * w;
;     if (pn == 13) return W_GK + 32 * w;
;     return W_GR + (pn - 14) * 256 + 32 * w;
; }
; __device__ __forceinline__ void convert_item(ArgsP a, const Ctx& c, int it, LAS float* scr) {
;     ...
;         if (r < I_IN) { const int kb = r / 128, gidx = r % 128;
;             transpose_item(a->in[3] + (size_t)l * DM * DIN, DIN, win_src_col(gidx), (bf16_t*)(wl + WL_IN), DM, 32 * gidx, 64 * kb, scr, c.lane); return; }
.LBB0_592:
	s_add_i32 s5, s17, 0xffff7c00
	s_mul_i32 s9, s2, 0x3020000
	s_mul_hi_i32 s8, s2, 0x3020000
	s_waitcnt lgkmcnt(0)
	s_add_u32 s6, s6, s9
	s_addc_u32 s7, s7, s8
	s_lshr_b32 s5, s5, 1
	s_and_b32 s8, s5, 0x7fffffc0
	s_ashr_i32 s5, s4, 31
	s_lshl_b32 s3, s3, 5
	s_lshl_b64 s[4:5], s[4:5], 2
	s_add_u32 s4, s6, s4
	v_or_b32_e32 v30, s8, v3
	s_addc_u32 s5, s7, s5
	v_lshlrev_b32_e32 v0, 2, v4
	v_lshl_add_u64 v[12:13], s[4:5], 0, v[0:1]
	v_or_b32_e32 v0, 2, v30
	v_mad_u64_u32 v[16:17], s[4:5], v0, s75, v[12:13]
	v_or_b32_e32 v0, 4, v30
	v_mad_u64_u32 v[18:19], s[4:5], v0, s75, v[12:13]
	v_or_b32_e32 v0, 6, v30
	v_mad_u64_u32 v[20:21], s[4:5], v0, s75, v[12:13]
	v_or_b32_e32 v0, 8, v30
	v_mad_u64_u32 v[22:23], s[4:5], v0, s75, v[12:13]
	v_or_b32_e32 v0, 10, v30
	v_mad_u64_u32 v[24:25], s[4:5], v0, s75, v[12:13]
	v_or_b32_e32 v0, 12, v30
	v_mad_u64_u32 v[26:27], s[4:5], v0, s75, v[12:13]
	v_or_b32_e32 v0, 14, v30
	v_mad_u64_u32 v[14:15], s[4:5], v30, s75, v[12:13]
	v_mad_u64_u32 v[28:29], s[4:5], v0, s75, v[12:13]
	global_load_dword v0, v[14:15], off nt
	global_load_dword v31, v[16:17], off nt
	global_load_dword v32, v[18:19], off nt
	global_load_dword v33, v[20:21], off nt
	global_load_dword v34, v[22:23], off nt
	global_load_dword v35, v[24:25], off nt
	global_load_dword v36, v[26:27], off nt
	global_load_dword v37, v[28:29], off nt
	v_or_b32_e32 v14, 16, v30
	v_or_b32_e32 v16, 18, v30
	v_or_b32_e32 v18, 20, v30
	v_or_b32_e32 v20, 22, v30
	v_or_b32_e32 v22, 24, v30
	v_or_b32_e32 v24, 26, v30
	v_or_b32_e32 v26, 28, v30
	v_or_b32_e32 v28, 30, v30
	v_mad_u64_u32 v[14:15], s[4:5], v14, s75, v[12:13]
	v_mad_u64_u32 v[16:17], s[4:5], v16, s75, v[12:13]
	v_mad_u64_u32 v[18:19], s[4:5], v18, s75, v[12:13]
	v_mad_u64_u32 v[20:21], s[4:5], v20, s75, v[12:13]
	v_mad_u64_u32 v[22:23], s[4:5], v22, s75, v[12:13]
	v_mad_u64_u32 v[24:25], s[4:5], v24, s75, v[12:13]
	v_mad_u64_u32 v[26:27], s[4:5], v26, s75, v[12:13]
	v_mad_u64_u32 v[28:29], s[4:5], v28, s75, v[12:13]
	global_load_dword v38, v[14:15], off nt
	global_load_dword v39, v[16:17], off nt
	global_load_dword v40, v[18:19], off nt
	global_load_dword v41, v[20:21], off nt
	global_load_dword v42, v[22:23], off nt
	global_load_dword v43, v[24:25], off nt
	global_load_dword v44, v[26:27], off nt
	global_load_dword v45, v[28:29], off nt
	v_or_b32_e32 v14, 32, v30
	v_or_b32_e32 v16, 34, v30
	v_or_b32_e32 v18, 36, v30
	v_or_b32_e32 v20, 38, v30
	v_or_b32_e32 v22, 40, v30
	v_or_b32_e32 v24, 42, v30
	v_or_b32_e32 v26, 44, v30
	v_or_b32_e32 v28, 46, v30
	v_mad_u64_u32 v[14:15], s[4:5], v14, s75, v[12:13]
	v_mad_u64_u32 v[16:17], s[4:5], v16, s75, v[12:13]
	v_mad_u64_u32 v[18:19], s[4:5], v18, s75, v[12:13]
	v_mad_u64_u32 v[20:21], s[4:5], v20, s75, v[12:13]
	v_mad_u64_u32 v[22:23], s[4:5], v22, s75, v[12:13]
	v_mad_u64_u32 v[24:25], s[4:5], v24, s75, v[12:13]
	v_mad_u64_u32 v[26:27], s[4:5], v26, s75, v[12:13]
	v_mad_u64_u32 v[28:29], s[4:5], v28, s75, v[12:13]
	global_load_dword v46, v[14:15], off nt
	global_load_dword v47, v[16:17], off nt
	global_load_dword v48, v[18:19], off nt
	global_load_dword v49, v[20:21], off nt
	global_load_dword v50, v[22:23], off nt
	global_load_dword v51, v[24:25], off nt
	global_load_dword v52, v[26:27], off nt
	s_nop 0
	global_load_dword v28, v[28:29], off nt
	v_or_b32_e32 v14, 48, v30
	v_or_b32_e32 v16, 50, v30
	v_or_b32_e32 v18, 52, v30
	v_or_b32_e32 v20, 54, v30
	v_or_b32_e32 v22, 56, v30
	v_or_b32_e32 v24, 58, v30
	v_or_b32_e32 v26, 60, v30
	v_or_b32_e32 v29, 62, v30
	v_mad_u64_u32 v[14:15], s[4:5], v14, s75, v[12:13]
	v_mad_u64_u32 v[16:17], s[4:5], v16, s75, v[12:13]
	v_mad_u64_u32 v[18:19], s[4:5], v18, s75, v[12:13]
	v_mad_u64_u32 v[20:21], s[4:5], v20, s75, v[12:13]
	v_mad_u64_u32 v[22:23], s[4:5], v22, s75, v[12:13]
	v_mad_u64_u32 v[24:25], s[4:5], v24, s75, v[12:13]
	v_mad_u64_u32 v[26:27], s[4:5], v26, s75, v[12:13]
	v_mad_u64_u32 v[12:13], s[4:5], v29, s75, v[12:13]
	global_load_dword v14, v[14:15], off nt
	s_nop 0
	global_load_dword v15, v[16:17], off nt
	s_nop 0
	global_load_dword v16, v[18:19], off nt
	global_load_dword v17, v[20:21], off nt
	s_nop 0
	global_load_dword v18, v[22:23], off nt
	global_load_dword v19, v[24:25], off nt
	global_load_dword v20, v[26:27], off nt
	s_nop 0
	global_load_dword v12, v[12:13], off nt
	s_waitcnt vmcnt(0)
; #define LAS __attribute__((address_space(3)))
; __device__ __forceinline__ unsigned pk_bf16(float lo, float hi) { f32x2 v = {lo, hi}; bf16x2_t b = __builtin_convertvector(v, bf16x2_t); return __builtin_bit_cast(unsigned, b); }
; #define LDS_WAIT() asm volatile("s_waitcnt lgkmcnt(0)" ::: "memory")
; __device__ __forceinline__ void transpose_item(const float* __restrict__ W, int ldw, int src_col0, bf16_t* WT, int K, int dst_row0, int k0, LAS float* scr, int lane) {
;     ...
; #pragma unroll
;     for (int i = 0; i < 32; ++i) scr[(2 * i + (lane >> 5)) * 33 + (lane & 31)] = tmp[i];
;     LDS_WAIT();
;     const int c = lane & 7;
; #pragma unroll
;     for (int j = 0; j < 4; ++j) { const int n = (lane >> 3) + 8 * j; const LAS float* s = scr + (8 * c) * 33 + n;
;         u32x4 o; o.x = pk_bf16(s[0 * 33], s[1 * 33]); o.y = pk_bf16(s[2 * 33], s[3 * 33]); o.z = pk_bf16(s[4 * 33], s[5 * 33]); o.w = pk_bf16(s[6 * 33], s[7 * 33]);
;         *(u32x4*)(WT + (size_t)(dst_row0 + n) * K + k0 + 8 * c) = o; }
; __device__ __forceinline__ void convert_item(ArgsP a, const Ctx& c, int it, LAS float* scr) {
;     ...
;         if (r < I_IN) { const int kb = r / 128, gidx = r % 128;
;             transpose_item(a->in[3] + (size_t)l * DM * DIN, DIN, win_src_col(gidx), (bf16_t*)(wl + WL_IN), DM, 32 * gidx, 64 * kb, scr, c.lane); return; }
	ds_write2_b32 v5, v0, v31 offset1:66
	ds_write2_b32 v5, v32, v33 offset0:132 offset1:198
	v_add_u32_e32 v0, 0x400, v5
	ds_write2_b32 v0, v34, v35 offset0:8 offset1:74
	ds_write2_b32 v0, v36, v37 offset0:140 offset1:206
	v_add_u32_e32 v0, 0x800, v5
	ds_write2_b32 v0, v38, v39 offset0:16 offset1:82
	ds_write2_b32 v0, v40, v41 offset0:148 offset1:214
	v_add_u32_e32 v0, 0xc00, v5
	ds_write2_b32 v0, v42, v43 offset0:24 offset1:90
	ds_write2_b32 v0, v44, v45 offset0:156 offset1:222
	v_add_u32_e32 v0, 0x1000, v5
	ds_write2_b32 v0, v46, v47 offset0:32 offset1:98
	ds_write2_b32 v0, v48, v49 offset0:164 offset1:230
	v_add_u32_e32 v0, 0x1400, v5
	ds_write2_b32 v0, v50, v51 offset0:40 offset1:106
	ds_write2_b32 v0, v52, v28 offset0:172 offset1:238
	v_add_u32_e32 v0, 0x1800, v5
	ds_write2_b32 v0, v14, v15 offset0:48 offset1:114
	ds_write2_b32 v0, v16, v17 offset0:180 offset1:246
	v_add_u32_e32 v0, 0x1c00, v5
	ds_write2_b32 v0, v18, v19 offset0:56 offset1:122
	ds_write2_b32 v0, v20, v12 offset0:188 offset1:254
	s_waitcnt lgkmcnt(0)
	s_lshl_b32 s4, s8, 1
	ds_read2_b32 v[16:17], v8 offset0:33 offset1:41
	ds_read2_b32 v[18:19], v8 offset1:8
	ds_read2_b32 v[20:21], v8 offset0:66 offset1:74
	ds_read2_b32 v[22:23], v8 offset0:99 offset1:107
	ds_read2_b32 v[24:25], v8 offset0:132 offset1:140
	ds_read2_b32 v[26:27], v8 offset0:165 offset1:173
	ds_read2_b32 v[28:29], v8 offset0:198 offset1:206
	ds_read2_b32 v[30:31], v8 offset0:231 offset1:239
	s_add_u32 s4, s15, s4
	s_addc_u32 s5, s16, 0
	v_lshlrev_b32_e32 v0, 1, v6
	v_lshl_add_u64 v[12:13], s[4:5], 0, v[0:1]
	s_mov_b64 s[4:5], 0x4200000
	v_or_b32_e32 v0, s3, v7
	v_lshl_add_u64 v[32:33], v[12:13], 0, s[4:5]
	v_lshlrev_b32_e32 v0, 12, v0
	s_waitcnt lgkmcnt(6)
	v_cvt_pk_bf16_f32 v12, v18, v16
	s_waitcnt lgkmcnt(4)
	v_cvt_pk_bf16_f32 v13, v20, v22
	s_waitcnt lgkmcnt(2)
	v_cvt_pk_bf16_f32 v14, v24, v26
	s_waitcnt lgkmcnt(0)
	v_cvt_pk_bf16_f32 v15, v28, v30
	v_lshl_add_u64 v[34:35], v[32:33], 0, v[0:1]
	global_store_dwordx4 v[34:35], v[12:15], off sc1
	v_or_b32_e32 v0, s3, v9
	v_lshlrev_b32_e32 v0, 12, v0
	v_cvt_pk_bf16_f32 v12, v19, v17
	v_cvt_pk_bf16_f32 v13, v21, v23
	v_cvt_pk_bf16_f32 v14, v25, v27
	v_cvt_pk_bf16_f32 v15, v29, v31
	ds_read2_b32 v[18:19], v8 offset0:49 offset1:57
	ds_read2_b32 v[20:21], v8 offset0:16 offset1:24
	ds_read2_b32 v[22:23], v8 offset0:82 offset1:90
	ds_read2_b32 v[24:25], v8 offset0:115 offset1:123
	ds_read2_b32 v[26:27], v8 offset0:148 offset1:156
	ds_read2_b32 v[28:29], v8 offset0:181 offset1:189
	ds_read2_b32 v[30:31], v8 offset0:214 offset1:222
	ds_read2_b32 v[34:35], v8 offset0:247 offset1:255
	v_lshl_add_u64 v[16:17], v[32:33], 0, v[0:1]
	v_or_b32_e32 v0, s3, v10
	v_lshlrev_b32_e32 v0, 12, v0
	global_store_dwordx4 v[16:17], v[12:15], off sc1
	v_lshl_add_u64 v[16:17], v[32:33], 0, v[0:1]
	v_or_b32_e32 v0, s3, v11
	s_waitcnt lgkmcnt(6)
	v_cvt_pk_bf16_f32 v12, v20, v18
	s_waitcnt lgkmcnt(4)
	v_cvt_pk_bf16_f32 v13, v22, v24
	s_waitcnt lgkmcnt(2)
	v_cvt_pk_bf16_f32 v14, v26, v28
	s_waitcnt lgkmcnt(0)
	v_cvt_pk_bf16_f32 v15, v30, v34
	v_lshlrev_b32_e32 v0, 12, v0
	global_store_dwordx4 v[16:17], v[12:15], off sc1
	v_lshl_add_u64 v[16:17], v[32:33], 0, v[0:1]
	s_nop 0
	v_cvt_pk_bf16_f32 v12, v21, v19
	v_cvt_pk_bf16_f32 v13, v23, v25
	v_cvt_pk_bf16_f32 v14, v27, v29
	v_cvt_pk_bf16_f32 v15, v31, v35
	global_store_dwordx4 v[16:17], v[12:15], off sc1
	s_waitcnt lgkmcnt(0)

; __device__ __forceinline__ void transpose_item(const float* __restrict__ W, int ldw, int src_col0, bf16_t* WT, int K, int dst_row0, int k0, LAS float* scr, int lane) {
;     ...
;     for (int i = 0; i < 32; ++i) tmp[i] = __builtin_nontemporal_load(W + (size_t)(k0 + 2 * i + (lane >> 5)) * ldw + src_col0 + (lane & 31));
; __device__ __forceinline__ void convert_item(ArgsP a, const Ctx& c, int it, LAS float* scr) {
;     ...
;         if (r < 2 * I_D) { const int second = r >= I_D; if (second) r -= I_D; const int kb = r / 64, nb = r % 64;
;             transpose_item(a->in[second ? 15 : 12] + (size_t)l * FF * DM, DM, 32 * nb, (bf16_t*)(wl + (second ? WL_D2 : WL_D1)), FF, 32 * nb, 64 * kb, scr, c.lane); return; }
.LBB0_594:
	s_andn2_b64 vcc, exec, s[4:5]
	s_cbranch_vccnz .LBB0_596
	s_cmpk_gt_u32 s17, 0x6dff
	s_cselect_b64 s[4:5], -1, 0
	s_and_b64 s[4:5], s[4:5], exec
	s_cselect_b32 s4, s70, 0xffffa800
	s_cselect_b32 s6, 0x8e00000, s92
	s_cselect_b32 s3, s65, 0x60
	s_add_i32 s7, s4, s17
	s_and_b32 s60, s7, 0xffffffc0
	s_add_u32 s4, s0, s3
	s_addc_u32 s5, s1, 0
	s_load_dwordx2 s[4:5], s[4:5], 0x0
	s_mul_i32 s8, s2, 0x2c00000
	s_mul_hi_i32 s3, s2, 0x2c00000
	v_or_b32_e32 v12, s60, v3
	v_or_b32_e32 v18, 2, v12
	s_waitcnt lgkmcnt(0)
	s_add_u32 s8, s4, s8
	s_addc_u32 s9, s5, s3
	s_lshl_b32 s3, s7, 5
	s_and_b32 s3, s3, 0x7e0
	s_add_u32 s4, s15, s6
	s_addc_u32 s5, s16, 0
	s_lshl_b32 s6, s3, 2
	s_add_u32 s6, s8, s6
	v_or_b32_e32 v20, 4, v12
	v_or_b32_e32 v22, 6, v12
	v_or_b32_e32 v24, 8, v12
	v_or_b32_e32 v26, 10, v12
	v_or_b32_e32 v28, 12, v12
	v_or_b32_e32 v30, 14, v12
	s_addc_u32 s7, s9, 0
	v_lshlrev_b32_e32 v0, 2, v4
	v_ashrrev_i32_e32 v13, 31, v12
	v_ashrrev_i32_e32 v19, 31, v18
	v_ashrrev_i32_e32 v21, 31, v20
	v_ashrrev_i32_e32 v23, 31, v22
	v_ashrrev_i32_e32 v25, 31, v24
	v_ashrrev_i32_e32 v27, 31, v26
	v_ashrrev_i32_e32 v29, 31, v28
	v_ashrrev_i32_e32 v31, 31, v30
	v_lshl_add_u64 v[14:15], s[6:7], 0, v[0:1]
	v_lshlrev_b64 v[16:17], 13, v[12:13]
	v_lshlrev_b64 v[18:19], 13, v[18:19]
	v_lshlrev_b64 v[20:21], 13, v[20:21]
	v_lshlrev_b64 v[22:23], 13, v[22:23]
	v_lshlrev_b64 v[24:25], 13, v[24:25]
	v_lshlrev_b64 v[26:27], 13, v[26:27]
	v_lshlrev_b64 v[28:29], 13, v[28:29]
	v_lshlrev_b64 v[30:31], 13, v[30:31]
	v_lshl_add_u64 v[16:17], v[14:15], 0, v[16:17]
	v_lshl_add_u64 v[18:19], v[14:15], 0, v[18:19]
	v_lshl_add_u64 v[20:21], v[14:15], 0, v[20:21]
	v_lshl_add_u64 v[22:23], v[14:15], 0, v[22:23]
	v_lshl_add_u64 v[24:25], v[14:15], 0, v[24:25]
	v_lshl_add_u64 v[26:27], v[14:15], 0, v[26:27]
	v_lshl_add_u64 v[28:29], v[14:15], 0, v[28:29]
	v_lshl_add_u64 v[30:31], v[14:15], 0, v[30:31]
	global_load_dword v0, v[16:17], off nt
	global_load_dword v32, v[18:19], off nt
	global_load_dword v33, v[20:21], off nt
	global_load_dword v34, v[22:23], off nt
	global_load_dword v35, v[24:25], off nt
	global_load_dword v36, v[26:27], off nt
	global_load_dword v37, v[28:29], off nt
	global_load_dword v38, v[30:31], off nt
	v_or_b32_e32 v16, 16, v12
	v_or_b32_e32 v18, 18, v12
	v_or_b32_e32 v20, 20, v12
	v_or_b32_e32 v22, 22, v12
	v_or_b32_e32 v24, 24, v12
	v_or_b32_e32 v26, 26, v12
	v_or_b32_e32 v28, 28, v12
	v_or_b32_e32 v30, 30, v12
	v_ashrrev_i32_e32 v17, 31, v16
	v_ashrrev_i32_e32 v19, 31, v18
	v_ashrrev_i32_e32 v21, 31, v20
	v_ashrrev_i32_e32 v23, 31, v22
	v_ashrrev_i32_e32 v25, 31, v24
	v_ashrrev_i32_e32 v27, 31, v26
	v_ashrrev_i32_e32 v29, 31, v28
	v_ashrrev_i32_e32 v31, 31, v30
	v_lshlrev_b64 v[16:17], 13, v[16:17]
	v_lshlrev_b64 v[18:19], 13, v[18:19]
	v_lshlrev_b64 v[20:21], 13, v[20:21]
	v_lshlrev_b64 v[22:23], 13, v[22:23]
	v_lshlrev_b64 v[24:25], 13, v[24:25]
	v_lshlrev_b64 v[26:27], 13, v[26:27]
	v_lshlrev_b64 v[28:29], 13, v[28:29]
	v_lshlrev_b64 v[30:31], 13, v[30:31]
	v_lshl_add_u64 v[16:17], v[14:15], 0, v[16:17]
	v_lshl_add_u64 v[18:19], v[14:15], 0, v[18:19]
	v_lshl_add_u64 v[20:21], v[14:15], 0, v[20:21]
	v_lshl_add_u64 v[22:23], v[14:15], 0, v[22:23]
	v_lshl_add_u64 v[24:25], v[14:15], 0, v[24:25]
	v_lshl_add_u64 v[26:27], v[14:15], 0, v[26:27]
	v_lshl_add_u64 v[28:29], v[14:15], 0, v[28:29]
	v_lshl_add_u64 v[30:31], v[14:15], 0, v[30:31]
	global_load_dword v39, v[16:17], off nt
	global_load_dword v40, v[18:19], off nt
	global_load_dword v41, v[20:21], off nt
	global_load_dword v42, v[22:23], off nt
	global_load_dword v43, v[24:25], off nt
	global_load_dword v44, v[26:27], off nt
	global_load_dword v45, v[28:29], off nt
	global_load_dword v46, v[30:31], off nt
	v_or_b32_e32 v16, 32, v12
	v_or_b32_e32 v18, 34, v12
	v_or_b32_e32 v20, 36, v12
	v_or_b32_e32 v22, 38, v12
	v_or_b32_e32 v24, 40, v12
	v_or_b32_e32 v26, 42, v12
	v_or_b32_e32 v28, 44, v12
	v_or_b32_e32 v30, 46, v12
	v_ashrrev_i32_e32 v17, 31, v16
	v_ashrrev_i32_e32 v19, 31, v18
	v_ashrrev_i32_e32 v21, 31, v20
	v_ashrrev_i32_e32 v23, 31, v22
	v_ashrrev_i32_e32 v25, 31, v24
	v_ashrrev_i32_e32 v27, 31, v26
	v_ashrrev_i32_e32 v29, 31, v28
	v_ashrrev_i32_e32 v31, 31, v30
	v_lshlrev_b64 v[16:17], 13, v[16:17]
	v_lshlrev_b64 v[18:19], 13, v[18:19]
	v_lshlrev_b64 v[20:21], 13, v[20:21]
	v_lshlrev_b64 v[22:23], 13, v[22:23]
	v_lshlrev_b64 v[24:25], 13, v[24:25]
	v_lshlrev_b64 v[26:27], 13, v[26:27]
	v_lshlrev_b64 v[28:29], 13, v[28:29]
	v_lshlrev_b64 v[30:31], 13, v[30:31]
	v_lshl_add_u64 v[16:17], v[14:15], 0, v[16:17]
	v_lshl_add_u64 v[18:19], v[14:15], 0, v[18:19]
	v_lshl_add_u64 v[20:21], v[14:15], 0, v[20:21]
	v_lshl_add_u64 v[22:23], v[14:15], 0, v[22:23]
	v_lshl_add_u64 v[24:25], v[14:15], 0, v[24:25]
	v_lshl_add_u64 v[26:27], v[14:15], 0, v[26:27]
	v_lshl_add_u64 v[28:29], v[14:15], 0, v[28:29]
	v_lshl_add_u64 v[30:31], v[14:15], 0, v[30:31]
	global_load_dword v47, v[16:17], off nt
	global_load_dword v48, v[18:19], off nt
	global_load_dword v49, v[20:21], off nt
	global_load_dword v50, v[22:23], off nt
	global_load_dword v51, v[24:25], off nt
	global_load_dword v52, v[26:27], off nt
	global_load_dword v53, v[28:29], off nt
	s_nop 0
	global_load_dword v30, v[30:31], off nt
	v_or_b32_e32 v16, 48, v12
	v_or_b32_e32 v18, 50, v12
	v_or_b32_e32 v20, 52, v12
	v_or_b32_e32 v22, 54, v12
	v_or_b32_e32 v24, 56, v12
	v_or_b32_e32 v26, 58, v12
	v_or_b32_e32 v28, 60, v12
	v_or_b32_e32 v12, 62, v12
	v_ashrrev_i32_e32 v17, 31, v16
	v_ashrrev_i32_e32 v19, 31, v18
	v_ashrrev_i32_e32 v21, 31, v20
	v_ashrrev_i32_e32 v13, 31, v12
	v_lshlrev_b64 v[16:17], 13, v[16:17]
	v_lshlrev_b64 v[18:19], 13, v[18:19]
	v_lshlrev_b64 v[20:21], 13, v[20:21]
	v_ashrrev_i32_e32 v23, 31, v22
	v_ashrrev_i32_e32 v25, 31, v24
	v_ashrrev_i32_e32 v27, 31, v26
	v_ashrrev_i32_e32 v29, 31, v28
	v_lshlrev_b64 v[12:13], 13, v[12:13]
	v_lshl_add_u64 v[16:17], v[14:15], 0, v[16:17]
	v_lshl_add_u64 v[18:19], v[14:15], 0, v[18:19]
	v_lshl_add_u64 v[20:21], v[14:15], 0, v[20:21]
	v_lshlrev_b64 v[22:23], 13, v[22:23]
	v_lshlrev_b64 v[24:25], 13, v[24:25]
	v_lshlrev_b64 v[26:27], 13, v[26:27]
	v_lshlrev_b64 v[28:29], 13, v[28:29]
	v_lshl_add_u64 v[12:13], v[14:15], 0, v[12:13]
	v_lshl_add_u64 v[22:23], v[14:15], 0, v[22:23]
	v_lshl_add_u64 v[24:25], v[14:15], 0, v[24:25]
	v_lshl_add_u64 v[26:27], v[14:15], 0, v[26:27]
	v_lshl_add_u64 v[28:29], v[14:15], 0, v[28:29]
	global_load_dword v14, v[16:17], off nt
	global_load_dword v15, v[18:19], off nt
	s_nop 0
	global_load_dword v16, v[20:21], off nt
	global_load_dword v17, v[22:23], off nt
	global_load_dword v18, v[24:25], off nt
	global_load_dword v19, v[26:27], off nt
	s_nop 0
	global_load_dword v20, v[28:29], off nt
	s_nop 0
	global_load_dword v12, v[12:13], off nt
	s_waitcnt vmcnt(0)
; #define LAS __attribute__((address_space(3)))
; __device__ __forceinline__ unsigned pk_bf16(float lo, float hi) { f32x2 v = {lo, hi}; bf16x2_t b = __builtin_convertvector(v, bf16x2_t); return __builtin_bit_cast(unsigned, b); }
; #define LDS_WAIT() asm volatile("s_waitcnt lgkmcnt(0)" ::: "memory")
; __device__ __forceinline__ void transpose_item(const float* __restrict__ W, int ldw, int src_col0, bf16_t* WT, int K, int dst_row0, int k0, LAS float* scr, int lane) {
;     ...
; #pragma unroll
;     for (int i = 0; i < 32; ++i) scr[(2 * i + (lane >> 5)) * 33 + (lane & 31)] = tmp[i];
;     LDS_WAIT();
;     const int c = lane & 7;
; #pragma unroll
;     for (int j = 0; j < 4; ++j) { const int n = (lane >> 3) + 8 * j; const LAS float* s = scr + (8 * c) * 33 + n;
;         u32x4 o; o.x = pk_bf16(s[0 * 33], s[1 * 33]); o.y = pk_bf16(s[2 * 33], s[3 * 33]); o.z = pk_bf16(s[4 * 33], s[5 * 33]); o.w = pk_bf16(s[6 * 33], s[7 * 33]);
;         *(u32x4*)(WT + (size_t)(dst_row0 + n) * K + k0 + 8 * c) = o; }
; __device__ __forceinline__ void convert_item(ArgsP a, const Ctx& c, int it, LAS float* scr) {
;     ...
;         if (r < 2 * I_D) { const int second = r >= I_D; if (second) r -= I_D; const int kb = r / 64, nb = r % 64;
;             transpose_item(a->in[second ? 15 : 12] + (size_t)l * FF * DM, DM, 32 * nb, (bf16_t*)(wl + (second ? WL_D2 : WL_D1)), FF, 32 * nb, 64 * kb, scr, c.lane); return; }
	ds_write2_b32 v5, v0, v32 offset1:66
	ds_write2_b32 v5, v33, v34 offset0:132 offset1:198
	v_add_u32_e32 v0, 0x400, v5
	ds_write2_b32 v0, v35, v36 offset0:8 offset1:74
	ds_write2_b32 v0, v37, v38 offset0:140 offset1:206
	v_add_u32_e32 v0, 0x800, v5
	ds_write2_b32 v0, v39, v40 offset0:16 offset1:82
	ds_write2_b32 v0, v41, v42 offset0:148 offset1:214
	v_add_u32_e32 v0, 0xc00, v5
	ds_write2_b32 v0, v43, v44 offset0:24 offset1:90
	ds_write2_b32 v0, v45, v46 offset0:156 offset1:222
	v_add_u32_e32 v0, 0x1000, v5
	ds_write2_b32 v0, v47, v48 offset0:32 offset1:98
	ds_write2_b32 v0, v49, v50 offset0:164 offset1:230
	v_add_u32_e32 v0, 0x1400, v5
	ds_write2_b32 v0, v51, v52 offset0:40 offset1:106
	ds_write2_b32 v0, v53, v30 offset0:172 offset1:238
	v_add_u32_e32 v0, 0x1800, v5
	ds_write2_b32 v0, v14, v15 offset0:48 offset1:114
	ds_write2_b32 v0, v16, v17 offset0:180 offset1:246
	v_add_u32_e32 v0, 0x1c00, v5
	ds_write2_b32 v0, v18, v19 offset0:56 offset1:122
	ds_write2_b32 v0, v20, v12 offset0:188 offset1:254
	s_waitcnt lgkmcnt(0)
	s_lshl_b64 s[6:7], s[60:61], 1
	ds_read2_b32 v[16:17], v8 offset0:33 offset1:41
	ds_read2_b32 v[18:19], v8 offset1:8
	ds_read2_b32 v[20:21], v8 offset0:66 offset1:74
	ds_read2_b32 v[22:23], v8 offset0:99 offset1:107
	ds_read2_b32 v[24:25], v8 offset0:132 offset1:140
	ds_read2_b32 v[26:27], v8 offset0:165 offset1:173
	ds_read2_b32 v[28:29], v8 offset0:198 offset1:206
	ds_read2_b32 v[30:31], v8 offset0:231 offset1:239
	s_add_u32 s4, s4, s6
	s_addc_u32 s5, s5, s7
	v_lshlrev_b32_e32 v0, 1, v6
	v_lshl_add_u64 v[32:33], s[4:5], 0, v[0:1]
	v_or_b32_e32 v0, s3, v7
	v_mul_u32_u24_e32 v0, 0x2c00, v0
	s_waitcnt lgkmcnt(6)
	v_cvt_pk_bf16_f32 v12, v18, v16
	s_waitcnt lgkmcnt(4)
	v_cvt_pk_bf16_f32 v13, v20, v22
	s_waitcnt lgkmcnt(2)
	v_cvt_pk_bf16_f32 v14, v24, v26
	s_waitcnt lgkmcnt(0)
	v_cvt_pk_bf16_f32 v15, v28, v30
	v_lshl_add_u64 v[34:35], v[32:33], 0, v[0:1]
	global_store_dwordx4 v[34:35], v[12:15], off sc1
	v_or_b32_e32 v0, s3, v9
	v_mul_u32_u24_e32 v0, 0x2c00, v0
	v_cvt_pk_bf16_f32 v12, v19, v17
	v_cvt_pk_bf16_f32 v13, v21, v23
	v_cvt_pk_bf16_f32 v14, v25, v27
	v_cvt_pk_bf16_f32 v15, v29, v31
	ds_read2_b32 v[18:19], v8 offset0:16 offset1:24
	ds_read2_b32 v[20:21], v8 offset0:49 offset1:57
	ds_read2_b32 v[22:23], v8 offset0:82 offset1:90
	ds_read2_b32 v[24:25], v8 offset0:115 offset1:123
	ds_read2_b32 v[26:27], v8 offset0:148 offset1:156
	ds_read2_b32 v[28:29], v8 offset0:181 offset1:189
	ds_read2_b32 v[30:31], v8 offset0:214 offset1:222
	ds_read2_b32 v[34:35], v8 offset0:247 offset1:255
	v_lshl_add_u64 v[16:17], v[32:33], 0, v[0:1]
	v_or_b32_e32 v0, s3, v10
	v_mul_u32_u24_e32 v0, 0x2c00, v0
	global_store_dwordx4 v[16:17], v[12:15], off sc1
	v_lshl_add_u64 v[16:17], v[32:33], 0, v[0:1]
	v_or_b32_e32 v0, s3, v11
	s_waitcnt lgkmcnt(6)
	v_cvt_pk_bf16_f32 v12, v18, v20
	s_waitcnt lgkmcnt(4)
	v_cvt_pk_bf16_f32 v13, v22, v24
	s_waitcnt lgkmcnt(2)
	v_cvt_pk_bf16_f32 v14, v26, v28
	s_waitcnt lgkmcnt(0)
	v_cvt_pk_bf16_f32 v15, v30, v34
	v_mul_u32_u24_e32 v0, 0x2c00, v0
	global_store_dwordx4 v[16:17], v[12:15], off sc1
	v_lshl_add_u64 v[16:17], v[32:33], 0, v[0:1]
	s_nop 0
	v_cvt_pk_bf16_f32 v12, v19, v21
	v_cvt_pk_bf16_f32 v13, v23, v25
	v_cvt_pk_bf16_f32 v14, v27, v29
	v_cvt_pk_bf16_f32 v15, v31, v35
	global_store_dwordx4 v[16:17], v[12:15], off sc1
	s_waitcnt lgkmcnt(0)

; __device__ __forceinline__ void transpose_item(const float* __restrict__ W, int ldw, int src_col0, bf16_t* WT, int K, int dst_row0, int k0, LAS float* scr, int lane) {
;     ...
;     for (int i = 0; i < 32; ++i) tmp[i] = __builtin_nontemporal_load(W + (size_t)(k0 + 2 * i + (lane >> 5)) * ldw + src_col0 + (lane & 31));
; __device__ __forceinline__ void convert_item(ArgsP a, const Ctx& c, int it, LAS float* scr) {
;     ...
;         if (r < 2 * I_GU) {
;             const int second = r >= I_GU; if (second) r -= I_GU;
;             const int kb = r / 352, gidx = r % 352, pn = gidx >> 3, w = gidx & 7;
;             const float* src = a->in[(second ? 13 : 10) + (w >> 2)] + (size_t)l * DM * FF;
;             transpose_item(src, FF, 128 * pn + 32 * (w & 3), (bf16_t*)(wl + (second ? WL_GU2 : WL_GU1)), DM, 32 * gidx, 64 * kb, scr, c.lane); return; }
.LBB0_597:
	s_add_i32 s3, s17, 0xffffd400
	s_cmpk_gt_i32 s17, 0x2bff
	s_cselect_b32 s3, s3, s17
	s_mul_hi_i32 s5, s3, 0x2e8ba2e9
	s_cselect_b32 s7, 0x6200000, 0
	s_cselect_b32 s4, 13, 10
	s_lshr_b32 s6, s5, 31
	s_ashr_i32 s5, s5, 6
	s_add_i32 s8, s5, s6
	s_mul_i32 s5, s8, 0x160
	s_sub_i32 s3, s3, s5
	s_bfe_u32 s5, s3, 0x10002
	s_add_i32 s5, s5, s4
	s_lshl_b32 s4, s5, 3
	s_load_dwordx2 s[4:5], s[0:1], s4 offset:0x0
	s_mul_hi_i32 s6, s2, 0x2c00000
	s_mul_i32 s2, s2, 0x2c00000
	v_lshlrev_b32_e32 v0, 2, v4
	s_waitcnt lgkmcnt(0)
	s_add_u32 s9, s4, s2
	s_addc_u32 s5, s5, s6
	s_lshl_b32 s2, s3, 4
	s_lshl_b32 s4, s3, 5
	s_and_b32 s2, s2, 0xffffff80
	s_and_b32 s3, s4, 0x60
	s_or_b32 s6, s2, s3
	s_add_u32 s10, s15, s7
	s_addc_u32 s11, s16, 0
	s_ashr_i32 s7, s6, 31
	s_lshl_b32 s2, s8, 6
	s_lshl_b64 s[6:7], s[6:7], 2
	s_add_u32 s6, s9, s6
	v_or_b32_e32 v30, s2, v3
	s_addc_u32 s7, s5, s7
	v_lshl_add_u64 v[12:13], s[6:7], 0, v[0:1]
	v_or_b32_e32 v0, 2, v30
	v_mad_i64_i32 v[16:17], s[6:7], v0, s46, v[12:13]
	v_or_b32_e32 v0, 4, v30
	v_mad_i64_i32 v[18:19], s[6:7], v0, s46, v[12:13]
	v_or_b32_e32 v0, 6, v30
	v_mad_i64_i32 v[20:21], s[6:7], v0, s46, v[12:13]
	v_or_b32_e32 v0, 8, v30
	v_mad_i64_i32 v[22:23], s[6:7], v0, s46, v[12:13]
	v_or_b32_e32 v0, 10, v30
	v_mad_i64_i32 v[24:25], s[6:7], v0, s46, v[12:13]
	v_or_b32_e32 v0, 12, v30
	v_mad_i64_i32 v[26:27], s[6:7], v0, s46, v[12:13]
	v_or_b32_e32 v0, 14, v30
	v_mad_i64_i32 v[14:15], s[6:7], v30, s46, v[12:13]
	v_mad_i64_i32 v[28:29], s[6:7], v0, s46, v[12:13]
	global_load_dword v0, v[14:15], off nt
	global_load_dword v31, v[16:17], off nt
	global_load_dword v32, v[18:19], off nt
	global_load_dword v33, v[20:21], off nt
	global_load_dword v34, v[22:23], off nt
	global_load_dword v35, v[24:25], off nt
	global_load_dword v36, v[26:27], off nt
	global_load_dword v37, v[28:29], off nt
	v_or_b32_e32 v14, 16, v30
	v_or_b32_e32 v16, 18, v30
	v_or_b32_e32 v18, 20, v30
	v_or_b32_e32 v20, 22, v30
	v_or_b32_e32 v22, 24, v30
	v_or_b32_e32 v24, 26, v30
	v_or_b32_e32 v26, 28, v30
	v_or_b32_e32 v28, 30, v30
	v_mad_i64_i32 v[14:15], s[6:7], v14, s46, v[12:13]
	v_mad_i64_i32 v[16:17], s[6:7], v16, s46, v[12:13]
	v_mad_i64_i32 v[18:19], s[6:7], v18, s46, v[12:13]
	v_mad_i64_i32 v[20:21], s[6:7], v20, s46, v[12:13]
	v_mad_i64_i32 v[22:23], s[6:7], v22, s46, v[12:13]
	v_mad_i64_i32 v[24:25], s[6:7], v24, s46, v[12:13]
	v_mad_i64_i32 v[26:27], s[6:7], v26, s46, v[12:13]
	v_mad_i64_i32 v[28:29], s[6:7], v28, s46, v[12:13]
	global_load_dword v38, v[14:15], off nt
	global_load_dword v39, v[16:17], off nt
	global_load_dword v40, v[18:19], off nt
	global_load_dword v41, v[20:21], off nt
	global_load_dword v42, v[22:23], off nt
	global_load_dword v43, v[24:25], off nt
	global_load_dword v44, v[26:27], off nt
	global_load_dword v45, v[28:29], off nt
	v_or_b32_e32 v14, 32, v30
	v_or_b32_e32 v16, 34, v30
	v_or_b32_e32 v18, 36, v30
	v_or_b32_e32 v20, 38, v30
	v_or_b32_e32 v22, 40, v30
	v_or_b32_e32 v24, 42, v30
	v_or_b32_e32 v26, 44, v30
	v_or_b32_e32 v28, 46, v30
	v_mad_i64_i32 v[14:15], s[6:7], v14, s46, v[12:13]
	v_mad_i64_i32 v[16:17], s[6:7], v16, s46, v[12:13]
	v_mad_i64_i32 v[18:19], s[6:7], v18, s46, v[12:13]
	v_mad_i64_i32 v[20:21], s[6:7], v20, s46, v[12:13]
	v_mad_i64_i32 v[22:23], s[6:7], v22, s46, v[12:13]
	v_mad_i64_i32 v[24:25], s[6:7], v24, s46, v[12:13]
	v_mad_i64_i32 v[26:27], s[6:7], v26, s46, v[12:13]
	v_mad_i64_i32 v[28:29], s[6:7], v28, s46, v[12:13]
	global_load_dword v46, v[14:15], off nt
	global_load_dword v47, v[16:17], off nt
	global_load_dword v48, v[18:19], off nt
	global_load_dword v49, v[20:21], off nt
	global_load_dword v50, v[22:23], off nt
	global_load_dword v51, v[24:25], off nt
	global_load_dword v52, v[26:27], off nt
	s_nop 0
	global_load_dword v28, v[28:29], off nt
	v_or_b32_e32 v14, 48, v30
	v_or_b32_e32 v16, 50, v30
	v_or_b32_e32 v18, 52, v30
	v_or_b32_e32 v20, 54, v30
	v_or_b32_e32 v22, 56, v30
	v_or_b32_e32 v24, 58, v30
	v_or_b32_e32 v26, 60, v30
	v_or_b32_e32 v29, 62, v30
	v_mad_i64_i32 v[14:15], s[6:7], v14, s46, v[12:13]
	v_mad_i64_i32 v[16:17], s[6:7], v16, s46, v[12:13]
	v_mad_i64_i32 v[18:19], s[6:7], v18, s46, v[12:13]
	v_mad_i64_i32 v[20:21], s[6:7], v20, s46, v[12:13]
	v_mad_i64_i32 v[22:23], s[6:7], v22, s46, v[12:13]
	v_mad_i64_i32 v[24:25], s[6:7], v24, s46, v[12:13]
	v_mad_i64_i32 v[26:27], s[6:7], v26, s46, v[12:13]
	v_mad_i64_i32 v[12:13], s[6:7], v29, s46, v[12:13]
	global_load_dword v14, v[14:15], off nt
	s_nop 0
	global_load_dword v15, v[16:17], off nt
	s_nop 0
	global_load_dword v16, v[18:19], off nt
	global_load_dword v17, v[20:21], off nt
	s_nop 0
	global_load_dword v18, v[22:23], off nt
	global_load_dword v19, v[24:25], off nt
	global_load_dword v20, v[26:27], off nt
	s_nop 0
	global_load_dword v12, v[12:13], off nt
	s_waitcnt vmcnt(0)
; #define LAS __attribute__((address_space(3)))
; __device__ __forceinline__ unsigned pk_bf16(float lo, float hi) { f32x2 v = {lo, hi}; bf16x2_t b = __builtin_convertvector(v, bf16x2_t); return __builtin_bit_cast(unsigned, b); }
; #define LDS_WAIT() asm volatile("s_waitcnt lgkmcnt(0)" ::: "memory")
; __device__ __forceinline__ void transpose_item(const float* __restrict__ W, int ldw, int src_col0, bf16_t* WT, int K, int dst_row0, int k0, LAS float* scr, int lane) {
;     ...
; #pragma unroll
;     for (int i = 0; i < 32; ++i) scr[(2 * i + (lane >> 5)) * 33 + (lane & 31)] = tmp[i];
;     LDS_WAIT();
;     const int c = lane & 7;
; #pragma unroll
;     for (int j = 0; j < 4; ++j) { const int n = (lane >> 3) + 8 * j; const LAS float* s = scr + (8 * c) * 33 + n;
;         u32x4 o; o.x = pk_bf16(s[0 * 33], s[1 * 33]); o.y = pk_bf16(s[2 * 33], s[3 * 33]); o.z = pk_bf16(s[4 * 33], s[5 * 33]); o.w = pk_bf16(s[6 * 33], s[7 * 33]);
;         *(u32x4*)(WT + (size_t)(dst_row0 + n) * K + k0 + 8 * c) = o; }
; __device__ __forceinline__ void prologue(ArgsP a, const Ctx& c) {
;     ...
;     for (int j = c.gw; j < N_PRO; j += c.NGW) {
;         const int it = j < PER_LAYER ? j : (j < PER_LAYER + N_MID ? PER_LAYER + DEFER_LO + (j - PER_LAYER) : PER_LAYER + DEFER_PG1 + (j - PER_LAYER - N_MID));
;         convert_item(a, c, it, scr);
	ds_write2_b32 v5, v0, v31 offset1:66
	ds_write2_b32 v5, v32, v33 offset0:132 offset1:198
	v_add_u32_e32 v0, 0x400, v5
	ds_write2_b32 v0, v34, v35 offset0:8 offset1:74
	ds_write2_b32 v0, v36, v37 offset0:140 offset1:206
	v_add_u32_e32 v0, 0x800, v5
	ds_write2_b32 v0, v38, v39 offset0:16 offset1:82
	ds_write2_b32 v0, v40, v41 offset0:148 offset1:214
	v_add_u32_e32 v0, 0xc00, v5
	ds_write2_b32 v0, v42, v43 offset0:24 offset1:90
	ds_write2_b32 v0, v44, v45 offset0:156 offset1:222
	v_add_u32_e32 v0, 0x1000, v5
	ds_write2_b32 v0, v46, v47 offset0:32 offset1:98
	ds_write2_b32 v0, v48, v49 offset0:164 offset1:230
	v_add_u32_e32 v0, 0x1400, v5
	ds_write2_b32 v0, v50, v51 offset0:40 offset1:106
	ds_write2_b32 v0, v52, v28 offset0:172 offset1:238
	v_add_u32_e32 v0, 0x1800, v5
	ds_write2_b32 v0, v14, v15 offset0:48 offset1:114
	ds_write2_b32 v0, v16, v17 offset0:180 offset1:246
	v_add_u32_e32 v0, 0x1c00, v5
	ds_write2_b32 v0, v18, v19 offset0:56 offset1:122
	ds_write2_b32 v0, v20, v12 offset0:188 offset1:254
	s_waitcnt lgkmcnt(0)
	s_ashr_i32 s3, s2, 31
	ds_read2_b32 v[16:17], v8 offset0:33 offset1:41
	ds_read2_b32 v[18:19], v8 offset1:8
	ds_read2_b32 v[20:21], v8 offset0:66 offset1:74
	ds_read2_b32 v[22:23], v8 offset0:99 offset1:107
	ds_read2_b32 v[24:25], v8 offset0:132 offset1:140
	ds_read2_b32 v[26:27], v8 offset0:165 offset1:173
	ds_read2_b32 v[28:29], v8 offset0:198 offset1:206
	ds_read2_b32 v[30:31], v8 offset0:231 offset1:239
	s_lshl_b64 s[2:3], s[2:3], 1
	s_add_u32 s2, s10, s2
	v_or_b32_e32 v34, s4, v7
	s_addc_u32 s3, s11, s3
	v_lshlrev_b32_e32 v0, 1, v6
	v_ashrrev_i32_e32 v35, 31, v34
	v_lshl_add_u64 v[32:33], s[2:3], 0, v[0:1]
	v_lshlrev_b64 v[34:35], 12, v[34:35]
	s_waitcnt lgkmcnt(6)
	v_cvt_pk_bf16_f32 v12, v18, v16
	s_waitcnt lgkmcnt(4)
	v_cvt_pk_bf16_f32 v13, v20, v22
	s_waitcnt lgkmcnt(2)
	v_cvt_pk_bf16_f32 v14, v24, v26
	s_waitcnt lgkmcnt(0)
	v_cvt_pk_bf16_f32 v15, v28, v30
	v_lshl_add_u64 v[34:35], v[32:33], 0, v[34:35]
	v_or_b32_e32 v16, s4, v9
	global_store_dwordx4 v[34:35], v[12:15], off sc1
	s_nop 1
	v_cvt_pk_bf16_f32 v12, v19, v17
	v_ashrrev_i32_e32 v17, 31, v16
	v_cvt_pk_bf16_f32 v13, v21, v23
	v_cvt_pk_bf16_f32 v14, v25, v27
	v_cvt_pk_bf16_f32 v15, v29, v31
	v_lshlrev_b64 v[16:17], 12, v[16:17]
	ds_read2_b32 v[18:19], v8 offset0:49 offset1:57
	ds_read2_b32 v[20:21], v8 offset0:16 offset1:24
	ds_read2_b32 v[22:23], v8 offset0:82 offset1:90
	ds_read2_b32 v[24:25], v8 offset0:115 offset1:123
	ds_read2_b32 v[26:27], v8 offset0:148 offset1:156
	ds_read2_b32 v[28:29], v8 offset0:181 offset1:189
	ds_read2_b32 v[30:31], v8 offset0:214 offset1:222
	ds_read2_b32 v[34:35], v8 offset0:247 offset1:255
	v_lshl_add_u64 v[16:17], v[32:33], 0, v[16:17]
	global_store_dwordx4 v[16:17], v[12:15], off sc1
	v_or_b32_e32 v16, s4, v10
	v_ashrrev_i32_e32 v17, 31, v16
	v_lshlrev_b64 v[16:17], 12, v[16:17]
	s_waitcnt lgkmcnt(6)
	v_cvt_pk_bf16_f32 v12, v20, v18
	s_waitcnt lgkmcnt(4)
	v_cvt_pk_bf16_f32 v13, v22, v24
	s_waitcnt lgkmcnt(2)
	v_cvt_pk_bf16_f32 v14, v26, v28
	s_waitcnt lgkmcnt(0)
	v_cvt_pk_bf16_f32 v15, v30, v34
	v_lshl_add_u64 v[16:17], v[32:33], 0, v[16:17]
	global_store_dwordx4 v[16:17], v[12:15], off sc1
	v_or_b32_e32 v16, s4, v11
	v_ashrrev_i32_e32 v17, 31, v16
	v_lshlrev_b64 v[16:17], 12, v[16:17]
	v_cvt_pk_bf16_f32 v12, v21, v19
	v_cvt_pk_bf16_f32 v13, v23, v25
	v_cvt_pk_bf16_f32 v14, v27, v29
	v_cvt_pk_bf16_f32 v15, v31, v35
	v_lshl_add_u64 v[16:17], v[32:33], 0, v[16:17]
	global_store_dwordx4 v[16:17], v[12:15], off sc1
	s_waitcnt lgkmcnt(0)
	s_branch .LBB0_542
